# weight conversion routine: dwordx4 row loads, 5 tiles in flight
# baseline (speedup 1.0000x reference)
.LBB0_149:
	v_readlane_b32 s100, v242, 0
	s_movk_i32 s67, 0x80
	s_movk_i32 s66, 0x280
	s_sub_u32 s100, s100, 0x180
	s_waitcnt vmcnt(0) lgkmcnt(0)
	s_barrier
	v_readlane_b32 s0, v242, 42
	v_readlane_b32 s1, v242, 43
	v_readlane_b32 s4, v242, 3
	v_readlane_b32 s5, v242, 4
	v_lshrrev_b32_e32 v225, 4, v137
	v_and_b32_e32 v226, 15, v137
	v_lshlrev_b32_e32 v226, 2, v226
	s_sub_u32 s0, s0, 0x118
	s_subb_u32 s1, s1, 0
	v_lshrrev_b32_e32 v227, 3, v137
	v_and_b32_e32 v228, 7, v137
	v_mul_u32_u24_e32 v218, 65, v225
	v_mul_u32_u24_e32 v219, 0x208, v228
	v_add_u32_e32 v218, v218, v226
	v_add_u32_e32 v219, v219, v227
	v_lshlrev_b32_e32 v218, 2, v218
	v_lshlrev_b32_e32 v219, 2, v219
	v_lshlrev_b32_e32 v226, 2, v226
	v_lshlrev_b32_e32 v228, 4, v228
	v_add_u32_e32 v220, 0x400, v219
	v_add_u32_e32 v221, 0x80, v219
	v_add_u32_e32 v222, 0x480, v219
	s_cmp_ge_u32 s100, s66
	s_cbranch_scc1 .Lwc0_done
	s_cmpk_ge_u32 s100, 0x900
	s_cbranch_scc1 .Lwc0_t3_1
	s_cmpk_ge_u32 s100, 0x380
	s_cbranch_scc1 .Lwc0_t2_1
	s_cmpk_ge_u32 s100, 0x280
	s_cbranch_scc1 .Lwc0_t1_1
	s_movk_i32 s41, 0x78
	s_sub_u32 s99, s100, 0
	s_mul_i32 s44, s99, 0x66667
	s_lshr_b32 s44, s44, 24
	s_mul_i32 s36, s44, 40
	s_sub_u32 s99, s99, s36
	s_mul_i32 s38, s44, 0xa0000
	s_lshl_b32 s36, s99, 8
	s_add_u32 s38, s38, s36
	s_add_u32 s38, s38, 0x0
	s_lshl_b32 s36, s99, 6
	s_mov_b32 s32, 0x10000
	s_mul_i32 s36, s36, 0x800
	s_lshl_b32 s44, s44, 7
	s_add_u32 s36, s36, s44
	s_add_u32 s36, s36, 0x0
	s_mov_b32 s37, 0x28000
	s_movk_i32 s44, 0x800
	s_mov_b32 s99, 0x2800
	s_branch .Lwc0_tj_1
.Lwc0_t1_1:
	s_movk_i32 s41, 0x80
	s_sub_u32 s99, s100, 640
	s_mul_i32 s44, s99, 0x100000
	s_lshr_b32 s44, s44, 24
	s_mul_i32 s36, s44, 16
	s_sub_u32 s99, s99, s36
	s_mul_i32 s38, s44, 0x40000
	s_lshl_b32 s36, s99, 8
	s_add_u32 s38, s38, s36
	s_add_u32 s38, s38, 0x0
	s_lshl_b32 s36, s99, 6
	s_mov_b32 s32, 0x10000
	s_mul_i32 s36, s36, 0x800
	s_lshl_b32 s44, s44, 7
	s_add_u32 s36, s36, s44
	s_add_u32 s36, s36, 0xa00000
	s_mov_b32 s37, 0x10000
	s_movk_i32 s44, 0x800
	s_mov_b32 s99, 0x1000
	s_branch .Lwc0_tj_1
.Lwc0_t2_1:
	s_movk_i32 s41, 0xf0
	s_sub_u32 s99, s100, 896
	s_mul_i32 s44, s99, 0x2e8bb
	s_lshr_b32 s44, s44, 24
	s_mul_i32 s36, s44, 88
	s_sub_u32 s99, s99, s36
	s_mul_i32 s38, s44, 0x160000
	s_lshl_b32 s36, s99, 8
	s_add_u32 s38, s38, s36
	s_add_u32 s38, s38, 0x0
	s_cmpk_ge_u32 s99, 44
	s_cselect_b32 s36, 44, 0
	s_cselect_b32 s37, 32, 0
	s_sub_u32 s36, s99, s36
	s_lshl_b32 s36, s36, 7
	s_add_u32 s36, s36, s37
	s_mov_b32 s32, 0x20000
	s_mul_i32 s36, s36, 0x800
	s_lshl_b32 s44, s44, 7
	s_add_u32 s36, s36, s44
	s_add_u32 s36, s36, 0xe00000
	s_mov_b32 s37, 0x58000
	s_movk_i32 s44, 0x800
	s_mov_b32 s99, 0x5800
	s_branch .Lwc0_tj_1
.Lwc0_t3_1:
	s_movk_i32 s41, 0xf8
	s_sub_u32 s99, s100, 2304
	s_mul_i32 s44, s99, 0x100000
	s_lshr_b32 s44, s44, 24
	s_mul_i32 s36, s44, 16
	s_sub_u32 s99, s99, s36
	s_mul_i32 s38, s44, 0x40000
	s_lshl_b32 s36, s99, 8
	s_add_u32 s38, s38, s36
	s_add_u32 s38, s38, 0x0
	s_lshl_b32 s36, s99, 6
	s_mov_b32 s32, 0x2c000
	s_mul_i32 s36, s36, 0x1600
	s_lshl_b32 s44, s44, 7
	s_add_u32 s36, s36, s44
	s_add_u32 s36, s36, 0x2400000
	s_mov_b32 s37, 0x10000
	s_movk_i32 s44, 0x1600
	s_mov_b32 s99, 0x1000
.Lwc0_tj_1:
	s_load_dwordx2 s[2:3], s[0:1], s41
	s_add_u32 s52, s4, s36
	s_addc_u32 s53, s5, 0
	v_mad_u32_u24 v223, v225, s99, v226
	v_writelane_b32 v229, s52, 8
	v_writelane_b32 v229, s53, 9
	v_writelane_b32 v229, s32, 10
	v_writelane_b32 v229, s44, 11
	s_add_u32 s100, s100, s67
	s_waitcnt lgkmcnt(0)
	s_add_u32 s38, s2, s38
	s_addc_u32 s39, s3, 0
	global_load_dwordx4 v[138:141], v223, s[38:39]
	s_add_u32 s38, s38, s37
	s_addc_u32 s39, s39, 0
	global_load_dwordx4 v[142:145], v223, s[38:39]
	s_add_u32 s38, s38, s37
	s_addc_u32 s39, s39, 0
	global_load_dwordx4 v[146:149], v223, s[38:39]
	s_add_u32 s38, s38, s37
	s_addc_u32 s39, s39, 0
	global_load_dwordx4 v[150:153], v223, s[38:39]
	s_cmp_ge_u32 s100, s66
	s_cbranch_scc1 .Lwc0_p1
	s_cmpk_ge_u32 s100, 0x900
	s_cbranch_scc1 .Lwc0_t3_2
	s_cmpk_ge_u32 s100, 0x380
	s_cbranch_scc1 .Lwc0_t2_2
	s_cmpk_ge_u32 s100, 0x280
	s_cbranch_scc1 .Lwc0_t1_2
	s_movk_i32 s41, 0x78
	s_sub_u32 s99, s100, 0
	s_mul_i32 s44, s99, 0x66667
	s_lshr_b32 s44, s44, 24
	s_mul_i32 s36, s44, 40
	s_sub_u32 s99, s99, s36
	s_mul_i32 s38, s44, 0xa0000
	s_lshl_b32 s36, s99, 8
	s_add_u32 s38, s38, s36
	s_add_u32 s38, s38, 0x0
	s_lshl_b32 s36, s99, 6
	s_mov_b32 s32, 0x10000
	s_mul_i32 s36, s36, 0x800
	s_lshl_b32 s44, s44, 7
	s_add_u32 s36, s36, s44
	s_add_u32 s36, s36, 0x0
	s_mov_b32 s37, 0x28000
	s_movk_i32 s44, 0x800
	s_mov_b32 s99, 0x2800
	s_branch .Lwc0_tj_2

.Lwc0_tj_2:
	s_load_dwordx2 s[2:3], s[0:1], s41
	s_add_u32 s52, s4, s36
	s_addc_u32 s53, s5, 0
	v_mad_u32_u24 v223, v225, s99, v226
	v_writelane_b32 v229, s52, 12
	v_writelane_b32 v229, s53, 13
	v_writelane_b32 v229, s32, 14
	v_writelane_b32 v229, s44, 15
	s_add_u32 s100, s100, s67
	s_waitcnt lgkmcnt(0)
	s_add_u32 s38, s2, s38
	s_addc_u32 s39, s3, 0
	global_load_dwordx4 v[154:157], v223, s[38:39]
	s_add_u32 s38, s38, s37
	s_addc_u32 s39, s39, 0
	global_load_dwordx4 v[158:161], v223, s[38:39]
	s_add_u32 s38, s38, s37
	s_addc_u32 s39, s39, 0
	global_load_dwordx4 v[162:165], v223, s[38:39]
	s_add_u32 s38, s38, s37
	s_addc_u32 s39, s39, 0
	global_load_dwordx4 v[166:169], v223, s[38:39]
	s_cmp_ge_u32 s100, s66
	s_cbranch_scc1 .Lwc0_p2
	s_cmpk_ge_u32 s100, 0x900
	s_cbranch_scc1 .Lwc0_t3_3
	s_cmpk_ge_u32 s100, 0x380
	s_cbranch_scc1 .Lwc0_t2_3
	s_cmpk_ge_u32 s100, 0x280
	s_cbranch_scc1 .Lwc0_t1_3
	s_movk_i32 s41, 0x78
	s_sub_u32 s99, s100, 0
	s_mul_i32 s44, s99, 0x66667
	s_lshr_b32 s44, s44, 24
	s_mul_i32 s36, s44, 40
	s_sub_u32 s99, s99, s36
	s_mul_i32 s38, s44, 0xa0000
	s_lshl_b32 s36, s99, 8
	s_add_u32 s38, s38, s36
	s_add_u32 s38, s38, 0x0
	s_lshl_b32 s36, s99, 6
	s_mov_b32 s32, 0x10000
	s_mul_i32 s36, s36, 0x800
	s_lshl_b32 s44, s44, 7
	s_add_u32 s36, s36, s44
	s_add_u32 s36, s36, 0x0
	s_mov_b32 s37, 0x28000
	s_movk_i32 s44, 0x800
	s_mov_b32 s99, 0x2800
	s_branch .Lwc0_tj_3

.Lwc0_tj_3:
	s_load_dwordx2 s[2:3], s[0:1], s41
	s_add_u32 s52, s4, s36
	s_addc_u32 s53, s5, 0
	v_mad_u32_u24 v223, v225, s99, v226
	v_writelane_b32 v229, s52, 16
	v_writelane_b32 v229, s53, 17
	v_writelane_b32 v229, s32, 18
	v_writelane_b32 v229, s44, 19
	s_add_u32 s100, s100, s67
	s_waitcnt lgkmcnt(0)
	s_add_u32 s38, s2, s38
	s_addc_u32 s39, s3, 0
	global_load_dwordx4 v[170:173], v223, s[38:39]
	s_add_u32 s38, s38, s37
	s_addc_u32 s39, s39, 0
	global_load_dwordx4 v[174:177], v223, s[38:39]
	s_add_u32 s38, s38, s37
	s_addc_u32 s39, s39, 0
	global_load_dwordx4 v[178:181], v223, s[38:39]
	s_add_u32 s38, s38, s37
	s_addc_u32 s39, s39, 0
	global_load_dwordx4 v[182:185], v223, s[38:39]
	s_cmp_ge_u32 s100, s66
	s_cbranch_scc1 .Lwc0_p3
	s_cmpk_ge_u32 s100, 0x900
	s_cbranch_scc1 .Lwc0_t3_4
	s_cmpk_ge_u32 s100, 0x380
	s_cbranch_scc1 .Lwc0_t2_4
	s_cmpk_ge_u32 s100, 0x280
	s_cbranch_scc1 .Lwc0_t1_4
	s_movk_i32 s41, 0x78
	s_sub_u32 s99, s100, 0
	s_mul_i32 s44, s99, 0x66667
	s_lshr_b32 s44, s44, 24
	s_mul_i32 s36, s44, 40
	s_sub_u32 s99, s99, s36
	s_mul_i32 s38, s44, 0xa0000
	s_lshl_b32 s36, s99, 8
	s_add_u32 s38, s38, s36
	s_add_u32 s38, s38, 0x0
	s_lshl_b32 s36, s99, 6
	s_mov_b32 s32, 0x10000
	s_mul_i32 s36, s36, 0x800
	s_lshl_b32 s44, s44, 7
	s_add_u32 s36, s36, s44
	s_add_u32 s36, s36, 0x0
	s_mov_b32 s37, 0x28000
	s_movk_i32 s44, 0x800
	s_mov_b32 s99, 0x2800
	s_branch .Lwc0_tj_4

.Lwc0_tj_4:
	s_load_dwordx2 s[2:3], s[0:1], s41
	s_add_u32 s52, s4, s36
	s_addc_u32 s53, s5, 0
	v_mad_u32_u24 v223, v225, s99, v226
	v_writelane_b32 v229, s52, 20
	v_writelane_b32 v229, s53, 21
	v_writelane_b32 v229, s32, 22
	v_writelane_b32 v229, s44, 23
	s_add_u32 s100, s100, s67
	s_waitcnt lgkmcnt(0)
	s_add_u32 s38, s2, s38
	s_addc_u32 s39, s3, 0
	global_load_dwordx4 v[186:189], v223, s[38:39]
	s_add_u32 s38, s38, s37
	s_addc_u32 s39, s39, 0
	global_load_dwordx4 v[190:193], v223, s[38:39]
	s_add_u32 s38, s38, s37
	s_addc_u32 s39, s39, 0
	global_load_dwordx4 v[194:197], v223, s[38:39]
	s_add_u32 s38, s38, s37
	s_addc_u32 s39, s39, 0
	global_load_dwordx4 v[198:201], v223, s[38:39]
	s_cmp_ge_u32 s100, s66
	s_cbranch_scc1 .Lwc0_p4
	s_cmpk_ge_u32 s100, 0x900
	s_cbranch_scc1 .Lwc0_t3_5
	s_cmpk_ge_u32 s100, 0x380
	s_cbranch_scc1 .Lwc0_t2_5
	s_cmpk_ge_u32 s100, 0x280
	s_cbranch_scc1 .Lwc0_t1_5
	s_movk_i32 s41, 0x78
	s_sub_u32 s99, s100, 0
	s_mul_i32 s44, s99, 0x66667
	s_lshr_b32 s44, s44, 24
	s_mul_i32 s36, s44, 40
	s_sub_u32 s99, s99, s36
	s_mul_i32 s38, s44, 0xa0000
	s_lshl_b32 s36, s99, 8
	s_add_u32 s38, s38, s36
	s_add_u32 s38, s38, 0x0
	s_lshl_b32 s36, s99, 6
	s_mov_b32 s32, 0x10000
	s_mul_i32 s36, s36, 0x800
	s_lshl_b32 s44, s44, 7
	s_add_u32 s36, s36, s44
	s_add_u32 s36, s36, 0x0
	s_mov_b32 s37, 0x28000
	s_movk_i32 s44, 0x800
	s_mov_b32 s99, 0x2800
	s_branch .Lwc0_tj_5

.Lwc0_tj_5:
	s_load_dwordx2 s[2:3], s[0:1], s41
	s_add_u32 s52, s4, s36
	s_addc_u32 s53, s5, 0
	v_mad_u32_u24 v223, v225, s99, v226
	v_writelane_b32 v229, s52, 24
	v_writelane_b32 v229, s53, 25
	v_writelane_b32 v229, s32, 26
	v_writelane_b32 v229, s44, 27
	s_add_u32 s100, s100, s67
	s_waitcnt lgkmcnt(0)
	s_add_u32 s38, s2, s38
	s_addc_u32 s39, s3, 0
	global_load_dwordx4 v[202:205], v223, s[38:39]
	s_add_u32 s38, s38, s37
	s_addc_u32 s39, s39, 0
	global_load_dwordx4 v[206:209], v223, s[38:39]
	s_add_u32 s38, s38, s37
	s_addc_u32 s39, s39, 0
	global_load_dwordx4 v[210:213], v223, s[38:39]
	s_add_u32 s38, s38, s37
	s_addc_u32 s39, s39, 0
	global_load_dwordx4 v[214:217], v223, s[38:39]
.Lwc0_loop:
	s_waitcnt vmcnt(16)
	v_readlane_b32 s52, v229, 8
	v_readlane_b32 s53, v229, 9
	v_readlane_b32 s32, v229, 10
	v_readlane_b32 s35, v229, 11
	ds_write_b32 v218, v138 offset:0
	ds_write_b32 v218, v139 offset:4
	ds_write_b32 v218, v140 offset:8
	ds_write_b32 v218, v141 offset:12
	ds_write_b32 v218, v142 offset:4160
	ds_write_b32 v218, v143 offset:4164
	ds_write_b32 v218, v144 offset:4168
	ds_write_b32 v218, v145 offset:4172
	ds_write_b32 v218, v146 offset:8320
	ds_write_b32 v218, v147 offset:8324
	ds_write_b32 v218, v148 offset:8328
	ds_write_b32 v218, v149 offset:8332
	ds_write_b32 v218, v150 offset:12480
	ds_write_b32 v218, v151 offset:12484
	ds_write_b32 v218, v152 offset:12488
	ds_write_b32 v218, v153 offset:12492
	v_mad_u32_u24 v224, v227, s35, v228
	s_waitcnt lgkmcnt(0)
	s_barrier
	ds_read2_b32 v[138:139], v219 offset1:65
	ds_read2_b32 v[140:141], v219 offset0:130 offset1:195
	ds_read2_b32 v[142:143], v220 offset0:4 offset1:69
	ds_read2_b32 v[144:145], v220 offset0:134 offset1:199
	ds_read2_b32 v[146:147], v221 offset1:65
	ds_read2_b32 v[148:149], v221 offset0:130 offset1:195
	ds_read2_b32 v[150:151], v222 offset0:4 offset1:69
	ds_read2_b32 v[152:153], v222 offset0:134 offset1:199
	s_add_u32 s96, s52, s32
	s_addc_u32 s97, s53, 0
	s_waitcnt lgkmcnt(0)
	s_barrier
	v_cvt_pk_bf16_f32 v138, v138, v139
	v_cvt_pk_bf16_f32 v139, v140, v141
	v_cvt_pk_bf16_f32 v140, v142, v143
	v_cvt_pk_bf16_f32 v141, v144, v145
	v_cvt_pk_bf16_f32 v146, v146, v147
	v_cvt_pk_bf16_f32 v147, v148, v149
	v_cvt_pk_bf16_f32 v148, v150, v151
	v_cvt_pk_bf16_f32 v149, v152, v153
	global_store_dwordx4 v224, v[138:141], s[52:53]
	global_store_dwordx4 v224, v[146:149], s[96:97]
	s_cmp_ge_u32 s100, s66
	s_cbranch_scc1 .Lwc0_tail0
	s_cmpk_ge_u32 s100, 0x900
	s_cbranch_scc1 .Lwc0_t3_6
	s_cmpk_ge_u32 s100, 0x380
	s_cbranch_scc1 .Lwc0_t2_6
	s_cmpk_ge_u32 s100, 0x280
	s_cbranch_scc1 .Lwc0_t1_6
	s_movk_i32 s41, 0x78
	s_sub_u32 s99, s100, 0
	s_mul_i32 s44, s99, 0x66667
	s_lshr_b32 s44, s44, 24
	s_mul_i32 s36, s44, 40
	s_sub_u32 s99, s99, s36
	s_mul_i32 s38, s44, 0xa0000
	s_lshl_b32 s36, s99, 8
	s_add_u32 s38, s38, s36
	s_add_u32 s38, s38, 0x0
	s_lshl_b32 s36, s99, 6
	s_mov_b32 s32, 0x10000
	s_mul_i32 s36, s36, 0x800
	s_lshl_b32 s44, s44, 7
	s_add_u32 s36, s36, s44
	s_add_u32 s36, s36, 0x0
	s_mov_b32 s37, 0x28000
	s_movk_i32 s44, 0x800
	s_mov_b32 s99, 0x2800
	s_branch .Lwc0_tj_6

.Lwc0_tj_6:
	s_load_dwordx2 s[2:3], s[0:1], s41
	s_add_u32 s52, s4, s36
	s_addc_u32 s53, s5, 0
	v_mad_u32_u24 v223, v225, s99, v226
	v_writelane_b32 v229, s52, 8
	v_writelane_b32 v229, s53, 9
	v_writelane_b32 v229, s32, 10
	v_writelane_b32 v229, s44, 11
	s_add_u32 s100, s100, s67
	s_waitcnt lgkmcnt(0)
	s_add_u32 s38, s2, s38
	s_addc_u32 s39, s3, 0
	global_load_dwordx4 v[138:141], v223, s[38:39]
	s_add_u32 s38, s38, s37
	s_addc_u32 s39, s39, 0
	global_load_dwordx4 v[142:145], v223, s[38:39]
	s_add_u32 s38, s38, s37
	s_addc_u32 s39, s39, 0
	global_load_dwordx4 v[146:149], v223, s[38:39]
	s_add_u32 s38, s38, s37
	s_addc_u32 s39, s39, 0
	global_load_dwordx4 v[150:153], v223, s[38:39]
	s_waitcnt vmcnt(16)
	v_readlane_b32 s52, v229, 12
	v_readlane_b32 s53, v229, 13
	v_readlane_b32 s32, v229, 14
	v_readlane_b32 s35, v229, 15
	ds_write_b32 v218, v154 offset:0
	ds_write_b32 v218, v155 offset:4
	ds_write_b32 v218, v156 offset:8
	ds_write_b32 v218, v157 offset:12
	ds_write_b32 v218, v158 offset:4160
	ds_write_b32 v218, v159 offset:4164
	ds_write_b32 v218, v160 offset:4168
	ds_write_b32 v218, v161 offset:4172
	ds_write_b32 v218, v162 offset:8320
	ds_write_b32 v218, v163 offset:8324
	ds_write_b32 v218, v164 offset:8328
	ds_write_b32 v218, v165 offset:8332
	ds_write_b32 v218, v166 offset:12480
	ds_write_b32 v218, v167 offset:12484
	ds_write_b32 v218, v168 offset:12488
	ds_write_b32 v218, v169 offset:12492
	v_mad_u32_u24 v224, v227, s35, v228
	s_waitcnt lgkmcnt(0)
	s_barrier
	ds_read2_b32 v[154:155], v219 offset1:65
	ds_read2_b32 v[156:157], v219 offset0:130 offset1:195
	ds_read2_b32 v[158:159], v220 offset0:4 offset1:69
	ds_read2_b32 v[160:161], v220 offset0:134 offset1:199
	ds_read2_b32 v[162:163], v221 offset1:65
	ds_read2_b32 v[164:165], v221 offset0:130 offset1:195
	ds_read2_b32 v[166:167], v222 offset0:4 offset1:69
	ds_read2_b32 v[168:169], v222 offset0:134 offset1:199
	s_add_u32 s96, s52, s32
	s_addc_u32 s97, s53, 0
	s_waitcnt lgkmcnt(0)
	s_barrier
	v_cvt_pk_bf16_f32 v154, v154, v155
	v_cvt_pk_bf16_f32 v155, v156, v157
	v_cvt_pk_bf16_f32 v156, v158, v159
	v_cvt_pk_bf16_f32 v157, v160, v161
	v_cvt_pk_bf16_f32 v162, v162, v163
	v_cvt_pk_bf16_f32 v163, v164, v165
	v_cvt_pk_bf16_f32 v164, v166, v167
	v_cvt_pk_bf16_f32 v165, v168, v169
	global_store_dwordx4 v224, v[154:157], s[52:53]
	global_store_dwordx4 v224, v[162:165], s[96:97]
	s_cmp_ge_u32 s100, s66
	s_cbranch_scc1 .Lwc0_tail1
	s_cmpk_ge_u32 s100, 0x900
	s_cbranch_scc1 .Lwc0_t3_7
	s_cmpk_ge_u32 s100, 0x380
	s_cbranch_scc1 .Lwc0_t2_7
	s_cmpk_ge_u32 s100, 0x280
	s_cbranch_scc1 .Lwc0_t1_7
	s_movk_i32 s41, 0x78
	s_sub_u32 s99, s100, 0
	s_mul_i32 s44, s99, 0x66667
	s_lshr_b32 s44, s44, 24
	s_mul_i32 s36, s44, 40
	s_sub_u32 s99, s99, s36
	s_mul_i32 s38, s44, 0xa0000
	s_lshl_b32 s36, s99, 8
	s_add_u32 s38, s38, s36
	s_add_u32 s38, s38, 0x0
	s_lshl_b32 s36, s99, 6
	s_mov_b32 s32, 0x10000
	s_mul_i32 s36, s36, 0x800
	s_lshl_b32 s44, s44, 7
	s_add_u32 s36, s36, s44
	s_add_u32 s36, s36, 0x0
	s_mov_b32 s37, 0x28000
	s_movk_i32 s44, 0x800
	s_mov_b32 s99, 0x2800
	s_branch .Lwc0_tj_7

.Lwc0_tj_7:
	s_load_dwordx2 s[2:3], s[0:1], s41
	s_add_u32 s52, s4, s36
	s_addc_u32 s53, s5, 0
	v_mad_u32_u24 v223, v225, s99, v226
	v_writelane_b32 v229, s52, 12
	v_writelane_b32 v229, s53, 13
	v_writelane_b32 v229, s32, 14
	v_writelane_b32 v229, s44, 15
	s_add_u32 s100, s100, s67
	s_waitcnt lgkmcnt(0)
	s_add_u32 s38, s2, s38
	s_addc_u32 s39, s3, 0
	global_load_dwordx4 v[154:157], v223, s[38:39]
	s_add_u32 s38, s38, s37
	s_addc_u32 s39, s39, 0
	global_load_dwordx4 v[158:161], v223, s[38:39]
	s_add_u32 s38, s38, s37
	s_addc_u32 s39, s39, 0
	global_load_dwordx4 v[162:165], v223, s[38:39]
	s_add_u32 s38, s38, s37
	s_addc_u32 s39, s39, 0
	global_load_dwordx4 v[166:169], v223, s[38:39]
	s_waitcnt vmcnt(16)
	v_readlane_b32 s52, v229, 16
	v_readlane_b32 s53, v229, 17
	v_readlane_b32 s32, v229, 18
	v_readlane_b32 s35, v229, 19
	ds_write_b32 v218, v170 offset:0
	ds_write_b32 v218, v171 offset:4
	ds_write_b32 v218, v172 offset:8
	ds_write_b32 v218, v173 offset:12
	ds_write_b32 v218, v174 offset:4160
	ds_write_b32 v218, v175 offset:4164
	ds_write_b32 v218, v176 offset:4168
	ds_write_b32 v218, v177 offset:4172
	ds_write_b32 v218, v178 offset:8320
	ds_write_b32 v218, v179 offset:8324
	ds_write_b32 v218, v180 offset:8328
	ds_write_b32 v218, v181 offset:8332
	ds_write_b32 v218, v182 offset:12480
	ds_write_b32 v218, v183 offset:12484
	ds_write_b32 v218, v184 offset:12488
	ds_write_b32 v218, v185 offset:12492
	v_mad_u32_u24 v224, v227, s35, v228
	s_waitcnt lgkmcnt(0)
	s_barrier
	ds_read2_b32 v[170:171], v219 offset1:65
	ds_read2_b32 v[172:173], v219 offset0:130 offset1:195
	ds_read2_b32 v[174:175], v220 offset0:4 offset1:69
	ds_read2_b32 v[176:177], v220 offset0:134 offset1:199
	ds_read2_b32 v[178:179], v221 offset1:65
	ds_read2_b32 v[180:181], v221 offset0:130 offset1:195
	ds_read2_b32 v[182:183], v222 offset0:4 offset1:69
	ds_read2_b32 v[184:185], v222 offset0:134 offset1:199
	s_add_u32 s96, s52, s32
	s_addc_u32 s97, s53, 0
	s_waitcnt lgkmcnt(0)
	s_barrier
	v_cvt_pk_bf16_f32 v170, v170, v171
	v_cvt_pk_bf16_f32 v171, v172, v173
	v_cvt_pk_bf16_f32 v172, v174, v175
	v_cvt_pk_bf16_f32 v173, v176, v177
	v_cvt_pk_bf16_f32 v178, v178, v179
	v_cvt_pk_bf16_f32 v179, v180, v181
	v_cvt_pk_bf16_f32 v180, v182, v183
	v_cvt_pk_bf16_f32 v181, v184, v185
	global_store_dwordx4 v224, v[170:173], s[52:53]
	global_store_dwordx4 v224, v[178:181], s[96:97]
	s_cmp_ge_u32 s100, s66
	s_cbranch_scc1 .Lwc0_tail2
	s_cmpk_ge_u32 s100, 0x900
	s_cbranch_scc1 .Lwc0_t3_8
	s_cmpk_ge_u32 s100, 0x380
	s_cbranch_scc1 .Lwc0_t2_8
	s_cmpk_ge_u32 s100, 0x280
	s_cbranch_scc1 .Lwc0_t1_8
	s_movk_i32 s41, 0x78
	s_sub_u32 s99, s100, 0
	s_mul_i32 s44, s99, 0x66667
	s_lshr_b32 s44, s44, 24
	s_mul_i32 s36, s44, 40
	s_sub_u32 s99, s99, s36
	s_mul_i32 s38, s44, 0xa0000
	s_lshl_b32 s36, s99, 8
	s_add_u32 s38, s38, s36
	s_add_u32 s38, s38, 0x0
	s_lshl_b32 s36, s99, 6
	s_mov_b32 s32, 0x10000
	s_mul_i32 s36, s36, 0x800
	s_lshl_b32 s44, s44, 7
	s_add_u32 s36, s36, s44
	s_add_u32 s36, s36, 0x0
	s_mov_b32 s37, 0x28000
	s_movk_i32 s44, 0x800
	s_mov_b32 s99, 0x2800
	s_branch .Lwc0_tj_8

.Lwc0_tj_8:
	s_load_dwordx2 s[2:3], s[0:1], s41
	s_add_u32 s52, s4, s36
	s_addc_u32 s53, s5, 0
	v_mad_u32_u24 v223, v225, s99, v226
	v_writelane_b32 v229, s52, 16
	v_writelane_b32 v229, s53, 17
	v_writelane_b32 v229, s32, 18
	v_writelane_b32 v229, s44, 19
	s_add_u32 s100, s100, s67
	s_waitcnt lgkmcnt(0)
	s_add_u32 s38, s2, s38
	s_addc_u32 s39, s3, 0
	global_load_dwordx4 v[170:173], v223, s[38:39]
	s_add_u32 s38, s38, s37
	s_addc_u32 s39, s39, 0
	global_load_dwordx4 v[174:177], v223, s[38:39]
	s_add_u32 s38, s38, s37
	s_addc_u32 s39, s39, 0
	global_load_dwordx4 v[178:181], v223, s[38:39]
	s_add_u32 s38, s38, s37
	s_addc_u32 s39, s39, 0
	global_load_dwordx4 v[182:185], v223, s[38:39]
	s_waitcnt vmcnt(16)
	v_readlane_b32 s52, v229, 20
	v_readlane_b32 s53, v229, 21
	v_readlane_b32 s32, v229, 22
	v_readlane_b32 s35, v229, 23
	ds_write_b32 v218, v186 offset:0
	ds_write_b32 v218, v187 offset:4
	ds_write_b32 v218, v188 offset:8
	ds_write_b32 v218, v189 offset:12
	ds_write_b32 v218, v190 offset:4160
	ds_write_b32 v218, v191 offset:4164
	ds_write_b32 v218, v192 offset:4168
	ds_write_b32 v218, v193 offset:4172
	ds_write_b32 v218, v194 offset:8320
	ds_write_b32 v218, v195 offset:8324
	ds_write_b32 v218, v196 offset:8328
	ds_write_b32 v218, v197 offset:8332
	ds_write_b32 v218, v198 offset:12480
	ds_write_b32 v218, v199 offset:12484
	ds_write_b32 v218, v200 offset:12488
	ds_write_b32 v218, v201 offset:12492
	v_mad_u32_u24 v224, v227, s35, v228
	s_waitcnt lgkmcnt(0)
	s_barrier
	ds_read2_b32 v[186:187], v219 offset1:65
	ds_read2_b32 v[188:189], v219 offset0:130 offset1:195
	ds_read2_b32 v[190:191], v220 offset0:4 offset1:69
	ds_read2_b32 v[192:193], v220 offset0:134 offset1:199
	ds_read2_b32 v[194:195], v221 offset1:65
	ds_read2_b32 v[196:197], v221 offset0:130 offset1:195
	ds_read2_b32 v[198:199], v222 offset0:4 offset1:69
	ds_read2_b32 v[200:201], v222 offset0:134 offset1:199
	s_add_u32 s96, s52, s32
	s_addc_u32 s97, s53, 0
	s_waitcnt lgkmcnt(0)
	s_barrier
	v_cvt_pk_bf16_f32 v186, v186, v187
	v_cvt_pk_bf16_f32 v187, v188, v189
	v_cvt_pk_bf16_f32 v188, v190, v191
	v_cvt_pk_bf16_f32 v189, v192, v193
	v_cvt_pk_bf16_f32 v194, v194, v195
	v_cvt_pk_bf16_f32 v195, v196, v197
	v_cvt_pk_bf16_f32 v196, v198, v199
	v_cvt_pk_bf16_f32 v197, v200, v201
	global_store_dwordx4 v224, v[186:189], s[52:53]
	global_store_dwordx4 v224, v[194:197], s[96:97]
	s_cmp_ge_u32 s100, s66
	s_cbranch_scc1 .Lwc0_tail3
	s_cmpk_ge_u32 s100, 0x900
	s_cbranch_scc1 .Lwc0_t3_9
	s_cmpk_ge_u32 s100, 0x380
	s_cbranch_scc1 .Lwc0_t2_9
	s_cmpk_ge_u32 s100, 0x280
	s_cbranch_scc1 .Lwc0_t1_9
	s_movk_i32 s41, 0x78
	s_sub_u32 s99, s100, 0
	s_mul_i32 s44, s99, 0x66667
	s_lshr_b32 s44, s44, 24
	s_mul_i32 s36, s44, 40
	s_sub_u32 s99, s99, s36
	s_mul_i32 s38, s44, 0xa0000
	s_lshl_b32 s36, s99, 8
	s_add_u32 s38, s38, s36
	s_add_u32 s38, s38, 0x0
	s_lshl_b32 s36, s99, 6
	s_mov_b32 s32, 0x10000
	s_mul_i32 s36, s36, 0x800
	s_lshl_b32 s44, s44, 7
	s_add_u32 s36, s36, s44
	s_add_u32 s36, s36, 0x0
	s_mov_b32 s37, 0x28000
	s_movk_i32 s44, 0x800
	s_mov_b32 s99, 0x2800
	s_branch .Lwc0_tj_9

.Lwc0_tj_9:
	s_load_dwordx2 s[2:3], s[0:1], s41
	s_add_u32 s52, s4, s36
	s_addc_u32 s53, s5, 0
	v_mad_u32_u24 v223, v225, s99, v226
	v_writelane_b32 v229, s52, 20
	v_writelane_b32 v229, s53, 21
	v_writelane_b32 v229, s32, 22
	v_writelane_b32 v229, s44, 23
	s_add_u32 s100, s100, s67
	s_waitcnt lgkmcnt(0)
	s_add_u32 s38, s2, s38
	s_addc_u32 s39, s3, 0
	global_load_dwordx4 v[186:189], v223, s[38:39]
	s_add_u32 s38, s38, s37
	s_addc_u32 s39, s39, 0
	global_load_dwordx4 v[190:193], v223, s[38:39]
	s_add_u32 s38, s38, s37
	s_addc_u32 s39, s39, 0
	global_load_dwordx4 v[194:197], v223, s[38:39]
	s_add_u32 s38, s38, s37
	s_addc_u32 s39, s39, 0
	global_load_dwordx4 v[198:201], v223, s[38:39]
	s_waitcnt vmcnt(16)
	v_readlane_b32 s52, v229, 24
	v_readlane_b32 s53, v229, 25
	v_readlane_b32 s32, v229, 26
	v_readlane_b32 s35, v229, 27
	ds_write_b32 v218, v202 offset:0
	ds_write_b32 v218, v203 offset:4
	ds_write_b32 v218, v204 offset:8
	ds_write_b32 v218, v205 offset:12
	ds_write_b32 v218, v206 offset:4160
	ds_write_b32 v218, v207 offset:4164
	ds_write_b32 v218, v208 offset:4168
	ds_write_b32 v218, v209 offset:4172
	ds_write_b32 v218, v210 offset:8320
	ds_write_b32 v218, v211 offset:8324
	ds_write_b32 v218, v212 offset:8328
	ds_write_b32 v218, v213 offset:8332
	ds_write_b32 v218, v214 offset:12480
	ds_write_b32 v218, v215 offset:12484
	ds_write_b32 v218, v216 offset:12488
	ds_write_b32 v218, v217 offset:12492
	v_mad_u32_u24 v224, v227, s35, v228
	s_waitcnt lgkmcnt(0)
	s_barrier
	ds_read2_b32 v[202:203], v219 offset1:65
	ds_read2_b32 v[204:205], v219 offset0:130 offset1:195
	ds_read2_b32 v[206:207], v220 offset0:4 offset1:69
	ds_read2_b32 v[208:209], v220 offset0:134 offset1:199
	ds_read2_b32 v[210:211], v221 offset1:65
	ds_read2_b32 v[212:213], v221 offset0:130 offset1:195
	ds_read2_b32 v[214:215], v222 offset0:4 offset1:69
	ds_read2_b32 v[216:217], v222 offset0:134 offset1:199
	s_add_u32 s96, s52, s32
	s_addc_u32 s97, s53, 0
	s_waitcnt lgkmcnt(0)
	s_barrier
	v_cvt_pk_bf16_f32 v202, v202, v203
	v_cvt_pk_bf16_f32 v203, v204, v205
	v_cvt_pk_bf16_f32 v204, v206, v207
	v_cvt_pk_bf16_f32 v205, v208, v209
	v_cvt_pk_bf16_f32 v210, v210, v211
	v_cvt_pk_bf16_f32 v211, v212, v213
	v_cvt_pk_bf16_f32 v212, v214, v215
	v_cvt_pk_bf16_f32 v213, v216, v217
	global_store_dwordx4 v224, v[202:205], s[52:53]
	global_store_dwordx4 v224, v[210:213], s[96:97]
	s_cmp_ge_u32 s100, s66
	s_cbranch_scc1 .Lwc0_tail4
	s_cmpk_ge_u32 s100, 0x900
	s_cbranch_scc1 .Lwc0_t3_10
	s_cmpk_ge_u32 s100, 0x380
	s_cbranch_scc1 .Lwc0_t2_10
	s_cmpk_ge_u32 s100, 0x280
	s_cbranch_scc1 .Lwc0_t1_10
	s_movk_i32 s41, 0x78
	s_sub_u32 s99, s100, 0
	s_mul_i32 s44, s99, 0x66667
	s_lshr_b32 s44, s44, 24
	s_mul_i32 s36, s44, 40
	s_sub_u32 s99, s99, s36
	s_mul_i32 s38, s44, 0xa0000
	s_lshl_b32 s36, s99, 8
	s_add_u32 s38, s38, s36
	s_add_u32 s38, s38, 0x0
	s_lshl_b32 s36, s99, 6
	s_mov_b32 s32, 0x10000
	s_mul_i32 s36, s36, 0x800
	s_lshl_b32 s44, s44, 7
	s_add_u32 s36, s36, s44
	s_add_u32 s36, s36, 0x0
	s_mov_b32 s37, 0x28000
	s_movk_i32 s44, 0x800
	s_mov_b32 s99, 0x2800
	s_branch .Lwc0_tj_10

.Lwc0_tj_10:
	s_load_dwordx2 s[2:3], s[0:1], s41
	s_add_u32 s52, s4, s36
	s_addc_u32 s53, s5, 0
	v_mad_u32_u24 v223, v225, s99, v226
	v_writelane_b32 v229, s52, 24
	v_writelane_b32 v229, s53, 25
	v_writelane_b32 v229, s32, 26
	v_writelane_b32 v229, s44, 27
	s_add_u32 s100, s100, s67
	s_waitcnt lgkmcnt(0)
	s_add_u32 s38, s2, s38
	s_addc_u32 s39, s3, 0
	global_load_dwordx4 v[202:205], v223, s[38:39]
	s_add_u32 s38, s38, s37
	s_addc_u32 s39, s39, 0
	global_load_dwordx4 v[206:209], v223, s[38:39]
	s_add_u32 s38, s38, s37
	s_addc_u32 s39, s39, 0
	global_load_dwordx4 v[210:213], v223, s[38:39]
	s_add_u32 s38, s38, s37
	s_addc_u32 s39, s39, 0
	global_load_dwordx4 v[214:217], v223, s[38:39]
	s_branch .Lwc0_loop
.Lwc0_tail0:
	s_waitcnt vmcnt(0)
	v_readlane_b32 s52, v229, 12
	v_readlane_b32 s53, v229, 13
	v_readlane_b32 s32, v229, 14
	v_readlane_b32 s35, v229, 15
	ds_write_b32 v218, v154 offset:0
	ds_write_b32 v218, v155 offset:4
	ds_write_b32 v218, v156 offset:8
	ds_write_b32 v218, v157 offset:12
	ds_write_b32 v218, v158 offset:4160
	ds_write_b32 v218, v159 offset:4164
	ds_write_b32 v218, v160 offset:4168
	ds_write_b32 v218, v161 offset:4172
	ds_write_b32 v218, v162 offset:8320
	ds_write_b32 v218, v163 offset:8324
	ds_write_b32 v218, v164 offset:8328
	ds_write_b32 v218, v165 offset:8332
	ds_write_b32 v218, v166 offset:12480
	ds_write_b32 v218, v167 offset:12484
	ds_write_b32 v218, v168 offset:12488
	ds_write_b32 v218, v169 offset:12492
	v_mad_u32_u24 v224, v227, s35, v228
	s_waitcnt lgkmcnt(0)
	s_barrier
	ds_read2_b32 v[154:155], v219 offset1:65
	ds_read2_b32 v[156:157], v219 offset0:130 offset1:195
	ds_read2_b32 v[158:159], v220 offset0:4 offset1:69
	ds_read2_b32 v[160:161], v220 offset0:134 offset1:199
	ds_read2_b32 v[162:163], v221 offset1:65
	ds_read2_b32 v[164:165], v221 offset0:130 offset1:195
	ds_read2_b32 v[166:167], v222 offset0:4 offset1:69
	ds_read2_b32 v[168:169], v222 offset0:134 offset1:199
	s_add_u32 s96, s52, s32
	s_addc_u32 s97, s53, 0
	s_waitcnt lgkmcnt(0)
	s_barrier
	v_cvt_pk_bf16_f32 v154, v154, v155
	v_cvt_pk_bf16_f32 v155, v156, v157
	v_cvt_pk_bf16_f32 v156, v158, v159
	v_cvt_pk_bf16_f32 v157, v160, v161
	v_cvt_pk_bf16_f32 v162, v162, v163
	v_cvt_pk_bf16_f32 v163, v164, v165
	v_cvt_pk_bf16_f32 v164, v166, v167
	v_cvt_pk_bf16_f32 v165, v168, v169
	global_store_dwordx4 v224, v[154:157], s[52:53]
	global_store_dwordx4 v224, v[162:165], s[96:97]
	v_readlane_b32 s52, v229, 16
	v_readlane_b32 s53, v229, 17
	v_readlane_b32 s32, v229, 18
	v_readlane_b32 s35, v229, 19
	ds_write_b32 v218, v170 offset:0
	ds_write_b32 v218, v171 offset:4
	ds_write_b32 v218, v172 offset:8
	ds_write_b32 v218, v173 offset:12
	ds_write_b32 v218, v174 offset:4160
	ds_write_b32 v218, v175 offset:4164
	ds_write_b32 v218, v176 offset:4168
	ds_write_b32 v218, v177 offset:4172
	ds_write_b32 v218, v178 offset:8320
	ds_write_b32 v218, v179 offset:8324
	ds_write_b32 v218, v180 offset:8328
	ds_write_b32 v218, v181 offset:8332
	ds_write_b32 v218, v182 offset:12480
	ds_write_b32 v218, v183 offset:12484
	ds_write_b32 v218, v184 offset:12488
	ds_write_b32 v218, v185 offset:12492
	v_mad_u32_u24 v224, v227, s35, v228
	s_waitcnt lgkmcnt(0)
	s_barrier
	ds_read2_b32 v[170:171], v219 offset1:65
	ds_read2_b32 v[172:173], v219 offset0:130 offset1:195
	ds_read2_b32 v[174:175], v220 offset0:4 offset1:69
	ds_read2_b32 v[176:177], v220 offset0:134 offset1:199
	ds_read2_b32 v[178:179], v221 offset1:65
	ds_read2_b32 v[180:181], v221 offset0:130 offset1:195
	ds_read2_b32 v[182:183], v222 offset0:4 offset1:69
	ds_read2_b32 v[184:185], v222 offset0:134 offset1:199
	s_add_u32 s96, s52, s32
	s_addc_u32 s97, s53, 0
	s_waitcnt lgkmcnt(0)
	s_barrier
	v_cvt_pk_bf16_f32 v170, v170, v171
	v_cvt_pk_bf16_f32 v171, v172, v173
	v_cvt_pk_bf16_f32 v172, v174, v175
	v_cvt_pk_bf16_f32 v173, v176, v177
	v_cvt_pk_bf16_f32 v178, v178, v179
	v_cvt_pk_bf16_f32 v179, v180, v181
	v_cvt_pk_bf16_f32 v180, v182, v183
	v_cvt_pk_bf16_f32 v181, v184, v185
	global_store_dwordx4 v224, v[170:173], s[52:53]
	global_store_dwordx4 v224, v[178:181], s[96:97]
	v_readlane_b32 s52, v229, 20
	v_readlane_b32 s53, v229, 21
	v_readlane_b32 s32, v229, 22
	v_readlane_b32 s35, v229, 23
	ds_write_b32 v218, v186 offset:0
	ds_write_b32 v218, v187 offset:4
	ds_write_b32 v218, v188 offset:8
	ds_write_b32 v218, v189 offset:12
	ds_write_b32 v218, v190 offset:4160
	ds_write_b32 v218, v191 offset:4164
	ds_write_b32 v218, v192 offset:4168
	ds_write_b32 v218, v193 offset:4172
	ds_write_b32 v218, v194 offset:8320
	ds_write_b32 v218, v195 offset:8324
	ds_write_b32 v218, v196 offset:8328
	ds_write_b32 v218, v197 offset:8332
	ds_write_b32 v218, v198 offset:12480
	ds_write_b32 v218, v199 offset:12484
	ds_write_b32 v218, v200 offset:12488
	ds_write_b32 v218, v201 offset:12492
	v_mad_u32_u24 v224, v227, s35, v228
	s_waitcnt lgkmcnt(0)
	s_barrier
	ds_read2_b32 v[186:187], v219 offset1:65
	ds_read2_b32 v[188:189], v219 offset0:130 offset1:195
	ds_read2_b32 v[190:191], v220 offset0:4 offset1:69
	ds_read2_b32 v[192:193], v220 offset0:134 offset1:199
	ds_read2_b32 v[194:195], v221 offset1:65
	ds_read2_b32 v[196:197], v221 offset0:130 offset1:195
	ds_read2_b32 v[198:199], v222 offset0:4 offset1:69
	ds_read2_b32 v[200:201], v222 offset0:134 offset1:199
	s_add_u32 s96, s52, s32
	s_addc_u32 s97, s53, 0
	s_waitcnt lgkmcnt(0)
	s_barrier
	v_cvt_pk_bf16_f32 v186, v186, v187
	v_cvt_pk_bf16_f32 v187, v188, v189
	v_cvt_pk_bf16_f32 v188, v190, v191
	v_cvt_pk_bf16_f32 v189, v192, v193
	v_cvt_pk_bf16_f32 v194, v194, v195
	v_cvt_pk_bf16_f32 v195, v196, v197
	v_cvt_pk_bf16_f32 v196, v198, v199
	v_cvt_pk_bf16_f32 v197, v200, v201
	global_store_dwordx4 v224, v[186:189], s[52:53]
	global_store_dwordx4 v224, v[194:197], s[96:97]
	v_readlane_b32 s52, v229, 24
	v_readlane_b32 s53, v229, 25
	v_readlane_b32 s32, v229, 26
	v_readlane_b32 s35, v229, 27
	ds_write_b32 v218, v202 offset:0
	ds_write_b32 v218, v203 offset:4
	ds_write_b32 v218, v204 offset:8
	ds_write_b32 v218, v205 offset:12
	ds_write_b32 v218, v206 offset:4160
	ds_write_b32 v218, v207 offset:4164
	ds_write_b32 v218, v208 offset:4168
	ds_write_b32 v218, v209 offset:4172
	ds_write_b32 v218, v210 offset:8320
	ds_write_b32 v218, v211 offset:8324
	ds_write_b32 v218, v212 offset:8328
	ds_write_b32 v218, v213 offset:8332
	ds_write_b32 v218, v214 offset:12480
	ds_write_b32 v218, v215 offset:12484
	ds_write_b32 v218, v216 offset:12488
	ds_write_b32 v218, v217 offset:12492
	v_mad_u32_u24 v224, v227, s35, v228
	s_waitcnt lgkmcnt(0)
	s_barrier
	ds_read2_b32 v[202:203], v219 offset1:65
	ds_read2_b32 v[204:205], v219 offset0:130 offset1:195
	ds_read2_b32 v[206:207], v220 offset0:4 offset1:69
	ds_read2_b32 v[208:209], v220 offset0:134 offset1:199
	ds_read2_b32 v[210:211], v221 offset1:65
	ds_read2_b32 v[212:213], v221 offset0:130 offset1:195
	ds_read2_b32 v[214:215], v222 offset0:4 offset1:69
	ds_read2_b32 v[216:217], v222 offset0:134 offset1:199
	s_add_u32 s96, s52, s32
	s_addc_u32 s97, s53, 0
	s_waitcnt lgkmcnt(0)
	s_barrier
	v_cvt_pk_bf16_f32 v202, v202, v203
	v_cvt_pk_bf16_f32 v203, v204, v205
	v_cvt_pk_bf16_f32 v204, v206, v207
	v_cvt_pk_bf16_f32 v205, v208, v209
	v_cvt_pk_bf16_f32 v210, v210, v211
	v_cvt_pk_bf16_f32 v211, v212, v213
	v_cvt_pk_bf16_f32 v212, v214, v215
	v_cvt_pk_bf16_f32 v213, v216, v217
	global_store_dwordx4 v224, v[202:205], s[52:53]
	global_store_dwordx4 v224, v[210:213], s[96:97]
	s_branch .Lwc0_done
.Lwc0_tail1:
	s_waitcnt vmcnt(0)
	v_readlane_b32 s52, v229, 16
	v_readlane_b32 s53, v229, 17
	v_readlane_b32 s32, v229, 18
	v_readlane_b32 s35, v229, 19
	ds_write_b32 v218, v170 offset:0
	ds_write_b32 v218, v171 offset:4
	ds_write_b32 v218, v172 offset:8
	ds_write_b32 v218, v173 offset:12
	ds_write_b32 v218, v174 offset:4160
	ds_write_b32 v218, v175 offset:4164
	ds_write_b32 v218, v176 offset:4168
	ds_write_b32 v218, v177 offset:4172
	ds_write_b32 v218, v178 offset:8320
	ds_write_b32 v218, v179 offset:8324
	ds_write_b32 v218, v180 offset:8328
	ds_write_b32 v218, v181 offset:8332
	ds_write_b32 v218, v182 offset:12480
	ds_write_b32 v218, v183 offset:12484
	ds_write_b32 v218, v184 offset:12488
	ds_write_b32 v218, v185 offset:12492
	v_mad_u32_u24 v224, v227, s35, v228
	s_waitcnt lgkmcnt(0)
	s_barrier
	ds_read2_b32 v[170:171], v219 offset1:65
	ds_read2_b32 v[172:173], v219 offset0:130 offset1:195
	ds_read2_b32 v[174:175], v220 offset0:4 offset1:69
	ds_read2_b32 v[176:177], v220 offset0:134 offset1:199
	ds_read2_b32 v[178:179], v221 offset1:65
	ds_read2_b32 v[180:181], v221 offset0:130 offset1:195
	ds_read2_b32 v[182:183], v222 offset0:4 offset1:69
	ds_read2_b32 v[184:185], v222 offset0:134 offset1:199
	s_add_u32 s96, s52, s32
	s_addc_u32 s97, s53, 0
	s_waitcnt lgkmcnt(0)
	s_barrier
	v_cvt_pk_bf16_f32 v170, v170, v171
	v_cvt_pk_bf16_f32 v171, v172, v173
	v_cvt_pk_bf16_f32 v172, v174, v175
	v_cvt_pk_bf16_f32 v173, v176, v177
	v_cvt_pk_bf16_f32 v178, v178, v179
	v_cvt_pk_bf16_f32 v179, v180, v181
	v_cvt_pk_bf16_f32 v180, v182, v183
	v_cvt_pk_bf16_f32 v181, v184, v185
	global_store_dwordx4 v224, v[170:173], s[52:53]
	global_store_dwordx4 v224, v[178:181], s[96:97]
	v_readlane_b32 s52, v229, 20
	v_readlane_b32 s53, v229, 21
	v_readlane_b32 s32, v229, 22
	v_readlane_b32 s35, v229, 23
	ds_write_b32 v218, v186 offset:0
	ds_write_b32 v218, v187 offset:4
	ds_write_b32 v218, v188 offset:8
	ds_write_b32 v218, v189 offset:12
	ds_write_b32 v218, v190 offset:4160
	ds_write_b32 v218, v191 offset:4164
	ds_write_b32 v218, v192 offset:4168
	ds_write_b32 v218, v193 offset:4172
	ds_write_b32 v218, v194 offset:8320
	ds_write_b32 v218, v195 offset:8324
	ds_write_b32 v218, v196 offset:8328
	ds_write_b32 v218, v197 offset:8332
	ds_write_b32 v218, v198 offset:12480
	ds_write_b32 v218, v199 offset:12484
	ds_write_b32 v218, v200 offset:12488
	ds_write_b32 v218, v201 offset:12492
	v_mad_u32_u24 v224, v227, s35, v228
	s_waitcnt lgkmcnt(0)
	s_barrier
	ds_read2_b32 v[186:187], v219 offset1:65
	ds_read2_b32 v[188:189], v219 offset0:130 offset1:195
	ds_read2_b32 v[190:191], v220 offset0:4 offset1:69
	ds_read2_b32 v[192:193], v220 offset0:134 offset1:199
	ds_read2_b32 v[194:195], v221 offset1:65
	ds_read2_b32 v[196:197], v221 offset0:130 offset1:195
	ds_read2_b32 v[198:199], v222 offset0:4 offset1:69
	ds_read2_b32 v[200:201], v222 offset0:134 offset1:199
	s_add_u32 s96, s52, s32
	s_addc_u32 s97, s53, 0
	s_waitcnt lgkmcnt(0)
	s_barrier
	v_cvt_pk_bf16_f32 v186, v186, v187
	v_cvt_pk_bf16_f32 v187, v188, v189
	v_cvt_pk_bf16_f32 v188, v190, v191
	v_cvt_pk_bf16_f32 v189, v192, v193
	v_cvt_pk_bf16_f32 v194, v194, v195
	v_cvt_pk_bf16_f32 v195, v196, v197
	v_cvt_pk_bf16_f32 v196, v198, v199
	v_cvt_pk_bf16_f32 v197, v200, v201
	global_store_dwordx4 v224, v[186:189], s[52:53]
	global_store_dwordx4 v224, v[194:197], s[96:97]
	v_readlane_b32 s52, v229, 24
	v_readlane_b32 s53, v229, 25
	v_readlane_b32 s32, v229, 26
	v_readlane_b32 s35, v229, 27
	ds_write_b32 v218, v202 offset:0
	ds_write_b32 v218, v203 offset:4
	ds_write_b32 v218, v204 offset:8
	ds_write_b32 v218, v205 offset:12
	ds_write_b32 v218, v206 offset:4160
	ds_write_b32 v218, v207 offset:4164
	ds_write_b32 v218, v208 offset:4168
	ds_write_b32 v218, v209 offset:4172
	ds_write_b32 v218, v210 offset:8320
	ds_write_b32 v218, v211 offset:8324
	ds_write_b32 v218, v212 offset:8328
	ds_write_b32 v218, v213 offset:8332
	ds_write_b32 v218, v214 offset:12480
	ds_write_b32 v218, v215 offset:12484
	ds_write_b32 v218, v216 offset:12488
	ds_write_b32 v218, v217 offset:12492
	v_mad_u32_u24 v224, v227, s35, v228
	s_waitcnt lgkmcnt(0)
	s_barrier
	ds_read2_b32 v[202:203], v219 offset1:65
	ds_read2_b32 v[204:205], v219 offset0:130 offset1:195
	ds_read2_b32 v[206:207], v220 offset0:4 offset1:69
	ds_read2_b32 v[208:209], v220 offset0:134 offset1:199
	ds_read2_b32 v[210:211], v221 offset1:65
	ds_read2_b32 v[212:213], v221 offset0:130 offset1:195
	ds_read2_b32 v[214:215], v222 offset0:4 offset1:69
	ds_read2_b32 v[216:217], v222 offset0:134 offset1:199
	s_add_u32 s96, s52, s32
	s_addc_u32 s97, s53, 0
	s_waitcnt lgkmcnt(0)
	s_barrier
	v_cvt_pk_bf16_f32 v202, v202, v203
	v_cvt_pk_bf16_f32 v203, v204, v205
	v_cvt_pk_bf16_f32 v204, v206, v207
	v_cvt_pk_bf16_f32 v205, v208, v209
	v_cvt_pk_bf16_f32 v210, v210, v211
	v_cvt_pk_bf16_f32 v211, v212, v213
	v_cvt_pk_bf16_f32 v212, v214, v215
	v_cvt_pk_bf16_f32 v213, v216, v217
	global_store_dwordx4 v224, v[202:205], s[52:53]
	global_store_dwordx4 v224, v[210:213], s[96:97]
	v_readlane_b32 s52, v229, 8
	v_readlane_b32 s53, v229, 9
	v_readlane_b32 s32, v229, 10
	v_readlane_b32 s35, v229, 11
	ds_write_b32 v218, v138 offset:0
	ds_write_b32 v218, v139 offset:4
	ds_write_b32 v218, v140 offset:8
	ds_write_b32 v218, v141 offset:12
	ds_write_b32 v218, v142 offset:4160
	ds_write_b32 v218, v143 offset:4164
	ds_write_b32 v218, v144 offset:4168
	ds_write_b32 v218, v145 offset:4172
	ds_write_b32 v218, v146 offset:8320
	ds_write_b32 v218, v147 offset:8324
	ds_write_b32 v218, v148 offset:8328
	ds_write_b32 v218, v149 offset:8332
	ds_write_b32 v218, v150 offset:12480
	ds_write_b32 v218, v151 offset:12484
	ds_write_b32 v218, v152 offset:12488
	ds_write_b32 v218, v153 offset:12492
	v_mad_u32_u24 v224, v227, s35, v228
	s_waitcnt lgkmcnt(0)
	s_barrier
	ds_read2_b32 v[138:139], v219 offset1:65
	ds_read2_b32 v[140:141], v219 offset0:130 offset1:195
	ds_read2_b32 v[142:143], v220 offset0:4 offset1:69
	ds_read2_b32 v[144:145], v220 offset0:134 offset1:199
	ds_read2_b32 v[146:147], v221 offset1:65
	ds_read2_b32 v[148:149], v221 offset0:130 offset1:195
	ds_read2_b32 v[150:151], v222 offset0:4 offset1:69
	ds_read2_b32 v[152:153], v222 offset0:134 offset1:199
	s_add_u32 s96, s52, s32
	s_addc_u32 s97, s53, 0
	s_waitcnt lgkmcnt(0)
	s_barrier
	v_cvt_pk_bf16_f32 v138, v138, v139
	v_cvt_pk_bf16_f32 v139, v140, v141
	v_cvt_pk_bf16_f32 v140, v142, v143
	v_cvt_pk_bf16_f32 v141, v144, v145
	v_cvt_pk_bf16_f32 v146, v146, v147
	v_cvt_pk_bf16_f32 v147, v148, v149
	v_cvt_pk_bf16_f32 v148, v150, v151
	v_cvt_pk_bf16_f32 v149, v152, v153
	global_store_dwordx4 v224, v[138:141], s[52:53]
	global_store_dwordx4 v224, v[146:149], s[96:97]
	s_branch .Lwc0_done
.Lwc0_tail2:
	s_waitcnt vmcnt(0)
	v_readlane_b32 s52, v229, 20
	v_readlane_b32 s53, v229, 21
	v_readlane_b32 s32, v229, 22
	v_readlane_b32 s35, v229, 23
	ds_write_b32 v218, v186 offset:0
	ds_write_b32 v218, v187 offset:4
	ds_write_b32 v218, v188 offset:8
	ds_write_b32 v218, v189 offset:12
	ds_write_b32 v218, v190 offset:4160
	ds_write_b32 v218, v191 offset:4164
	ds_write_b32 v218, v192 offset:4168
	ds_write_b32 v218, v193 offset:4172
	ds_write_b32 v218, v194 offset:8320
	ds_write_b32 v218, v195 offset:8324
	ds_write_b32 v218, v196 offset:8328
	ds_write_b32 v218, v197 offset:8332
	ds_write_b32 v218, v198 offset:12480
	ds_write_b32 v218, v199 offset:12484
	ds_write_b32 v218, v200 offset:12488
	ds_write_b32 v218, v201 offset:12492
	v_mad_u32_u24 v224, v227, s35, v228
	s_waitcnt lgkmcnt(0)
	s_barrier
	ds_read2_b32 v[186:187], v219 offset1:65
	ds_read2_b32 v[188:189], v219 offset0:130 offset1:195
	ds_read2_b32 v[190:191], v220 offset0:4 offset1:69
	ds_read2_b32 v[192:193], v220 offset0:134 offset1:199
	ds_read2_b32 v[194:195], v221 offset1:65
	ds_read2_b32 v[196:197], v221 offset0:130 offset1:195
	ds_read2_b32 v[198:199], v222 offset0:4 offset1:69
	ds_read2_b32 v[200:201], v222 offset0:134 offset1:199
	s_add_u32 s96, s52, s32
	s_addc_u32 s97, s53, 0
	s_waitcnt lgkmcnt(0)
	s_barrier
	v_cvt_pk_bf16_f32 v186, v186, v187
	v_cvt_pk_bf16_f32 v187, v188, v189
	v_cvt_pk_bf16_f32 v188, v190, v191
	v_cvt_pk_bf16_f32 v189, v192, v193
	v_cvt_pk_bf16_f32 v194, v194, v195
	v_cvt_pk_bf16_f32 v195, v196, v197
	v_cvt_pk_bf16_f32 v196, v198, v199
	v_cvt_pk_bf16_f32 v197, v200, v201
	global_store_dwordx4 v224, v[186:189], s[52:53]
	global_store_dwordx4 v224, v[194:197], s[96:97]
	v_readlane_b32 s52, v229, 24
	v_readlane_b32 s53, v229, 25
	v_readlane_b32 s32, v229, 26
	v_readlane_b32 s35, v229, 27
	ds_write_b32 v218, v202 offset:0
	ds_write_b32 v218, v203 offset:4
	ds_write_b32 v218, v204 offset:8
	ds_write_b32 v218, v205 offset:12
	ds_write_b32 v218, v206 offset:4160
	ds_write_b32 v218, v207 offset:4164
	ds_write_b32 v218, v208 offset:4168
	ds_write_b32 v218, v209 offset:4172
	ds_write_b32 v218, v210 offset:8320
	ds_write_b32 v218, v211 offset:8324
	ds_write_b32 v218, v212 offset:8328
	ds_write_b32 v218, v213 offset:8332
	ds_write_b32 v218, v214 offset:12480
	ds_write_b32 v218, v215 offset:12484
	ds_write_b32 v218, v216 offset:12488
	ds_write_b32 v218, v217 offset:12492
	v_mad_u32_u24 v224, v227, s35, v228
	s_waitcnt lgkmcnt(0)
	s_barrier
	ds_read2_b32 v[202:203], v219 offset1:65
	ds_read2_b32 v[204:205], v219 offset0:130 offset1:195
	ds_read2_b32 v[206:207], v220 offset0:4 offset1:69
	ds_read2_b32 v[208:209], v220 offset0:134 offset1:199
	ds_read2_b32 v[210:211], v221 offset1:65
	ds_read2_b32 v[212:213], v221 offset0:130 offset1:195
	ds_read2_b32 v[214:215], v222 offset0:4 offset1:69
	ds_read2_b32 v[216:217], v222 offset0:134 offset1:199
	s_add_u32 s96, s52, s32
	s_addc_u32 s97, s53, 0
	s_waitcnt lgkmcnt(0)
	s_barrier
	v_cvt_pk_bf16_f32 v202, v202, v203
	v_cvt_pk_bf16_f32 v203, v204, v205
	v_cvt_pk_bf16_f32 v204, v206, v207
	v_cvt_pk_bf16_f32 v205, v208, v209
	v_cvt_pk_bf16_f32 v210, v210, v211
	v_cvt_pk_bf16_f32 v211, v212, v213
	v_cvt_pk_bf16_f32 v212, v214, v215
	v_cvt_pk_bf16_f32 v213, v216, v217
	global_store_dwordx4 v224, v[202:205], s[52:53]
	global_store_dwordx4 v224, v[210:213], s[96:97]
	v_readlane_b32 s52, v229, 8
	v_readlane_b32 s53, v229, 9
	v_readlane_b32 s32, v229, 10
	v_readlane_b32 s35, v229, 11
	ds_write_b32 v218, v138 offset:0
	ds_write_b32 v218, v139 offset:4
	ds_write_b32 v218, v140 offset:8
	ds_write_b32 v218, v141 offset:12
	ds_write_b32 v218, v142 offset:4160
	ds_write_b32 v218, v143 offset:4164
	ds_write_b32 v218, v144 offset:4168
	ds_write_b32 v218, v145 offset:4172
	ds_write_b32 v218, v146 offset:8320
	ds_write_b32 v218, v147 offset:8324
	ds_write_b32 v218, v148 offset:8328
	ds_write_b32 v218, v149 offset:8332
	ds_write_b32 v218, v150 offset:12480
	ds_write_b32 v218, v151 offset:12484
	ds_write_b32 v218, v152 offset:12488
	ds_write_b32 v218, v153 offset:12492
	v_mad_u32_u24 v224, v227, s35, v228
	s_waitcnt lgkmcnt(0)
	s_barrier
	ds_read2_b32 v[138:139], v219 offset1:65
	ds_read2_b32 v[140:141], v219 offset0:130 offset1:195
	ds_read2_b32 v[142:143], v220 offset0:4 offset1:69
	ds_read2_b32 v[144:145], v220 offset0:134 offset1:199
	ds_read2_b32 v[146:147], v221 offset1:65
	ds_read2_b32 v[148:149], v221 offset0:130 offset1:195
	ds_read2_b32 v[150:151], v222 offset0:4 offset1:69
	ds_read2_b32 v[152:153], v222 offset0:134 offset1:199
	s_add_u32 s96, s52, s32
	s_addc_u32 s97, s53, 0
	s_waitcnt lgkmcnt(0)
	s_barrier
	v_cvt_pk_bf16_f32 v138, v138, v139
	v_cvt_pk_bf16_f32 v139, v140, v141
	v_cvt_pk_bf16_f32 v140, v142, v143
	v_cvt_pk_bf16_f32 v141, v144, v145
	v_cvt_pk_bf16_f32 v146, v146, v147
	v_cvt_pk_bf16_f32 v147, v148, v149
	v_cvt_pk_bf16_f32 v148, v150, v151
	v_cvt_pk_bf16_f32 v149, v152, v153
	global_store_dwordx4 v224, v[138:141], s[52:53]
	global_store_dwordx4 v224, v[146:149], s[96:97]
	v_readlane_b32 s52, v229, 12
	v_readlane_b32 s53, v229, 13
	v_readlane_b32 s32, v229, 14
	v_readlane_b32 s35, v229, 15
	ds_write_b32 v218, v154 offset:0
	ds_write_b32 v218, v155 offset:4
	ds_write_b32 v218, v156 offset:8
	ds_write_b32 v218, v157 offset:12
	ds_write_b32 v218, v158 offset:4160
	ds_write_b32 v218, v159 offset:4164
	ds_write_b32 v218, v160 offset:4168
	ds_write_b32 v218, v161 offset:4172
	ds_write_b32 v218, v162 offset:8320
	ds_write_b32 v218, v163 offset:8324
	ds_write_b32 v218, v164 offset:8328
	ds_write_b32 v218, v165 offset:8332
	ds_write_b32 v218, v166 offset:12480
	ds_write_b32 v218, v167 offset:12484
	ds_write_b32 v218, v168 offset:12488
	ds_write_b32 v218, v169 offset:12492
	v_mad_u32_u24 v224, v227, s35, v228
	s_waitcnt lgkmcnt(0)
	s_barrier
	ds_read2_b32 v[154:155], v219 offset1:65
	ds_read2_b32 v[156:157], v219 offset0:130 offset1:195
	ds_read2_b32 v[158:159], v220 offset0:4 offset1:69
	ds_read2_b32 v[160:161], v220 offset0:134 offset1:199
	ds_read2_b32 v[162:163], v221 offset1:65
	ds_read2_b32 v[164:165], v221 offset0:130 offset1:195
	ds_read2_b32 v[166:167], v222 offset0:4 offset1:69
	ds_read2_b32 v[168:169], v222 offset0:134 offset1:199
	s_add_u32 s96, s52, s32
	s_addc_u32 s97, s53, 0
	s_waitcnt lgkmcnt(0)
	s_barrier
	v_cvt_pk_bf16_f32 v154, v154, v155
	v_cvt_pk_bf16_f32 v155, v156, v157
	v_cvt_pk_bf16_f32 v156, v158, v159
	v_cvt_pk_bf16_f32 v157, v160, v161
	v_cvt_pk_bf16_f32 v162, v162, v163
	v_cvt_pk_bf16_f32 v163, v164, v165
	v_cvt_pk_bf16_f32 v164, v166, v167
	v_cvt_pk_bf16_f32 v165, v168, v169
	global_store_dwordx4 v224, v[154:157], s[52:53]
	global_store_dwordx4 v224, v[162:165], s[96:97]
	s_branch .Lwc0_done
.Lwc0_tail3:
	s_waitcnt vmcnt(0)
	v_readlane_b32 s52, v229, 24
	v_readlane_b32 s53, v229, 25
	v_readlane_b32 s32, v229, 26
	v_readlane_b32 s35, v229, 27
	ds_write_b32 v218, v202 offset:0
	ds_write_b32 v218, v203 offset:4
	ds_write_b32 v218, v204 offset:8
	ds_write_b32 v218, v205 offset:12
	ds_write_b32 v218, v206 offset:4160
	ds_write_b32 v218, v207 offset:4164
	ds_write_b32 v218, v208 offset:4168
	ds_write_b32 v218, v209 offset:4172
	ds_write_b32 v218, v210 offset:8320
	ds_write_b32 v218, v211 offset:8324
	ds_write_b32 v218, v212 offset:8328
	ds_write_b32 v218, v213 offset:8332
	ds_write_b32 v218, v214 offset:12480
	ds_write_b32 v218, v215 offset:12484
	ds_write_b32 v218, v216 offset:12488
	ds_write_b32 v218, v217 offset:12492
	v_mad_u32_u24 v224, v227, s35, v228
	s_waitcnt lgkmcnt(0)
	s_barrier
	ds_read2_b32 v[202:203], v219 offset1:65
	ds_read2_b32 v[204:205], v219 offset0:130 offset1:195
	ds_read2_b32 v[206:207], v220 offset0:4 offset1:69
	ds_read2_b32 v[208:209], v220 offset0:134 offset1:199
	ds_read2_b32 v[210:211], v221 offset1:65
	ds_read2_b32 v[212:213], v221 offset0:130 offset1:195
	ds_read2_b32 v[214:215], v222 offset0:4 offset1:69
	ds_read2_b32 v[216:217], v222 offset0:134 offset1:199
	s_add_u32 s96, s52, s32
	s_addc_u32 s97, s53, 0
	s_waitcnt lgkmcnt(0)
	s_barrier
	v_cvt_pk_bf16_f32 v202, v202, v203
	v_cvt_pk_bf16_f32 v203, v204, v205
	v_cvt_pk_bf16_f32 v204, v206, v207
	v_cvt_pk_bf16_f32 v205, v208, v209
	v_cvt_pk_bf16_f32 v210, v210, v211
	v_cvt_pk_bf16_f32 v211, v212, v213
	v_cvt_pk_bf16_f32 v212, v214, v215
	v_cvt_pk_bf16_f32 v213, v216, v217
	global_store_dwordx4 v224, v[202:205], s[52:53]
	global_store_dwordx4 v224, v[210:213], s[96:97]
	v_readlane_b32 s52, v229, 8
	v_readlane_b32 s53, v229, 9
	v_readlane_b32 s32, v229, 10
	v_readlane_b32 s35, v229, 11
	ds_write_b32 v218, v138 offset:0
	ds_write_b32 v218, v139 offset:4
	ds_write_b32 v218, v140 offset:8
	ds_write_b32 v218, v141 offset:12
	ds_write_b32 v218, v142 offset:4160
	ds_write_b32 v218, v143 offset:4164
	ds_write_b32 v218, v144 offset:4168
	ds_write_b32 v218, v145 offset:4172
	ds_write_b32 v218, v146 offset:8320
	ds_write_b32 v218, v147 offset:8324
	ds_write_b32 v218, v148 offset:8328
	ds_write_b32 v218, v149 offset:8332
	ds_write_b32 v218, v150 offset:12480
	ds_write_b32 v218, v151 offset:12484
	ds_write_b32 v218, v152 offset:12488
	ds_write_b32 v218, v153 offset:12492
	v_mad_u32_u24 v224, v227, s35, v228
	s_waitcnt lgkmcnt(0)
	s_barrier
	ds_read2_b32 v[138:139], v219 offset1:65
	ds_read2_b32 v[140:141], v219 offset0:130 offset1:195
	ds_read2_b32 v[142:143], v220 offset0:4 offset1:69
	ds_read2_b32 v[144:145], v220 offset0:134 offset1:199
	ds_read2_b32 v[146:147], v221 offset1:65
	ds_read2_b32 v[148:149], v221 offset0:130 offset1:195
	ds_read2_b32 v[150:151], v222 offset0:4 offset1:69
	ds_read2_b32 v[152:153], v222 offset0:134 offset1:199
	s_add_u32 s96, s52, s32
	s_addc_u32 s97, s53, 0
	s_waitcnt lgkmcnt(0)
	s_barrier
	v_cvt_pk_bf16_f32 v138, v138, v139
	v_cvt_pk_bf16_f32 v139, v140, v141
	v_cvt_pk_bf16_f32 v140, v142, v143
	v_cvt_pk_bf16_f32 v141, v144, v145
	v_cvt_pk_bf16_f32 v146, v146, v147
	v_cvt_pk_bf16_f32 v147, v148, v149
	v_cvt_pk_bf16_f32 v148, v150, v151
	v_cvt_pk_bf16_f32 v149, v152, v153
	global_store_dwordx4 v224, v[138:141], s[52:53]
	global_store_dwordx4 v224, v[146:149], s[96:97]
	v_readlane_b32 s52, v229, 12
	v_readlane_b32 s53, v229, 13
	v_readlane_b32 s32, v229, 14
	v_readlane_b32 s35, v229, 15
	ds_write_b32 v218, v154 offset:0
	ds_write_b32 v218, v155 offset:4
	ds_write_b32 v218, v156 offset:8
	ds_write_b32 v218, v157 offset:12
	ds_write_b32 v218, v158 offset:4160
	ds_write_b32 v218, v159 offset:4164
	ds_write_b32 v218, v160 offset:4168
	ds_write_b32 v218, v161 offset:4172
	ds_write_b32 v218, v162 offset:8320
	ds_write_b32 v218, v163 offset:8324
	ds_write_b32 v218, v164 offset:8328
	ds_write_b32 v218, v165 offset:8332
	ds_write_b32 v218, v166 offset:12480
	ds_write_b32 v218, v167 offset:12484
	ds_write_b32 v218, v168 offset:12488
	ds_write_b32 v218, v169 offset:12492
	v_mad_u32_u24 v224, v227, s35, v228
	s_waitcnt lgkmcnt(0)
	s_barrier
	ds_read2_b32 v[154:155], v219 offset1:65
	ds_read2_b32 v[156:157], v219 offset0:130 offset1:195
	ds_read2_b32 v[158:159], v220 offset0:4 offset1:69
	ds_read2_b32 v[160:161], v220 offset0:134 offset1:199
	ds_read2_b32 v[162:163], v221 offset1:65
	ds_read2_b32 v[164:165], v221 offset0:130 offset1:195
	ds_read2_b32 v[166:167], v222 offset0:4 offset1:69
	ds_read2_b32 v[168:169], v222 offset0:134 offset1:199
	s_add_u32 s96, s52, s32
	s_addc_u32 s97, s53, 0
	s_waitcnt lgkmcnt(0)
	s_barrier
	v_cvt_pk_bf16_f32 v154, v154, v155
	v_cvt_pk_bf16_f32 v155, v156, v157
	v_cvt_pk_bf16_f32 v156, v158, v159
	v_cvt_pk_bf16_f32 v157, v160, v161
	v_cvt_pk_bf16_f32 v162, v162, v163
	v_cvt_pk_bf16_f32 v163, v164, v165
	v_cvt_pk_bf16_f32 v164, v166, v167
	v_cvt_pk_bf16_f32 v165, v168, v169
	global_store_dwordx4 v224, v[154:157], s[52:53]
	global_store_dwordx4 v224, v[162:165], s[96:97]
	v_readlane_b32 s52, v229, 16
	v_readlane_b32 s53, v229, 17
	v_readlane_b32 s32, v229, 18
	v_readlane_b32 s35, v229, 19
	ds_write_b32 v218, v170 offset:0
	ds_write_b32 v218, v171 offset:4
	ds_write_b32 v218, v172 offset:8
	ds_write_b32 v218, v173 offset:12
	ds_write_b32 v218, v174 offset:4160
	ds_write_b32 v218, v175 offset:4164
	ds_write_b32 v218, v176 offset:4168
	ds_write_b32 v218, v177 offset:4172
	ds_write_b32 v218, v178 offset:8320
	ds_write_b32 v218, v179 offset:8324
	ds_write_b32 v218, v180 offset:8328
	ds_write_b32 v218, v181 offset:8332
	ds_write_b32 v218, v182 offset:12480
	ds_write_b32 v218, v183 offset:12484
	ds_write_b32 v218, v184 offset:12488
	ds_write_b32 v218, v185 offset:12492
	v_mad_u32_u24 v224, v227, s35, v228
	s_waitcnt lgkmcnt(0)
	s_barrier
	ds_read2_b32 v[170:171], v219 offset1:65
	ds_read2_b32 v[172:173], v219 offset0:130 offset1:195
	ds_read2_b32 v[174:175], v220 offset0:4 offset1:69
	ds_read2_b32 v[176:177], v220 offset0:134 offset1:199
	ds_read2_b32 v[178:179], v221 offset1:65
	ds_read2_b32 v[180:181], v221 offset0:130 offset1:195
	ds_read2_b32 v[182:183], v222 offset0:4 offset1:69
	ds_read2_b32 v[184:185], v222 offset0:134 offset1:199
	s_add_u32 s96, s52, s32
	s_addc_u32 s97, s53, 0
	s_waitcnt lgkmcnt(0)
	s_barrier
	v_cvt_pk_bf16_f32 v170, v170, v171
	v_cvt_pk_bf16_f32 v171, v172, v173
	v_cvt_pk_bf16_f32 v172, v174, v175
	v_cvt_pk_bf16_f32 v173, v176, v177
	v_cvt_pk_bf16_f32 v178, v178, v179
	v_cvt_pk_bf16_f32 v179, v180, v181
	v_cvt_pk_bf16_f32 v180, v182, v183
	v_cvt_pk_bf16_f32 v181, v184, v185
	global_store_dwordx4 v224, v[170:173], s[52:53]
	global_store_dwordx4 v224, v[178:181], s[96:97]
	s_branch .Lwc0_done
.Lwc0_tail4:
	s_waitcnt vmcnt(0)
	v_readlane_b32 s52, v229, 8
	v_readlane_b32 s53, v229, 9
	v_readlane_b32 s32, v229, 10
	v_readlane_b32 s35, v229, 11
	ds_write_b32 v218, v138 offset:0
	ds_write_b32 v218, v139 offset:4
	ds_write_b32 v218, v140 offset:8
	ds_write_b32 v218, v141 offset:12
	ds_write_b32 v218, v142 offset:4160
	ds_write_b32 v218, v143 offset:4164
	ds_write_b32 v218, v144 offset:4168
	ds_write_b32 v218, v145 offset:4172
	ds_write_b32 v218, v146 offset:8320
	ds_write_b32 v218, v147 offset:8324
	ds_write_b32 v218, v148 offset:8328
	ds_write_b32 v218, v149 offset:8332
	ds_write_b32 v218, v150 offset:12480
	ds_write_b32 v218, v151 offset:12484
	ds_write_b32 v218, v152 offset:12488
	ds_write_b32 v218, v153 offset:12492
	v_mad_u32_u24 v224, v227, s35, v228
	s_waitcnt lgkmcnt(0)
	s_barrier
	ds_read2_b32 v[138:139], v219 offset1:65
	ds_read2_b32 v[140:141], v219 offset0:130 offset1:195
	ds_read2_b32 v[142:143], v220 offset0:4 offset1:69
	ds_read2_b32 v[144:145], v220 offset0:134 offset1:199
	ds_read2_b32 v[146:147], v221 offset1:65
	ds_read2_b32 v[148:149], v221 offset0:130 offset1:195
	ds_read2_b32 v[150:151], v222 offset0:4 offset1:69
	ds_read2_b32 v[152:153], v222 offset0:134 offset1:199
	s_add_u32 s96, s52, s32
	s_addc_u32 s97, s53, 0
	s_waitcnt lgkmcnt(0)
	s_barrier
	v_cvt_pk_bf16_f32 v138, v138, v139
	v_cvt_pk_bf16_f32 v139, v140, v141
	v_cvt_pk_bf16_f32 v140, v142, v143
	v_cvt_pk_bf16_f32 v141, v144, v145
	v_cvt_pk_bf16_f32 v146, v146, v147
	v_cvt_pk_bf16_f32 v147, v148, v149
	v_cvt_pk_bf16_f32 v148, v150, v151
	v_cvt_pk_bf16_f32 v149, v152, v153
	global_store_dwordx4 v224, v[138:141], s[52:53]
	global_store_dwordx4 v224, v[146:149], s[96:97]
	v_readlane_b32 s52, v229, 12
	v_readlane_b32 s53, v229, 13
	v_readlane_b32 s32, v229, 14
	v_readlane_b32 s35, v229, 15
	ds_write_b32 v218, v154 offset:0
	ds_write_b32 v218, v155 offset:4
	ds_write_b32 v218, v156 offset:8
	ds_write_b32 v218, v157 offset:12
	ds_write_b32 v218, v158 offset:4160
	ds_write_b32 v218, v159 offset:4164
	ds_write_b32 v218, v160 offset:4168
	ds_write_b32 v218, v161 offset:4172
	ds_write_b32 v218, v162 offset:8320
	ds_write_b32 v218, v163 offset:8324
	ds_write_b32 v218, v164 offset:8328
	ds_write_b32 v218, v165 offset:8332
	ds_write_b32 v218, v166 offset:12480
	ds_write_b32 v218, v167 offset:12484
	ds_write_b32 v218, v168 offset:12488
	ds_write_b32 v218, v169 offset:12492
	v_mad_u32_u24 v224, v227, s35, v228
	s_waitcnt lgkmcnt(0)
	s_barrier
	ds_read2_b32 v[154:155], v219 offset1:65
	ds_read2_b32 v[156:157], v219 offset0:130 offset1:195
	ds_read2_b32 v[158:159], v220 offset0:4 offset1:69
	ds_read2_b32 v[160:161], v220 offset0:134 offset1:199
	ds_read2_b32 v[162:163], v221 offset1:65
	ds_read2_b32 v[164:165], v221 offset0:130 offset1:195
	ds_read2_b32 v[166:167], v222 offset0:4 offset1:69
	ds_read2_b32 v[168:169], v222 offset0:134 offset1:199
	s_add_u32 s96, s52, s32
	s_addc_u32 s97, s53, 0
	s_waitcnt lgkmcnt(0)
	s_barrier
	v_cvt_pk_bf16_f32 v154, v154, v155
	v_cvt_pk_bf16_f32 v155, v156, v157
	v_cvt_pk_bf16_f32 v156, v158, v159
	v_cvt_pk_bf16_f32 v157, v160, v161
	v_cvt_pk_bf16_f32 v162, v162, v163
	v_cvt_pk_bf16_f32 v163, v164, v165
	v_cvt_pk_bf16_f32 v164, v166, v167
	v_cvt_pk_bf16_f32 v165, v168, v169
	global_store_dwordx4 v224, v[154:157], s[52:53]
	global_store_dwordx4 v224, v[162:165], s[96:97]
	v_readlane_b32 s52, v229, 16
	v_readlane_b32 s53, v229, 17
	v_readlane_b32 s32, v229, 18
	v_readlane_b32 s35, v229, 19
	ds_write_b32 v218, v170 offset:0
	ds_write_b32 v218, v171 offset:4
	ds_write_b32 v218, v172 offset:8
	ds_write_b32 v218, v173 offset:12
	ds_write_b32 v218, v174 offset:4160
	ds_write_b32 v218, v175 offset:4164
	ds_write_b32 v218, v176 offset:4168
	ds_write_b32 v218, v177 offset:4172
	ds_write_b32 v218, v178 offset:8320
	ds_write_b32 v218, v179 offset:8324
	ds_write_b32 v218, v180 offset:8328
	ds_write_b32 v218, v181 offset:8332
	ds_write_b32 v218, v182 offset:12480
	ds_write_b32 v218, v183 offset:12484
	ds_write_b32 v218, v184 offset:12488
	ds_write_b32 v218, v185 offset:12492
	v_mad_u32_u24 v224, v227, s35, v228
	s_waitcnt lgkmcnt(0)
	s_barrier
	ds_read2_b32 v[170:171], v219 offset1:65
	ds_read2_b32 v[172:173], v219 offset0:130 offset1:195
	ds_read2_b32 v[174:175], v220 offset0:4 offset1:69
	ds_read2_b32 v[176:177], v220 offset0:134 offset1:199
	ds_read2_b32 v[178:179], v221 offset1:65
	ds_read2_b32 v[180:181], v221 offset0:130 offset1:195
	ds_read2_b32 v[182:183], v222 offset0:4 offset1:69
	ds_read2_b32 v[184:185], v222 offset0:134 offset1:199
	s_add_u32 s96, s52, s32
	s_addc_u32 s97, s53, 0
	s_waitcnt lgkmcnt(0)
	s_barrier
	v_cvt_pk_bf16_f32 v170, v170, v171
	v_cvt_pk_bf16_f32 v171, v172, v173
	v_cvt_pk_bf16_f32 v172, v174, v175
	v_cvt_pk_bf16_f32 v173, v176, v177
	v_cvt_pk_bf16_f32 v178, v178, v179
	v_cvt_pk_bf16_f32 v179, v180, v181
	v_cvt_pk_bf16_f32 v180, v182, v183
	v_cvt_pk_bf16_f32 v181, v184, v185
	global_store_dwordx4 v224, v[170:173], s[52:53]
	global_store_dwordx4 v224, v[178:181], s[96:97]
	v_readlane_b32 s52, v229, 20
	v_readlane_b32 s53, v229, 21
	v_readlane_b32 s32, v229, 22
	v_readlane_b32 s35, v229, 23
	ds_write_b32 v218, v186 offset:0
	ds_write_b32 v218, v187 offset:4
	ds_write_b32 v218, v188 offset:8
	ds_write_b32 v218, v189 offset:12
	ds_write_b32 v218, v190 offset:4160
	ds_write_b32 v218, v191 offset:4164
	ds_write_b32 v218, v192 offset:4168
	ds_write_b32 v218, v193 offset:4172
	ds_write_b32 v218, v194 offset:8320
	ds_write_b32 v218, v195 offset:8324
	ds_write_b32 v218, v196 offset:8328
	ds_write_b32 v218, v197 offset:8332
	ds_write_b32 v218, v198 offset:12480
	ds_write_b32 v218, v199 offset:12484
	ds_write_b32 v218, v200 offset:12488
	ds_write_b32 v218, v201 offset:12492
	v_mad_u32_u24 v224, v227, s35, v228
	s_waitcnt lgkmcnt(0)
	s_barrier
	ds_read2_b32 v[186:187], v219 offset1:65
	ds_read2_b32 v[188:189], v219 offset0:130 offset1:195
	ds_read2_b32 v[190:191], v220 offset0:4 offset1:69
	ds_read2_b32 v[192:193], v220 offset0:134 offset1:199
	ds_read2_b32 v[194:195], v221 offset1:65
	ds_read2_b32 v[196:197], v221 offset0:130 offset1:195
	ds_read2_b32 v[198:199], v222 offset0:4 offset1:69
	ds_read2_b32 v[200:201], v222 offset0:134 offset1:199
	s_add_u32 s96, s52, s32
	s_addc_u32 s97, s53, 0
	s_waitcnt lgkmcnt(0)
	s_barrier
	v_cvt_pk_bf16_f32 v186, v186, v187
	v_cvt_pk_bf16_f32 v187, v188, v189
	v_cvt_pk_bf16_f32 v188, v190, v191
	v_cvt_pk_bf16_f32 v189, v192, v193
	v_cvt_pk_bf16_f32 v194, v194, v195
	v_cvt_pk_bf16_f32 v195, v196, v197
	v_cvt_pk_bf16_f32 v196, v198, v199
	v_cvt_pk_bf16_f32 v197, v200, v201
	global_store_dwordx4 v224, v[186:189], s[52:53]
	global_store_dwordx4 v224, v[194:197], s[96:97]
	s_branch .Lwc0_done

.Lwc0_p3:
	s_waitcnt vmcnt(0)
	v_readlane_b32 s52, v229, 8
	v_readlane_b32 s53, v229, 9
	v_readlane_b32 s32, v229, 10
	v_readlane_b32 s35, v229, 11
	ds_write_b32 v218, v138 offset:0
	ds_write_b32 v218, v139 offset:4
	ds_write_b32 v218, v140 offset:8
	ds_write_b32 v218, v141 offset:12
	ds_write_b32 v218, v142 offset:4160
	ds_write_b32 v218, v143 offset:4164
	ds_write_b32 v218, v144 offset:4168
	ds_write_b32 v218, v145 offset:4172
	ds_write_b32 v218, v146 offset:8320
	ds_write_b32 v218, v147 offset:8324
	ds_write_b32 v218, v148 offset:8328
	ds_write_b32 v218, v149 offset:8332
	ds_write_b32 v218, v150 offset:12480
	ds_write_b32 v218, v151 offset:12484
	ds_write_b32 v218, v152 offset:12488
	ds_write_b32 v218, v153 offset:12492
	v_mad_u32_u24 v224, v227, s35, v228
	s_waitcnt lgkmcnt(0)
	s_barrier
	ds_read2_b32 v[138:139], v219 offset1:65
	ds_read2_b32 v[140:141], v219 offset0:130 offset1:195
	ds_read2_b32 v[142:143], v220 offset0:4 offset1:69
	ds_read2_b32 v[144:145], v220 offset0:134 offset1:199
	ds_read2_b32 v[146:147], v221 offset1:65
	ds_read2_b32 v[148:149], v221 offset0:130 offset1:195
	ds_read2_b32 v[150:151], v222 offset0:4 offset1:69
	ds_read2_b32 v[152:153], v222 offset0:134 offset1:199
	s_add_u32 s96, s52, s32
	s_addc_u32 s97, s53, 0
	s_waitcnt lgkmcnt(0)
	s_barrier
	v_cvt_pk_bf16_f32 v138, v138, v139
	v_cvt_pk_bf16_f32 v139, v140, v141
	v_cvt_pk_bf16_f32 v140, v142, v143
	v_cvt_pk_bf16_f32 v141, v144, v145
	v_cvt_pk_bf16_f32 v146, v146, v147
	v_cvt_pk_bf16_f32 v147, v148, v149
	v_cvt_pk_bf16_f32 v148, v150, v151
	v_cvt_pk_bf16_f32 v149, v152, v153
	global_store_dwordx4 v224, v[138:141], s[52:53]
	global_store_dwordx4 v224, v[146:149], s[96:97]
	v_readlane_b32 s52, v229, 12
	v_readlane_b32 s53, v229, 13
	v_readlane_b32 s32, v229, 14
	v_readlane_b32 s35, v229, 15
	ds_write_b32 v218, v154 offset:0
	ds_write_b32 v218, v155 offset:4
	ds_write_b32 v218, v156 offset:8
	ds_write_b32 v218, v157 offset:12
	ds_write_b32 v218, v158 offset:4160
	ds_write_b32 v218, v159 offset:4164
	ds_write_b32 v218, v160 offset:4168
	ds_write_b32 v218, v161 offset:4172
	ds_write_b32 v218, v162 offset:8320
	ds_write_b32 v218, v163 offset:8324
	ds_write_b32 v218, v164 offset:8328
	ds_write_b32 v218, v165 offset:8332
	ds_write_b32 v218, v166 offset:12480
	ds_write_b32 v218, v167 offset:12484
	ds_write_b32 v218, v168 offset:12488
	ds_write_b32 v218, v169 offset:12492
	v_mad_u32_u24 v224, v227, s35, v228
	s_waitcnt lgkmcnt(0)
	s_barrier
	ds_read2_b32 v[154:155], v219 offset1:65
	ds_read2_b32 v[156:157], v219 offset0:130 offset1:195
	ds_read2_b32 v[158:159], v220 offset0:4 offset1:69
	ds_read2_b32 v[160:161], v220 offset0:134 offset1:199
	ds_read2_b32 v[162:163], v221 offset1:65
	ds_read2_b32 v[164:165], v221 offset0:130 offset1:195
	ds_read2_b32 v[166:167], v222 offset0:4 offset1:69
	ds_read2_b32 v[168:169], v222 offset0:134 offset1:199
	s_add_u32 s96, s52, s32
	s_addc_u32 s97, s53, 0
	s_waitcnt lgkmcnt(0)
	s_barrier
	v_cvt_pk_bf16_f32 v154, v154, v155
	v_cvt_pk_bf16_f32 v155, v156, v157
	v_cvt_pk_bf16_f32 v156, v158, v159
	v_cvt_pk_bf16_f32 v157, v160, v161
	v_cvt_pk_bf16_f32 v162, v162, v163
	v_cvt_pk_bf16_f32 v163, v164, v165
	v_cvt_pk_bf16_f32 v164, v166, v167
	v_cvt_pk_bf16_f32 v165, v168, v169
	global_store_dwordx4 v224, v[154:157], s[52:53]
	global_store_dwordx4 v224, v[162:165], s[96:97]
	v_readlane_b32 s52, v229, 16
	v_readlane_b32 s53, v229, 17
	v_readlane_b32 s32, v229, 18
	v_readlane_b32 s35, v229, 19
	ds_write_b32 v218, v170 offset:0
	ds_write_b32 v218, v171 offset:4
	ds_write_b32 v218, v172 offset:8
	ds_write_b32 v218, v173 offset:12
	ds_write_b32 v218, v174 offset:4160
	ds_write_b32 v218, v175 offset:4164
	ds_write_b32 v218, v176 offset:4168
	ds_write_b32 v218, v177 offset:4172
	ds_write_b32 v218, v178 offset:8320
	ds_write_b32 v218, v179 offset:8324
	ds_write_b32 v218, v180 offset:8328
	ds_write_b32 v218, v181 offset:8332
	ds_write_b32 v218, v182 offset:12480
	ds_write_b32 v218, v183 offset:12484
	ds_write_b32 v218, v184 offset:12488
	ds_write_b32 v218, v185 offset:12492
	v_mad_u32_u24 v224, v227, s35, v228
	s_waitcnt lgkmcnt(0)
	s_barrier
	ds_read2_b32 v[170:171], v219 offset1:65
	ds_read2_b32 v[172:173], v219 offset0:130 offset1:195
	ds_read2_b32 v[174:175], v220 offset0:4 offset1:69
	ds_read2_b32 v[176:177], v220 offset0:134 offset1:199
	ds_read2_b32 v[178:179], v221 offset1:65
	ds_read2_b32 v[180:181], v221 offset0:130 offset1:195
	ds_read2_b32 v[182:183], v222 offset0:4 offset1:69
	ds_read2_b32 v[184:185], v222 offset0:134 offset1:199
	s_add_u32 s96, s52, s32
	s_addc_u32 s97, s53, 0
	s_waitcnt lgkmcnt(0)
	s_barrier
	v_cvt_pk_bf16_f32 v170, v170, v171
	v_cvt_pk_bf16_f32 v171, v172, v173
	v_cvt_pk_bf16_f32 v172, v174, v175
	v_cvt_pk_bf16_f32 v173, v176, v177
	v_cvt_pk_bf16_f32 v178, v178, v179
	v_cvt_pk_bf16_f32 v179, v180, v181
	v_cvt_pk_bf16_f32 v180, v182, v183
	v_cvt_pk_bf16_f32 v181, v184, v185
	global_store_dwordx4 v224, v[170:173], s[52:53]
	global_store_dwordx4 v224, v[178:181], s[96:97]
	s_branch .Lwc0_done
.Lwc0_p2:
	s_waitcnt vmcnt(0)
	v_readlane_b32 s52, v229, 8
	v_readlane_b32 s53, v229, 9
	v_readlane_b32 s32, v229, 10
	v_readlane_b32 s35, v229, 11
	ds_write_b32 v218, v138 offset:0
	ds_write_b32 v218, v139 offset:4
	ds_write_b32 v218, v140 offset:8
	ds_write_b32 v218, v141 offset:12
	ds_write_b32 v218, v142 offset:4160
	ds_write_b32 v218, v143 offset:4164
	ds_write_b32 v218, v144 offset:4168
	ds_write_b32 v218, v145 offset:4172
	ds_write_b32 v218, v146 offset:8320
	ds_write_b32 v218, v147 offset:8324
	ds_write_b32 v218, v148 offset:8328
	ds_write_b32 v218, v149 offset:8332
	ds_write_b32 v218, v150 offset:12480
	ds_write_b32 v218, v151 offset:12484
	ds_write_b32 v218, v152 offset:12488
	ds_write_b32 v218, v153 offset:12492
	v_mad_u32_u24 v224, v227, s35, v228
	s_waitcnt lgkmcnt(0)
	s_barrier
	ds_read2_b32 v[138:139], v219 offset1:65
	ds_read2_b32 v[140:141], v219 offset0:130 offset1:195
	ds_read2_b32 v[142:143], v220 offset0:4 offset1:69
	ds_read2_b32 v[144:145], v220 offset0:134 offset1:199
	ds_read2_b32 v[146:147], v221 offset1:65
	ds_read2_b32 v[148:149], v221 offset0:130 offset1:195
	ds_read2_b32 v[150:151], v222 offset0:4 offset1:69
	ds_read2_b32 v[152:153], v222 offset0:134 offset1:199
	s_add_u32 s96, s52, s32
	s_addc_u32 s97, s53, 0
	s_waitcnt lgkmcnt(0)
	s_barrier
	v_cvt_pk_bf16_f32 v138, v138, v139
	v_cvt_pk_bf16_f32 v139, v140, v141
	v_cvt_pk_bf16_f32 v140, v142, v143
	v_cvt_pk_bf16_f32 v141, v144, v145
	v_cvt_pk_bf16_f32 v146, v146, v147
	v_cvt_pk_bf16_f32 v147, v148, v149
	v_cvt_pk_bf16_f32 v148, v150, v151
	v_cvt_pk_bf16_f32 v149, v152, v153
	global_store_dwordx4 v224, v[138:141], s[52:53]
	global_store_dwordx4 v224, v[146:149], s[96:97]
	v_readlane_b32 s52, v229, 12
	v_readlane_b32 s53, v229, 13
	v_readlane_b32 s32, v229, 14
	v_readlane_b32 s35, v229, 15
	ds_write_b32 v218, v154 offset:0
	ds_write_b32 v218, v155 offset:4
	ds_write_b32 v218, v156 offset:8
	ds_write_b32 v218, v157 offset:12
	ds_write_b32 v218, v158 offset:4160
	ds_write_b32 v218, v159 offset:4164
	ds_write_b32 v218, v160 offset:4168
	ds_write_b32 v218, v161 offset:4172
	ds_write_b32 v218, v162 offset:8320
	ds_write_b32 v218, v163 offset:8324
	ds_write_b32 v218, v164 offset:8328
	ds_write_b32 v218, v165 offset:8332
	ds_write_b32 v218, v166 offset:12480
	ds_write_b32 v218, v167 offset:12484
	ds_write_b32 v218, v168 offset:12488
	ds_write_b32 v218, v169 offset:12492
	v_mad_u32_u24 v224, v227, s35, v228
	s_waitcnt lgkmcnt(0)
	s_barrier
	ds_read2_b32 v[154:155], v219 offset1:65
	ds_read2_b32 v[156:157], v219 offset0:130 offset1:195
	ds_read2_b32 v[158:159], v220 offset0:4 offset1:69
	ds_read2_b32 v[160:161], v220 offset0:134 offset1:199
	ds_read2_b32 v[162:163], v221 offset1:65
	ds_read2_b32 v[164:165], v221 offset0:130 offset1:195
	ds_read2_b32 v[166:167], v222 offset0:4 offset1:69
	ds_read2_b32 v[168:169], v222 offset0:134 offset1:199
	s_add_u32 s96, s52, s32
	s_addc_u32 s97, s53, 0
	s_waitcnt lgkmcnt(0)
	s_barrier
	v_cvt_pk_bf16_f32 v154, v154, v155
	v_cvt_pk_bf16_f32 v155, v156, v157
	v_cvt_pk_bf16_f32 v156, v158, v159
	v_cvt_pk_bf16_f32 v157, v160, v161
	v_cvt_pk_bf16_f32 v162, v162, v163
	v_cvt_pk_bf16_f32 v163, v164, v165
	v_cvt_pk_bf16_f32 v164, v166, v167
	v_cvt_pk_bf16_f32 v165, v168, v169
	global_store_dwordx4 v224, v[154:157], s[52:53]
	global_store_dwordx4 v224, v[162:165], s[96:97]
	s_branch .Lwc0_done
.Lwc0_p1:
	s_waitcnt vmcnt(0)
	v_readlane_b32 s52, v229, 8
	v_readlane_b32 s53, v229, 9
	v_readlane_b32 s32, v229, 10
	v_readlane_b32 s35, v229, 11
	ds_write_b32 v218, v138 offset:0
	ds_write_b32 v218, v139 offset:4
	ds_write_b32 v218, v140 offset:8
	ds_write_b32 v218, v141 offset:12
	ds_write_b32 v218, v142 offset:4160
	ds_write_b32 v218, v143 offset:4164
	ds_write_b32 v218, v144 offset:4168
	ds_write_b32 v218, v145 offset:4172
	ds_write_b32 v218, v146 offset:8320
	ds_write_b32 v218, v147 offset:8324
	ds_write_b32 v218, v148 offset:8328
	ds_write_b32 v218, v149 offset:8332
	ds_write_b32 v218, v150 offset:12480
	ds_write_b32 v218, v151 offset:12484
	ds_write_b32 v218, v152 offset:12488
	ds_write_b32 v218, v153 offset:12492
	v_mad_u32_u24 v224, v227, s35, v228
	s_waitcnt lgkmcnt(0)
	s_barrier
	ds_read2_b32 v[138:139], v219 offset1:65
	ds_read2_b32 v[140:141], v219 offset0:130 offset1:195
	ds_read2_b32 v[142:143], v220 offset0:4 offset1:69
	ds_read2_b32 v[144:145], v220 offset0:134 offset1:199
	ds_read2_b32 v[146:147], v221 offset1:65
	ds_read2_b32 v[148:149], v221 offset0:130 offset1:195
	ds_read2_b32 v[150:151], v222 offset0:4 offset1:69
	ds_read2_b32 v[152:153], v222 offset0:134 offset1:199
	s_add_u32 s96, s52, s32
	s_addc_u32 s97, s53, 0
	s_waitcnt lgkmcnt(0)
	s_barrier
	v_cvt_pk_bf16_f32 v138, v138, v139
	v_cvt_pk_bf16_f32 v139, v140, v141
	v_cvt_pk_bf16_f32 v140, v142, v143
	v_cvt_pk_bf16_f32 v141, v144, v145
	v_cvt_pk_bf16_f32 v146, v146, v147
	v_cvt_pk_bf16_f32 v147, v148, v149
	v_cvt_pk_bf16_f32 v148, v150, v151
	v_cvt_pk_bf16_f32 v149, v152, v153
	global_store_dwordx4 v224, v[138:141], s[52:53]
	global_store_dwordx4 v224, v[146:149], s[96:97]

.Lxbi3_skip:
	s_barrier
	v_readlane_b32 s99, v242, 0
	s_nop 0
	s_sub_u32 s99, s99, 0x100
	s_cmpk_lt_u32 s99, 96
	s_cbranch_scc0 .Lwcm_skip
	s_add_u32 s100, s99, 0x280
	s_movk_i32 s23, 96
	s_movk_i32 s22, 0xbc0
	s_waitcnt vmcnt(0) lgkmcnt(0)
	s_barrier
	v_readlane_b32 s0, v242, 42
	v_readlane_b32 s1, v242, 43
	v_readlane_b32 s12, v242, 3
	v_readlane_b32 s13, v242, 4
	v_lshrrev_b32_e32 v233, 4, v137
	v_and_b32_e32 v234, 15, v137
	v_lshlrev_b32_e32 v234, 2, v234
	s_sub_u32 s0, s0, 0x118
	s_subb_u32 s1, s1, 0
	v_lshrrev_b32_e32 v235, 3, v137
	v_and_b32_e32 v236, 7, v137
	v_mul_u32_u24_e32 v226, 65, v233
	v_mul_u32_u24_e32 v227, 0x208, v236
	v_add_u32_e32 v226, v226, v234
	v_add_u32_e32 v227, v227, v235
	v_lshlrev_b32_e32 v226, 2, v226
	v_lshlrev_b32_e32 v227, 2, v227
	v_lshlrev_b32_e32 v234, 2, v234
	v_lshlrev_b32_e32 v236, 4, v236
	v_add_u32_e32 v228, 0x400, v227
	v_add_u32_e32 v229, 0x80, v227
	v_add_u32_e32 v230, 0x480, v227
	s_cmp_ge_u32 s100, s22
	s_cbranch_scc1 .Lwcm0_done
	s_cmpk_ge_u32 s100, 0x900
	s_cbranch_scc1 .Lwcm0_t3_1
	s_cmpk_ge_u32 s100, 0x380
	s_cbranch_scc1 .Lwcm0_t2_1
	s_cmpk_ge_u32 s100, 0x280
	s_cbranch_scc1 .Lwcm0_t1_1
	s_movk_i32 s14, 0x78
	s_sub_u32 s99, s100, 0
	s_mul_i32 s44, s99, 0x66667
	s_lshr_b32 s44, s44, 24
	s_mul_i32 s36, s44, 40
	s_sub_u32 s99, s99, s36
	s_mul_i32 s38, s44, 0xa0000
	s_lshl_b32 s36, s99, 8
	s_add_u32 s38, s38, s36
	s_add_u32 s38, s38, 0x0
	s_lshl_b32 s36, s99, 6
	s_mov_b32 s32, 0x10000
	s_mul_i32 s36, s36, 0x800
	s_lshl_b32 s44, s44, 7
	s_add_u32 s36, s36, s44
	s_add_u32 s36, s36, 0x0
	s_mov_b32 s37, 0x28000
	s_movk_i32 s44, 0x800
	s_mov_b32 s99, 0x2800
	s_branch .Lwcm0_tj_1
.Lwcm0_t1_1:
	s_movk_i32 s14, 0x80
	s_sub_u32 s99, s100, 640
	s_mul_i32 s44, s99, 0x100000
	s_lshr_b32 s44, s44, 24
	s_mul_i32 s36, s44, 16
	s_sub_u32 s99, s99, s36
	s_mul_i32 s38, s44, 0x40000
	s_lshl_b32 s36, s99, 8
	s_add_u32 s38, s38, s36
	s_add_u32 s38, s38, 0x0
	s_lshl_b32 s36, s99, 6
	s_mov_b32 s32, 0x10000
	s_mul_i32 s36, s36, 0x800
	s_lshl_b32 s44, s44, 7
	s_add_u32 s36, s36, s44
	s_add_u32 s36, s36, 0xa00000
	s_mov_b32 s37, 0x10000
	s_movk_i32 s44, 0x800
	s_mov_b32 s99, 0x1000
	s_branch .Lwcm0_tj_1
.Lwcm0_t2_1:
	s_movk_i32 s14, 0xf0
	s_sub_u32 s99, s100, 896
	s_mul_i32 s44, s99, 0x2e8bb
	s_lshr_b32 s44, s44, 24
	s_mul_i32 s36, s44, 88
	s_sub_u32 s99, s99, s36
	s_mul_i32 s38, s44, 0x160000
	s_lshl_b32 s36, s99, 8
	s_add_u32 s38, s38, s36
	s_add_u32 s38, s38, 0x0
	s_cmpk_ge_u32 s99, 44
	s_cselect_b32 s36, 44, 0
	s_cselect_b32 s37, 32, 0
	s_sub_u32 s36, s99, s36
	s_lshl_b32 s36, s36, 7
	s_add_u32 s36, s36, s37
	s_mov_b32 s32, 0x20000
	s_mul_i32 s36, s36, 0x800
	s_lshl_b32 s44, s44, 7
	s_add_u32 s36, s36, s44
	s_add_u32 s36, s36, 0xe00000
	s_mov_b32 s37, 0x58000
	s_movk_i32 s44, 0x800
	s_mov_b32 s99, 0x5800
	s_branch .Lwcm0_tj_1
.Lwcm0_t3_1:
	s_movk_i32 s14, 0xf8
	s_sub_u32 s99, s100, 2304
	s_mul_i32 s44, s99, 0x100000
	s_lshr_b32 s44, s44, 24
	s_mul_i32 s36, s44, 16
	s_sub_u32 s99, s99, s36
	s_mul_i32 s38, s44, 0x40000
	s_lshl_b32 s36, s99, 8
	s_add_u32 s38, s38, s36
	s_add_u32 s38, s38, 0x0
	s_lshl_b32 s36, s99, 6
	s_mov_b32 s32, 0x2c000
	s_mul_i32 s36, s36, 0x1600
	s_lshl_b32 s44, s44, 7
	s_add_u32 s36, s36, s44
	s_add_u32 s36, s36, 0x2400000
	s_mov_b32 s37, 0x10000
	s_movk_i32 s44, 0x1600
	s_mov_b32 s99, 0x1000
.Lwcm0_tj_1:
	s_load_dwordx2 s[8:9], s[0:1], s14
	s_add_u32 s20, s12, s36
	s_addc_u32 s21, s13, 0
	v_mad_u32_u24 v231, v233, s99, v234
	v_writelane_b32 v237, s20, 8
	v_writelane_b32 v237, s21, 9
	v_writelane_b32 v237, s32, 10
	v_writelane_b32 v237, s44, 11
	s_add_u32 s100, s100, s23
	s_waitcnt lgkmcnt(0)
	s_add_u32 s38, s8, s38
	s_addc_u32 s39, s9, 0
	global_load_dwordx4 v[146:149], v231, s[38:39]
	s_add_u32 s38, s38, s37
	s_addc_u32 s39, s39, 0
	global_load_dwordx4 v[150:153], v231, s[38:39]
	s_add_u32 s38, s38, s37
	s_addc_u32 s39, s39, 0
	global_load_dwordx4 v[154:157], v231, s[38:39]
	s_add_u32 s38, s38, s37
	s_addc_u32 s39, s39, 0
	global_load_dwordx4 v[158:161], v231, s[38:39]
	s_cmp_ge_u32 s100, s22
	s_cbranch_scc1 .Lwcm0_p1
	s_cmpk_ge_u32 s100, 0x900
	s_cbranch_scc1 .Lwcm0_t3_2
	s_cmpk_ge_u32 s100, 0x380
	s_cbranch_scc1 .Lwcm0_t2_2
	s_cmpk_ge_u32 s100, 0x280
	s_cbranch_scc1 .Lwcm0_t1_2
	s_movk_i32 s14, 0x78
	s_sub_u32 s99, s100, 0
	s_mul_i32 s44, s99, 0x66667
	s_lshr_b32 s44, s44, 24
	s_mul_i32 s36, s44, 40
	s_sub_u32 s99, s99, s36
	s_mul_i32 s38, s44, 0xa0000
	s_lshl_b32 s36, s99, 8
	s_add_u32 s38, s38, s36
	s_add_u32 s38, s38, 0x0
	s_lshl_b32 s36, s99, 6
	s_mov_b32 s32, 0x10000
	s_mul_i32 s36, s36, 0x800
	s_lshl_b32 s44, s44, 7
	s_add_u32 s36, s36, s44
	s_add_u32 s36, s36, 0x0
	s_mov_b32 s37, 0x28000
	s_movk_i32 s44, 0x800
	s_mov_b32 s99, 0x2800
	s_branch .Lwcm0_tj_2

.Lwcm0_tj_2:
	s_load_dwordx2 s[8:9], s[0:1], s14
	s_add_u32 s20, s12, s36
	s_addc_u32 s21, s13, 0
	v_mad_u32_u24 v231, v233, s99, v234
	v_writelane_b32 v237, s20, 12
	v_writelane_b32 v237, s21, 13
	v_writelane_b32 v237, s32, 14
	v_writelane_b32 v237, s44, 15
	s_add_u32 s100, s100, s23
	s_waitcnt lgkmcnt(0)
	s_add_u32 s38, s8, s38
	s_addc_u32 s39, s9, 0
	global_load_dwordx4 v[162:165], v231, s[38:39]
	s_add_u32 s38, s38, s37
	s_addc_u32 s39, s39, 0
	global_load_dwordx4 v[166:169], v231, s[38:39]
	s_add_u32 s38, s38, s37
	s_addc_u32 s39, s39, 0
	global_load_dwordx4 v[170:173], v231, s[38:39]
	s_add_u32 s38, s38, s37
	s_addc_u32 s39, s39, 0
	global_load_dwordx4 v[174:177], v231, s[38:39]
	s_cmp_ge_u32 s100, s22
	s_cbranch_scc1 .Lwcm0_p2
	s_cmpk_ge_u32 s100, 0x900
	s_cbranch_scc1 .Lwcm0_t3_3
	s_cmpk_ge_u32 s100, 0x380
	s_cbranch_scc1 .Lwcm0_t2_3
	s_cmpk_ge_u32 s100, 0x280
	s_cbranch_scc1 .Lwcm0_t1_3
	s_movk_i32 s14, 0x78
	s_sub_u32 s99, s100, 0
	s_mul_i32 s44, s99, 0x66667
	s_lshr_b32 s44, s44, 24
	s_mul_i32 s36, s44, 40
	s_sub_u32 s99, s99, s36
	s_mul_i32 s38, s44, 0xa0000
	s_lshl_b32 s36, s99, 8
	s_add_u32 s38, s38, s36
	s_add_u32 s38, s38, 0x0
	s_lshl_b32 s36, s99, 6
	s_mov_b32 s32, 0x10000
	s_mul_i32 s36, s36, 0x800
	s_lshl_b32 s44, s44, 7
	s_add_u32 s36, s36, s44
	s_add_u32 s36, s36, 0x0
	s_mov_b32 s37, 0x28000
	s_movk_i32 s44, 0x800
	s_mov_b32 s99, 0x2800
	s_branch .Lwcm0_tj_3

.Lwcm0_tj_3:
	s_load_dwordx2 s[8:9], s[0:1], s14
	s_add_u32 s20, s12, s36
	s_addc_u32 s21, s13, 0
	v_mad_u32_u24 v231, v233, s99, v234
	v_writelane_b32 v237, s20, 16
	v_writelane_b32 v237, s21, 17
	v_writelane_b32 v237, s32, 18
	v_writelane_b32 v237, s44, 19
	s_add_u32 s100, s100, s23
	s_waitcnt lgkmcnt(0)
	s_add_u32 s38, s8, s38
	s_addc_u32 s39, s9, 0
	global_load_dwordx4 v[178:181], v231, s[38:39]
	s_add_u32 s38, s38, s37
	s_addc_u32 s39, s39, 0
	global_load_dwordx4 v[182:185], v231, s[38:39]
	s_add_u32 s38, s38, s37
	s_addc_u32 s39, s39, 0
	global_load_dwordx4 v[186:189], v231, s[38:39]
	s_add_u32 s38, s38, s37
	s_addc_u32 s39, s39, 0
	global_load_dwordx4 v[190:193], v231, s[38:39]
	s_cmp_ge_u32 s100, s22
	s_cbranch_scc1 .Lwcm0_p3
	s_cmpk_ge_u32 s100, 0x900
	s_cbranch_scc1 .Lwcm0_t3_4
	s_cmpk_ge_u32 s100, 0x380
	s_cbranch_scc1 .Lwcm0_t2_4
	s_cmpk_ge_u32 s100, 0x280
	s_cbranch_scc1 .Lwcm0_t1_4
	s_movk_i32 s14, 0x78
	s_sub_u32 s99, s100, 0
	s_mul_i32 s44, s99, 0x66667
	s_lshr_b32 s44, s44, 24
	s_mul_i32 s36, s44, 40
	s_sub_u32 s99, s99, s36
	s_mul_i32 s38, s44, 0xa0000
	s_lshl_b32 s36, s99, 8
	s_add_u32 s38, s38, s36
	s_add_u32 s38, s38, 0x0
	s_lshl_b32 s36, s99, 6
	s_mov_b32 s32, 0x10000
	s_mul_i32 s36, s36, 0x800
	s_lshl_b32 s44, s44, 7
	s_add_u32 s36, s36, s44
	s_add_u32 s36, s36, 0x0
	s_mov_b32 s37, 0x28000
	s_movk_i32 s44, 0x800
	s_mov_b32 s99, 0x2800
	s_branch .Lwcm0_tj_4

.Lwcm0_tj_4:
	s_load_dwordx2 s[8:9], s[0:1], s14
	s_add_u32 s20, s12, s36
	s_addc_u32 s21, s13, 0
	v_mad_u32_u24 v231, v233, s99, v234
	v_writelane_b32 v237, s20, 20
	v_writelane_b32 v237, s21, 21
	v_writelane_b32 v237, s32, 22
	v_writelane_b32 v237, s44, 23
	s_add_u32 s100, s100, s23
	s_waitcnt lgkmcnt(0)
	s_add_u32 s38, s8, s38
	s_addc_u32 s39, s9, 0
	global_load_dwordx4 v[194:197], v231, s[38:39]
	s_add_u32 s38, s38, s37
	s_addc_u32 s39, s39, 0
	global_load_dwordx4 v[198:201], v231, s[38:39]
	s_add_u32 s38, s38, s37
	s_addc_u32 s39, s39, 0
	global_load_dwordx4 v[202:205], v231, s[38:39]
	s_add_u32 s38, s38, s37
	s_addc_u32 s39, s39, 0
	global_load_dwordx4 v[206:209], v231, s[38:39]
	s_cmp_ge_u32 s100, s22
	s_cbranch_scc1 .Lwcm0_p4
	s_cmpk_ge_u32 s100, 0x900
	s_cbranch_scc1 .Lwcm0_t3_5
	s_cmpk_ge_u32 s100, 0x380
	s_cbranch_scc1 .Lwcm0_t2_5
	s_cmpk_ge_u32 s100, 0x280
	s_cbranch_scc1 .Lwcm0_t1_5
	s_movk_i32 s14, 0x78
	s_sub_u32 s99, s100, 0
	s_mul_i32 s44, s99, 0x66667
	s_lshr_b32 s44, s44, 24
	s_mul_i32 s36, s44, 40
	s_sub_u32 s99, s99, s36
	s_mul_i32 s38, s44, 0xa0000
	s_lshl_b32 s36, s99, 8
	s_add_u32 s38, s38, s36
	s_add_u32 s38, s38, 0x0
	s_lshl_b32 s36, s99, 6
	s_mov_b32 s32, 0x10000
	s_mul_i32 s36, s36, 0x800
	s_lshl_b32 s44, s44, 7
	s_add_u32 s36, s36, s44
	s_add_u32 s36, s36, 0x0
	s_mov_b32 s37, 0x28000
	s_movk_i32 s44, 0x800
	s_mov_b32 s99, 0x2800
	s_branch .Lwcm0_tj_5

.Lwcm0_tj_5:
	s_load_dwordx2 s[8:9], s[0:1], s14
	s_add_u32 s20, s12, s36
	s_addc_u32 s21, s13, 0
	v_mad_u32_u24 v231, v233, s99, v234
	v_writelane_b32 v237, s20, 24
	v_writelane_b32 v237, s21, 25
	v_writelane_b32 v237, s32, 26
	v_writelane_b32 v237, s44, 27
	s_add_u32 s100, s100, s23
	s_waitcnt lgkmcnt(0)
	s_add_u32 s38, s8, s38
	s_addc_u32 s39, s9, 0
	global_load_dwordx4 v[210:213], v231, s[38:39]
	s_add_u32 s38, s38, s37
	s_addc_u32 s39, s39, 0
	global_load_dwordx4 v[214:217], v231, s[38:39]
	s_add_u32 s38, s38, s37
	s_addc_u32 s39, s39, 0
	global_load_dwordx4 v[218:221], v231, s[38:39]
	s_add_u32 s38, s38, s37
	s_addc_u32 s39, s39, 0
	global_load_dwordx4 v[222:225], v231, s[38:39]
.Lwcm0_loop:
	s_waitcnt vmcnt(16)
	v_readlane_b32 s20, v237, 8
	v_readlane_b32 s21, v237, 9
	v_readlane_b32 s32, v237, 10
	v_readlane_b32 s35, v237, 11
	ds_write_b32 v226, v146 offset:0
	ds_write_b32 v226, v147 offset:4
	ds_write_b32 v226, v148 offset:8
	ds_write_b32 v226, v149 offset:12
	ds_write_b32 v226, v150 offset:4160
	ds_write_b32 v226, v151 offset:4164
	ds_write_b32 v226, v152 offset:4168
	ds_write_b32 v226, v153 offset:4172
	ds_write_b32 v226, v154 offset:8320
	ds_write_b32 v226, v155 offset:8324
	ds_write_b32 v226, v156 offset:8328
	ds_write_b32 v226, v157 offset:8332
	ds_write_b32 v226, v158 offset:12480
	ds_write_b32 v226, v159 offset:12484
	ds_write_b32 v226, v160 offset:12488
	ds_write_b32 v226, v161 offset:12492
	v_mad_u32_u24 v232, v235, s35, v236
	s_waitcnt lgkmcnt(0)
	s_barrier
	ds_read2_b32 v[146:147], v227 offset1:65
	ds_read2_b32 v[148:149], v227 offset0:130 offset1:195
	ds_read2_b32 v[150:151], v228 offset0:4 offset1:69
	ds_read2_b32 v[152:153], v228 offset0:134 offset1:199
	ds_read2_b32 v[154:155], v229 offset1:65
	ds_read2_b32 v[156:157], v229 offset0:130 offset1:195
	ds_read2_b32 v[158:159], v230 offset0:4 offset1:69
	ds_read2_b32 v[160:161], v230 offset0:134 offset1:199
	s_add_u32 s26, s20, s32
	s_addc_u32 s27, s21, 0
	s_waitcnt lgkmcnt(0)
	s_barrier
	v_cvt_pk_bf16_f32 v146, v146, v147
	v_cvt_pk_bf16_f32 v147, v148, v149
	v_cvt_pk_bf16_f32 v148, v150, v151
	v_cvt_pk_bf16_f32 v149, v152, v153
	v_cvt_pk_bf16_f32 v154, v154, v155
	v_cvt_pk_bf16_f32 v155, v156, v157
	v_cvt_pk_bf16_f32 v156, v158, v159
	v_cvt_pk_bf16_f32 v157, v160, v161
	global_store_dwordx4 v232, v[146:149], s[20:21]
	global_store_dwordx4 v232, v[154:157], s[26:27]
	s_cmp_ge_u32 s100, s22
	s_cbranch_scc1 .Lwcm0_tail0
	s_cmpk_ge_u32 s100, 0x900
	s_cbranch_scc1 .Lwcm0_t3_6
	s_cmpk_ge_u32 s100, 0x380
	s_cbranch_scc1 .Lwcm0_t2_6
	s_cmpk_ge_u32 s100, 0x280
	s_cbranch_scc1 .Lwcm0_t1_6
	s_movk_i32 s14, 0x78
	s_sub_u32 s99, s100, 0
	s_mul_i32 s44, s99, 0x66667
	s_lshr_b32 s44, s44, 24
	s_mul_i32 s36, s44, 40
	s_sub_u32 s99, s99, s36
	s_mul_i32 s38, s44, 0xa0000
	s_lshl_b32 s36, s99, 8
	s_add_u32 s38, s38, s36
	s_add_u32 s38, s38, 0x0
	s_lshl_b32 s36, s99, 6
	s_mov_b32 s32, 0x10000
	s_mul_i32 s36, s36, 0x800
	s_lshl_b32 s44, s44, 7
	s_add_u32 s36, s36, s44
	s_add_u32 s36, s36, 0x0
	s_mov_b32 s37, 0x28000
	s_movk_i32 s44, 0x800
	s_mov_b32 s99, 0x2800
	s_branch .Lwcm0_tj_6

.Lwcm0_tj_6:
	s_load_dwordx2 s[8:9], s[0:1], s14
	s_add_u32 s20, s12, s36
	s_addc_u32 s21, s13, 0
	v_mad_u32_u24 v231, v233, s99, v234
	v_writelane_b32 v237, s20, 8
	v_writelane_b32 v237, s21, 9
	v_writelane_b32 v237, s32, 10
	v_writelane_b32 v237, s44, 11
	s_add_u32 s100, s100, s23
	s_waitcnt lgkmcnt(0)
	s_add_u32 s38, s8, s38
	s_addc_u32 s39, s9, 0
	global_load_dwordx4 v[146:149], v231, s[38:39]
	s_add_u32 s38, s38, s37
	s_addc_u32 s39, s39, 0
	global_load_dwordx4 v[150:153], v231, s[38:39]
	s_add_u32 s38, s38, s37
	s_addc_u32 s39, s39, 0
	global_load_dwordx4 v[154:157], v231, s[38:39]
	s_add_u32 s38, s38, s37
	s_addc_u32 s39, s39, 0
	global_load_dwordx4 v[158:161], v231, s[38:39]
	s_waitcnt vmcnt(16)
	v_readlane_b32 s20, v237, 12
	v_readlane_b32 s21, v237, 13
	v_readlane_b32 s32, v237, 14
	v_readlane_b32 s35, v237, 15
	ds_write_b32 v226, v162 offset:0
	ds_write_b32 v226, v163 offset:4
	ds_write_b32 v226, v164 offset:8
	ds_write_b32 v226, v165 offset:12
	ds_write_b32 v226, v166 offset:4160
	ds_write_b32 v226, v167 offset:4164
	ds_write_b32 v226, v168 offset:4168
	ds_write_b32 v226, v169 offset:4172
	ds_write_b32 v226, v170 offset:8320
	ds_write_b32 v226, v171 offset:8324
	ds_write_b32 v226, v172 offset:8328
	ds_write_b32 v226, v173 offset:8332
	ds_write_b32 v226, v174 offset:12480
	ds_write_b32 v226, v175 offset:12484
	ds_write_b32 v226, v176 offset:12488
	ds_write_b32 v226, v177 offset:12492
	v_mad_u32_u24 v232, v235, s35, v236
	s_waitcnt lgkmcnt(0)
	s_barrier
	ds_read2_b32 v[162:163], v227 offset1:65
	ds_read2_b32 v[164:165], v227 offset0:130 offset1:195
	ds_read2_b32 v[166:167], v228 offset0:4 offset1:69
	ds_read2_b32 v[168:169], v228 offset0:134 offset1:199
	ds_read2_b32 v[170:171], v229 offset1:65
	ds_read2_b32 v[172:173], v229 offset0:130 offset1:195
	ds_read2_b32 v[174:175], v230 offset0:4 offset1:69
	ds_read2_b32 v[176:177], v230 offset0:134 offset1:199
	s_add_u32 s26, s20, s32
	s_addc_u32 s27, s21, 0
	s_waitcnt lgkmcnt(0)
	s_barrier
	v_cvt_pk_bf16_f32 v162, v162, v163
	v_cvt_pk_bf16_f32 v163, v164, v165
	v_cvt_pk_bf16_f32 v164, v166, v167
	v_cvt_pk_bf16_f32 v165, v168, v169
	v_cvt_pk_bf16_f32 v170, v170, v171
	v_cvt_pk_bf16_f32 v171, v172, v173
	v_cvt_pk_bf16_f32 v172, v174, v175
	v_cvt_pk_bf16_f32 v173, v176, v177
	global_store_dwordx4 v232, v[162:165], s[20:21]
	global_store_dwordx4 v232, v[170:173], s[26:27]
	s_cmp_ge_u32 s100, s22
	s_cbranch_scc1 .Lwcm0_tail1
	s_cmpk_ge_u32 s100, 0x900
	s_cbranch_scc1 .Lwcm0_t3_7
	s_cmpk_ge_u32 s100, 0x380
	s_cbranch_scc1 .Lwcm0_t2_7
	s_cmpk_ge_u32 s100, 0x280
	s_cbranch_scc1 .Lwcm0_t1_7
	s_movk_i32 s14, 0x78
	s_sub_u32 s99, s100, 0
	s_mul_i32 s44, s99, 0x66667
	s_lshr_b32 s44, s44, 24
	s_mul_i32 s36, s44, 40
	s_sub_u32 s99, s99, s36
	s_mul_i32 s38, s44, 0xa0000
	s_lshl_b32 s36, s99, 8
	s_add_u32 s38, s38, s36
	s_add_u32 s38, s38, 0x0
	s_lshl_b32 s36, s99, 6
	s_mov_b32 s32, 0x10000
	s_mul_i32 s36, s36, 0x800
	s_lshl_b32 s44, s44, 7
	s_add_u32 s36, s36, s44
	s_add_u32 s36, s36, 0x0
	s_mov_b32 s37, 0x28000
	s_movk_i32 s44, 0x800
	s_mov_b32 s99, 0x2800
	s_branch .Lwcm0_tj_7

.Lwcm0_tj_7:
	s_load_dwordx2 s[8:9], s[0:1], s14
	s_add_u32 s20, s12, s36
	s_addc_u32 s21, s13, 0
	v_mad_u32_u24 v231, v233, s99, v234
	v_writelane_b32 v237, s20, 12
	v_writelane_b32 v237, s21, 13
	v_writelane_b32 v237, s32, 14
	v_writelane_b32 v237, s44, 15
	s_add_u32 s100, s100, s23
	s_waitcnt lgkmcnt(0)
	s_add_u32 s38, s8, s38
	s_addc_u32 s39, s9, 0
	global_load_dwordx4 v[162:165], v231, s[38:39]
	s_add_u32 s38, s38, s37
	s_addc_u32 s39, s39, 0
	global_load_dwordx4 v[166:169], v231, s[38:39]
	s_add_u32 s38, s38, s37
	s_addc_u32 s39, s39, 0
	global_load_dwordx4 v[170:173], v231, s[38:39]
	s_add_u32 s38, s38, s37
	s_addc_u32 s39, s39, 0
	global_load_dwordx4 v[174:177], v231, s[38:39]
	s_waitcnt vmcnt(16)
	v_readlane_b32 s20, v237, 16
	v_readlane_b32 s21, v237, 17
	v_readlane_b32 s32, v237, 18
	v_readlane_b32 s35, v237, 19
	ds_write_b32 v226, v178 offset:0
	ds_write_b32 v226, v179 offset:4
	ds_write_b32 v226, v180 offset:8
	ds_write_b32 v226, v181 offset:12
	ds_write_b32 v226, v182 offset:4160
	ds_write_b32 v226, v183 offset:4164
	ds_write_b32 v226, v184 offset:4168
	ds_write_b32 v226, v185 offset:4172
	ds_write_b32 v226, v186 offset:8320
	ds_write_b32 v226, v187 offset:8324
	ds_write_b32 v226, v188 offset:8328
	ds_write_b32 v226, v189 offset:8332
	ds_write_b32 v226, v190 offset:12480
	ds_write_b32 v226, v191 offset:12484
	ds_write_b32 v226, v192 offset:12488
	ds_write_b32 v226, v193 offset:12492
	v_mad_u32_u24 v232, v235, s35, v236
	s_waitcnt lgkmcnt(0)
	s_barrier
	ds_read2_b32 v[178:179], v227 offset1:65
	ds_read2_b32 v[180:181], v227 offset0:130 offset1:195
	ds_read2_b32 v[182:183], v228 offset0:4 offset1:69
	ds_read2_b32 v[184:185], v228 offset0:134 offset1:199
	ds_read2_b32 v[186:187], v229 offset1:65
	ds_read2_b32 v[188:189], v229 offset0:130 offset1:195
	ds_read2_b32 v[190:191], v230 offset0:4 offset1:69
	ds_read2_b32 v[192:193], v230 offset0:134 offset1:199
	s_add_u32 s26, s20, s32
	s_addc_u32 s27, s21, 0
	s_waitcnt lgkmcnt(0)
	s_barrier
	v_cvt_pk_bf16_f32 v178, v178, v179
	v_cvt_pk_bf16_f32 v179, v180, v181
	v_cvt_pk_bf16_f32 v180, v182, v183
	v_cvt_pk_bf16_f32 v181, v184, v185
	v_cvt_pk_bf16_f32 v186, v186, v187
	v_cvt_pk_bf16_f32 v187, v188, v189
	v_cvt_pk_bf16_f32 v188, v190, v191
	v_cvt_pk_bf16_f32 v189, v192, v193
	global_store_dwordx4 v232, v[178:181], s[20:21]
	global_store_dwordx4 v232, v[186:189], s[26:27]
	s_cmp_ge_u32 s100, s22
	s_cbranch_scc1 .Lwcm0_tail2
	s_cmpk_ge_u32 s100, 0x900
	s_cbranch_scc1 .Lwcm0_t3_8
	s_cmpk_ge_u32 s100, 0x380
	s_cbranch_scc1 .Lwcm0_t2_8
	s_cmpk_ge_u32 s100, 0x280
	s_cbranch_scc1 .Lwcm0_t1_8
	s_movk_i32 s14, 0x78
	s_sub_u32 s99, s100, 0
	s_mul_i32 s44, s99, 0x66667
	s_lshr_b32 s44, s44, 24
	s_mul_i32 s36, s44, 40
	s_sub_u32 s99, s99, s36
	s_mul_i32 s38, s44, 0xa0000
	s_lshl_b32 s36, s99, 8
	s_add_u32 s38, s38, s36
	s_add_u32 s38, s38, 0x0
	s_lshl_b32 s36, s99, 6
	s_mov_b32 s32, 0x10000
	s_mul_i32 s36, s36, 0x800
	s_lshl_b32 s44, s44, 7
	s_add_u32 s36, s36, s44
	s_add_u32 s36, s36, 0x0
	s_mov_b32 s37, 0x28000
	s_movk_i32 s44, 0x800
	s_mov_b32 s99, 0x2800
	s_branch .Lwcm0_tj_8

.Lwcm0_tj_8:
	s_load_dwordx2 s[8:9], s[0:1], s14
	s_add_u32 s20, s12, s36
	s_addc_u32 s21, s13, 0
	v_mad_u32_u24 v231, v233, s99, v234
	v_writelane_b32 v237, s20, 16
	v_writelane_b32 v237, s21, 17
	v_writelane_b32 v237, s32, 18
	v_writelane_b32 v237, s44, 19
	s_add_u32 s100, s100, s23
	s_waitcnt lgkmcnt(0)
	s_add_u32 s38, s8, s38
	s_addc_u32 s39, s9, 0
	global_load_dwordx4 v[178:181], v231, s[38:39]
	s_add_u32 s38, s38, s37
	s_addc_u32 s39, s39, 0
	global_load_dwordx4 v[182:185], v231, s[38:39]
	s_add_u32 s38, s38, s37
	s_addc_u32 s39, s39, 0
	global_load_dwordx4 v[186:189], v231, s[38:39]
	s_add_u32 s38, s38, s37
	s_addc_u32 s39, s39, 0
	global_load_dwordx4 v[190:193], v231, s[38:39]
	s_waitcnt vmcnt(16)
	v_readlane_b32 s20, v237, 20
	v_readlane_b32 s21, v237, 21
	v_readlane_b32 s32, v237, 22
	v_readlane_b32 s35, v237, 23
	ds_write_b32 v226, v194 offset:0
	ds_write_b32 v226, v195 offset:4
	ds_write_b32 v226, v196 offset:8
	ds_write_b32 v226, v197 offset:12
	ds_write_b32 v226, v198 offset:4160
	ds_write_b32 v226, v199 offset:4164
	ds_write_b32 v226, v200 offset:4168
	ds_write_b32 v226, v201 offset:4172
	ds_write_b32 v226, v202 offset:8320
	ds_write_b32 v226, v203 offset:8324
	ds_write_b32 v226, v204 offset:8328
	ds_write_b32 v226, v205 offset:8332
	ds_write_b32 v226, v206 offset:12480
	ds_write_b32 v226, v207 offset:12484
	ds_write_b32 v226, v208 offset:12488
	ds_write_b32 v226, v209 offset:12492
	v_mad_u32_u24 v232, v235, s35, v236
	s_waitcnt lgkmcnt(0)
	s_barrier
	ds_read2_b32 v[194:195], v227 offset1:65
	ds_read2_b32 v[196:197], v227 offset0:130 offset1:195
	ds_read2_b32 v[198:199], v228 offset0:4 offset1:69
	ds_read2_b32 v[200:201], v228 offset0:134 offset1:199
	ds_read2_b32 v[202:203], v229 offset1:65
	ds_read2_b32 v[204:205], v229 offset0:130 offset1:195
	ds_read2_b32 v[206:207], v230 offset0:4 offset1:69
	ds_read2_b32 v[208:209], v230 offset0:134 offset1:199
	s_add_u32 s26, s20, s32
	s_addc_u32 s27, s21, 0
	s_waitcnt lgkmcnt(0)
	s_barrier
	v_cvt_pk_bf16_f32 v194, v194, v195
	v_cvt_pk_bf16_f32 v195, v196, v197
	v_cvt_pk_bf16_f32 v196, v198, v199
	v_cvt_pk_bf16_f32 v197, v200, v201
	v_cvt_pk_bf16_f32 v202, v202, v203
	v_cvt_pk_bf16_f32 v203, v204, v205
	v_cvt_pk_bf16_f32 v204, v206, v207
	v_cvt_pk_bf16_f32 v205, v208, v209
	global_store_dwordx4 v232, v[194:197], s[20:21]
	global_store_dwordx4 v232, v[202:205], s[26:27]
	s_cmp_ge_u32 s100, s22
	s_cbranch_scc1 .Lwcm0_tail3
	s_cmpk_ge_u32 s100, 0x900
	s_cbranch_scc1 .Lwcm0_t3_9
	s_cmpk_ge_u32 s100, 0x380
	s_cbranch_scc1 .Lwcm0_t2_9
	s_cmpk_ge_u32 s100, 0x280
	s_cbranch_scc1 .Lwcm0_t1_9
	s_movk_i32 s14, 0x78
	s_sub_u32 s99, s100, 0
	s_mul_i32 s44, s99, 0x66667
	s_lshr_b32 s44, s44, 24
	s_mul_i32 s36, s44, 40
	s_sub_u32 s99, s99, s36
	s_mul_i32 s38, s44, 0xa0000
	s_lshl_b32 s36, s99, 8
	s_add_u32 s38, s38, s36
	s_add_u32 s38, s38, 0x0
	s_lshl_b32 s36, s99, 6
	s_mov_b32 s32, 0x10000
	s_mul_i32 s36, s36, 0x800
	s_lshl_b32 s44, s44, 7
	s_add_u32 s36, s36, s44
	s_add_u32 s36, s36, 0x0
	s_mov_b32 s37, 0x28000
	s_movk_i32 s44, 0x800
	s_mov_b32 s99, 0x2800
	s_branch .Lwcm0_tj_9

.Lwcm0_tj_9:
	s_load_dwordx2 s[8:9], s[0:1], s14
	s_add_u32 s20, s12, s36
	s_addc_u32 s21, s13, 0
	v_mad_u32_u24 v231, v233, s99, v234
	v_writelane_b32 v237, s20, 20
	v_writelane_b32 v237, s21, 21
	v_writelane_b32 v237, s32, 22
	v_writelane_b32 v237, s44, 23
	s_add_u32 s100, s100, s23
	s_waitcnt lgkmcnt(0)
	s_add_u32 s38, s8, s38
	s_addc_u32 s39, s9, 0
	global_load_dwordx4 v[194:197], v231, s[38:39]
	s_add_u32 s38, s38, s37
	s_addc_u32 s39, s39, 0
	global_load_dwordx4 v[198:201], v231, s[38:39]
	s_add_u32 s38, s38, s37
	s_addc_u32 s39, s39, 0
	global_load_dwordx4 v[202:205], v231, s[38:39]
	s_add_u32 s38, s38, s37
	s_addc_u32 s39, s39, 0
	global_load_dwordx4 v[206:209], v231, s[38:39]
	s_waitcnt vmcnt(16)
	v_readlane_b32 s20, v237, 24
	v_readlane_b32 s21, v237, 25
	v_readlane_b32 s32, v237, 26
	v_readlane_b32 s35, v237, 27
	ds_write_b32 v226, v210 offset:0
	ds_write_b32 v226, v211 offset:4
	ds_write_b32 v226, v212 offset:8
	ds_write_b32 v226, v213 offset:12
	ds_write_b32 v226, v214 offset:4160
	ds_write_b32 v226, v215 offset:4164
	ds_write_b32 v226, v216 offset:4168
	ds_write_b32 v226, v217 offset:4172
	ds_write_b32 v226, v218 offset:8320
	ds_write_b32 v226, v219 offset:8324
	ds_write_b32 v226, v220 offset:8328
	ds_write_b32 v226, v221 offset:8332
	ds_write_b32 v226, v222 offset:12480
	ds_write_b32 v226, v223 offset:12484
	ds_write_b32 v226, v224 offset:12488
	ds_write_b32 v226, v225 offset:12492
	v_mad_u32_u24 v232, v235, s35, v236
	s_waitcnt lgkmcnt(0)
	s_barrier
	ds_read2_b32 v[210:211], v227 offset1:65
	ds_read2_b32 v[212:213], v227 offset0:130 offset1:195
	ds_read2_b32 v[214:215], v228 offset0:4 offset1:69
	ds_read2_b32 v[216:217], v228 offset0:134 offset1:199
	ds_read2_b32 v[218:219], v229 offset1:65
	ds_read2_b32 v[220:221], v229 offset0:130 offset1:195
	ds_read2_b32 v[222:223], v230 offset0:4 offset1:69
	ds_read2_b32 v[224:225], v230 offset0:134 offset1:199
	s_add_u32 s26, s20, s32
	s_addc_u32 s27, s21, 0
	s_waitcnt lgkmcnt(0)
	s_barrier
	v_cvt_pk_bf16_f32 v210, v210, v211
	v_cvt_pk_bf16_f32 v211, v212, v213
	v_cvt_pk_bf16_f32 v212, v214, v215
	v_cvt_pk_bf16_f32 v213, v216, v217
	v_cvt_pk_bf16_f32 v218, v218, v219
	v_cvt_pk_bf16_f32 v219, v220, v221
	v_cvt_pk_bf16_f32 v220, v222, v223
	v_cvt_pk_bf16_f32 v221, v224, v225
	global_store_dwordx4 v232, v[210:213], s[20:21]
	global_store_dwordx4 v232, v[218:221], s[26:27]
	s_cmp_ge_u32 s100, s22
	s_cbranch_scc1 .Lwcm0_tail4
	s_cmpk_ge_u32 s100, 0x900
	s_cbranch_scc1 .Lwcm0_t3_10
	s_cmpk_ge_u32 s100, 0x380
	s_cbranch_scc1 .Lwcm0_t2_10
	s_cmpk_ge_u32 s100, 0x280
	s_cbranch_scc1 .Lwcm0_t1_10
	s_movk_i32 s14, 0x78
	s_sub_u32 s99, s100, 0
	s_mul_i32 s44, s99, 0x66667
	s_lshr_b32 s44, s44, 24
	s_mul_i32 s36, s44, 40
	s_sub_u32 s99, s99, s36
	s_mul_i32 s38, s44, 0xa0000
	s_lshl_b32 s36, s99, 8
	s_add_u32 s38, s38, s36
	s_add_u32 s38, s38, 0x0
	s_lshl_b32 s36, s99, 6
	s_mov_b32 s32, 0x10000
	s_mul_i32 s36, s36, 0x800
	s_lshl_b32 s44, s44, 7
	s_add_u32 s36, s36, s44
	s_add_u32 s36, s36, 0x0
	s_mov_b32 s37, 0x28000
	s_movk_i32 s44, 0x800
	s_mov_b32 s99, 0x2800
	s_branch .Lwcm0_tj_10

.Lwcm0_tj_10:
	s_load_dwordx2 s[8:9], s[0:1], s14
	s_add_u32 s20, s12, s36
	s_addc_u32 s21, s13, 0
	v_mad_u32_u24 v231, v233, s99, v234
	v_writelane_b32 v237, s20, 24
	v_writelane_b32 v237, s21, 25
	v_writelane_b32 v237, s32, 26
	v_writelane_b32 v237, s44, 27
	s_add_u32 s100, s100, s23
	s_waitcnt lgkmcnt(0)
	s_add_u32 s38, s8, s38
	s_addc_u32 s39, s9, 0
	global_load_dwordx4 v[210:213], v231, s[38:39]
	s_add_u32 s38, s38, s37
	s_addc_u32 s39, s39, 0
	global_load_dwordx4 v[214:217], v231, s[38:39]
	s_add_u32 s38, s38, s37
	s_addc_u32 s39, s39, 0
	global_load_dwordx4 v[218:221], v231, s[38:39]
	s_add_u32 s38, s38, s37
	s_addc_u32 s39, s39, 0
	global_load_dwordx4 v[222:225], v231, s[38:39]
	s_branch .Lwcm0_loop
.Lwcm0_tail0:
	s_waitcnt vmcnt(0)
	v_readlane_b32 s20, v237, 12
	v_readlane_b32 s21, v237, 13
	v_readlane_b32 s32, v237, 14
	v_readlane_b32 s35, v237, 15
	ds_write_b32 v226, v162 offset:0
	ds_write_b32 v226, v163 offset:4
	ds_write_b32 v226, v164 offset:8
	ds_write_b32 v226, v165 offset:12
	ds_write_b32 v226, v166 offset:4160
	ds_write_b32 v226, v167 offset:4164
	ds_write_b32 v226, v168 offset:4168
	ds_write_b32 v226, v169 offset:4172
	ds_write_b32 v226, v170 offset:8320
	ds_write_b32 v226, v171 offset:8324
	ds_write_b32 v226, v172 offset:8328
	ds_write_b32 v226, v173 offset:8332
	ds_write_b32 v226, v174 offset:12480
	ds_write_b32 v226, v175 offset:12484
	ds_write_b32 v226, v176 offset:12488
	ds_write_b32 v226, v177 offset:12492
	v_mad_u32_u24 v232, v235, s35, v236
	s_waitcnt lgkmcnt(0)
	s_barrier
	ds_read2_b32 v[162:163], v227 offset1:65
	ds_read2_b32 v[164:165], v227 offset0:130 offset1:195
	ds_read2_b32 v[166:167], v228 offset0:4 offset1:69
	ds_read2_b32 v[168:169], v228 offset0:134 offset1:199
	ds_read2_b32 v[170:171], v229 offset1:65
	ds_read2_b32 v[172:173], v229 offset0:130 offset1:195
	ds_read2_b32 v[174:175], v230 offset0:4 offset1:69
	ds_read2_b32 v[176:177], v230 offset0:134 offset1:199
	s_add_u32 s26, s20, s32
	s_addc_u32 s27, s21, 0
	s_waitcnt lgkmcnt(0)
	s_barrier
	v_cvt_pk_bf16_f32 v162, v162, v163
	v_cvt_pk_bf16_f32 v163, v164, v165
	v_cvt_pk_bf16_f32 v164, v166, v167
	v_cvt_pk_bf16_f32 v165, v168, v169
	v_cvt_pk_bf16_f32 v170, v170, v171
	v_cvt_pk_bf16_f32 v171, v172, v173
	v_cvt_pk_bf16_f32 v172, v174, v175
	v_cvt_pk_bf16_f32 v173, v176, v177
	global_store_dwordx4 v232, v[162:165], s[20:21]
	global_store_dwordx4 v232, v[170:173], s[26:27]
	v_readlane_b32 s20, v237, 16
	v_readlane_b32 s21, v237, 17
	v_readlane_b32 s32, v237, 18
	v_readlane_b32 s35, v237, 19
	ds_write_b32 v226, v178 offset:0
	ds_write_b32 v226, v179 offset:4
	ds_write_b32 v226, v180 offset:8
	ds_write_b32 v226, v181 offset:12
	ds_write_b32 v226, v182 offset:4160
	ds_write_b32 v226, v183 offset:4164
	ds_write_b32 v226, v184 offset:4168
	ds_write_b32 v226, v185 offset:4172
	ds_write_b32 v226, v186 offset:8320
	ds_write_b32 v226, v187 offset:8324
	ds_write_b32 v226, v188 offset:8328
	ds_write_b32 v226, v189 offset:8332
	ds_write_b32 v226, v190 offset:12480
	ds_write_b32 v226, v191 offset:12484
	ds_write_b32 v226, v192 offset:12488
	ds_write_b32 v226, v193 offset:12492
	v_mad_u32_u24 v232, v235, s35, v236
	s_waitcnt lgkmcnt(0)
	s_barrier
	ds_read2_b32 v[178:179], v227 offset1:65
	ds_read2_b32 v[180:181], v227 offset0:130 offset1:195
	ds_read2_b32 v[182:183], v228 offset0:4 offset1:69
	ds_read2_b32 v[184:185], v228 offset0:134 offset1:199
	ds_read2_b32 v[186:187], v229 offset1:65
	ds_read2_b32 v[188:189], v229 offset0:130 offset1:195
	ds_read2_b32 v[190:191], v230 offset0:4 offset1:69
	ds_read2_b32 v[192:193], v230 offset0:134 offset1:199
	s_add_u32 s26, s20, s32
	s_addc_u32 s27, s21, 0
	s_waitcnt lgkmcnt(0)
	s_barrier
	v_cvt_pk_bf16_f32 v178, v178, v179
	v_cvt_pk_bf16_f32 v179, v180, v181
	v_cvt_pk_bf16_f32 v180, v182, v183
	v_cvt_pk_bf16_f32 v181, v184, v185
	v_cvt_pk_bf16_f32 v186, v186, v187
	v_cvt_pk_bf16_f32 v187, v188, v189
	v_cvt_pk_bf16_f32 v188, v190, v191
	v_cvt_pk_bf16_f32 v189, v192, v193
	global_store_dwordx4 v232, v[178:181], s[20:21]
	global_store_dwordx4 v232, v[186:189], s[26:27]
	v_readlane_b32 s20, v237, 20
	v_readlane_b32 s21, v237, 21
	v_readlane_b32 s32, v237, 22
	v_readlane_b32 s35, v237, 23
	ds_write_b32 v226, v194 offset:0
	ds_write_b32 v226, v195 offset:4
	ds_write_b32 v226, v196 offset:8
	ds_write_b32 v226, v197 offset:12
	ds_write_b32 v226, v198 offset:4160
	ds_write_b32 v226, v199 offset:4164
	ds_write_b32 v226, v200 offset:4168
	ds_write_b32 v226, v201 offset:4172
	ds_write_b32 v226, v202 offset:8320
	ds_write_b32 v226, v203 offset:8324
	ds_write_b32 v226, v204 offset:8328
	ds_write_b32 v226, v205 offset:8332
	ds_write_b32 v226, v206 offset:12480
	ds_write_b32 v226, v207 offset:12484
	ds_write_b32 v226, v208 offset:12488
	ds_write_b32 v226, v209 offset:12492
	v_mad_u32_u24 v232, v235, s35, v236
	s_waitcnt lgkmcnt(0)
	s_barrier
	ds_read2_b32 v[194:195], v227 offset1:65
	ds_read2_b32 v[196:197], v227 offset0:130 offset1:195
	ds_read2_b32 v[198:199], v228 offset0:4 offset1:69
	ds_read2_b32 v[200:201], v228 offset0:134 offset1:199
	ds_read2_b32 v[202:203], v229 offset1:65
	ds_read2_b32 v[204:205], v229 offset0:130 offset1:195
	ds_read2_b32 v[206:207], v230 offset0:4 offset1:69
	ds_read2_b32 v[208:209], v230 offset0:134 offset1:199
	s_add_u32 s26, s20, s32
	s_addc_u32 s27, s21, 0
	s_waitcnt lgkmcnt(0)
	s_barrier
	v_cvt_pk_bf16_f32 v194, v194, v195
	v_cvt_pk_bf16_f32 v195, v196, v197
	v_cvt_pk_bf16_f32 v196, v198, v199
	v_cvt_pk_bf16_f32 v197, v200, v201
	v_cvt_pk_bf16_f32 v202, v202, v203
	v_cvt_pk_bf16_f32 v203, v204, v205
	v_cvt_pk_bf16_f32 v204, v206, v207
	v_cvt_pk_bf16_f32 v205, v208, v209
	global_store_dwordx4 v232, v[194:197], s[20:21]
	global_store_dwordx4 v232, v[202:205], s[26:27]
	v_readlane_b32 s20, v237, 24
	v_readlane_b32 s21, v237, 25
	v_readlane_b32 s32, v237, 26
	v_readlane_b32 s35, v237, 27
	ds_write_b32 v226, v210 offset:0
	ds_write_b32 v226, v211 offset:4
	ds_write_b32 v226, v212 offset:8
	ds_write_b32 v226, v213 offset:12
	ds_write_b32 v226, v214 offset:4160
	ds_write_b32 v226, v215 offset:4164
	ds_write_b32 v226, v216 offset:4168
	ds_write_b32 v226, v217 offset:4172
	ds_write_b32 v226, v218 offset:8320
	ds_write_b32 v226, v219 offset:8324
	ds_write_b32 v226, v220 offset:8328
	ds_write_b32 v226, v221 offset:8332
	ds_write_b32 v226, v222 offset:12480
	ds_write_b32 v226, v223 offset:12484
	ds_write_b32 v226, v224 offset:12488
	ds_write_b32 v226, v225 offset:12492
	v_mad_u32_u24 v232, v235, s35, v236
	s_waitcnt lgkmcnt(0)
	s_barrier
	ds_read2_b32 v[210:211], v227 offset1:65
	ds_read2_b32 v[212:213], v227 offset0:130 offset1:195
	ds_read2_b32 v[214:215], v228 offset0:4 offset1:69
	ds_read2_b32 v[216:217], v228 offset0:134 offset1:199
	ds_read2_b32 v[218:219], v229 offset1:65
	ds_read2_b32 v[220:221], v229 offset0:130 offset1:195
	ds_read2_b32 v[222:223], v230 offset0:4 offset1:69
	ds_read2_b32 v[224:225], v230 offset0:134 offset1:199
	s_add_u32 s26, s20, s32
	s_addc_u32 s27, s21, 0
	s_waitcnt lgkmcnt(0)
	s_barrier
	v_cvt_pk_bf16_f32 v210, v210, v211
	v_cvt_pk_bf16_f32 v211, v212, v213
	v_cvt_pk_bf16_f32 v212, v214, v215
	v_cvt_pk_bf16_f32 v213, v216, v217
	v_cvt_pk_bf16_f32 v218, v218, v219
	v_cvt_pk_bf16_f32 v219, v220, v221
	v_cvt_pk_bf16_f32 v220, v222, v223
	v_cvt_pk_bf16_f32 v221, v224, v225
	global_store_dwordx4 v232, v[210:213], s[20:21]
	global_store_dwordx4 v232, v[218:221], s[26:27]
	s_branch .Lwcm0_done
.Lwcm0_tail1:
	s_waitcnt vmcnt(0)
	v_readlane_b32 s20, v237, 16
	v_readlane_b32 s21, v237, 17
	v_readlane_b32 s32, v237, 18
	v_readlane_b32 s35, v237, 19
	ds_write_b32 v226, v178 offset:0
	ds_write_b32 v226, v179 offset:4
	ds_write_b32 v226, v180 offset:8
	ds_write_b32 v226, v181 offset:12
	ds_write_b32 v226, v182 offset:4160
	ds_write_b32 v226, v183 offset:4164
	ds_write_b32 v226, v184 offset:4168
	ds_write_b32 v226, v185 offset:4172
	ds_write_b32 v226, v186 offset:8320
	ds_write_b32 v226, v187 offset:8324
	ds_write_b32 v226, v188 offset:8328
	ds_write_b32 v226, v189 offset:8332
	ds_write_b32 v226, v190 offset:12480
	ds_write_b32 v226, v191 offset:12484
	ds_write_b32 v226, v192 offset:12488
	ds_write_b32 v226, v193 offset:12492
	v_mad_u32_u24 v232, v235, s35, v236
	s_waitcnt lgkmcnt(0)
	s_barrier
	ds_read2_b32 v[178:179], v227 offset1:65
	ds_read2_b32 v[180:181], v227 offset0:130 offset1:195
	ds_read2_b32 v[182:183], v228 offset0:4 offset1:69
	ds_read2_b32 v[184:185], v228 offset0:134 offset1:199
	ds_read2_b32 v[186:187], v229 offset1:65
	ds_read2_b32 v[188:189], v229 offset0:130 offset1:195
	ds_read2_b32 v[190:191], v230 offset0:4 offset1:69
	ds_read2_b32 v[192:193], v230 offset0:134 offset1:199
	s_add_u32 s26, s20, s32
	s_addc_u32 s27, s21, 0
	s_waitcnt lgkmcnt(0)
	s_barrier
	v_cvt_pk_bf16_f32 v178, v178, v179
	v_cvt_pk_bf16_f32 v179, v180, v181
	v_cvt_pk_bf16_f32 v180, v182, v183
	v_cvt_pk_bf16_f32 v181, v184, v185
	v_cvt_pk_bf16_f32 v186, v186, v187
	v_cvt_pk_bf16_f32 v187, v188, v189
	v_cvt_pk_bf16_f32 v188, v190, v191
	v_cvt_pk_bf16_f32 v189, v192, v193
	global_store_dwordx4 v232, v[178:181], s[20:21]
	global_store_dwordx4 v232, v[186:189], s[26:27]
	v_readlane_b32 s20, v237, 20
	v_readlane_b32 s21, v237, 21
	v_readlane_b32 s32, v237, 22
	v_readlane_b32 s35, v237, 23
	ds_write_b32 v226, v194 offset:0
	ds_write_b32 v226, v195 offset:4
	ds_write_b32 v226, v196 offset:8
	ds_write_b32 v226, v197 offset:12
	ds_write_b32 v226, v198 offset:4160
	ds_write_b32 v226, v199 offset:4164
	ds_write_b32 v226, v200 offset:4168
	ds_write_b32 v226, v201 offset:4172
	ds_write_b32 v226, v202 offset:8320
	ds_write_b32 v226, v203 offset:8324
	ds_write_b32 v226, v204 offset:8328
	ds_write_b32 v226, v205 offset:8332
	ds_write_b32 v226, v206 offset:12480
	ds_write_b32 v226, v207 offset:12484
	ds_write_b32 v226, v208 offset:12488
	ds_write_b32 v226, v209 offset:12492
	v_mad_u32_u24 v232, v235, s35, v236
	s_waitcnt lgkmcnt(0)
	s_barrier
	ds_read2_b32 v[194:195], v227 offset1:65
	ds_read2_b32 v[196:197], v227 offset0:130 offset1:195
	ds_read2_b32 v[198:199], v228 offset0:4 offset1:69
	ds_read2_b32 v[200:201], v228 offset0:134 offset1:199
	ds_read2_b32 v[202:203], v229 offset1:65
	ds_read2_b32 v[204:205], v229 offset0:130 offset1:195
	ds_read2_b32 v[206:207], v230 offset0:4 offset1:69
	ds_read2_b32 v[208:209], v230 offset0:134 offset1:199
	s_add_u32 s26, s20, s32
	s_addc_u32 s27, s21, 0
	s_waitcnt lgkmcnt(0)
	s_barrier
	v_cvt_pk_bf16_f32 v194, v194, v195
	v_cvt_pk_bf16_f32 v195, v196, v197
	v_cvt_pk_bf16_f32 v196, v198, v199
	v_cvt_pk_bf16_f32 v197, v200, v201
	v_cvt_pk_bf16_f32 v202, v202, v203
	v_cvt_pk_bf16_f32 v203, v204, v205
	v_cvt_pk_bf16_f32 v204, v206, v207
	v_cvt_pk_bf16_f32 v205, v208, v209
	global_store_dwordx4 v232, v[194:197], s[20:21]
	global_store_dwordx4 v232, v[202:205], s[26:27]
	v_readlane_b32 s20, v237, 24
	v_readlane_b32 s21, v237, 25
	v_readlane_b32 s32, v237, 26
	v_readlane_b32 s35, v237, 27
	ds_write_b32 v226, v210 offset:0
	ds_write_b32 v226, v211 offset:4
	ds_write_b32 v226, v212 offset:8
	ds_write_b32 v226, v213 offset:12
	ds_write_b32 v226, v214 offset:4160
	ds_write_b32 v226, v215 offset:4164
	ds_write_b32 v226, v216 offset:4168
	ds_write_b32 v226, v217 offset:4172
	ds_write_b32 v226, v218 offset:8320
	ds_write_b32 v226, v219 offset:8324
	ds_write_b32 v226, v220 offset:8328
	ds_write_b32 v226, v221 offset:8332
	ds_write_b32 v226, v222 offset:12480
	ds_write_b32 v226, v223 offset:12484
	ds_write_b32 v226, v224 offset:12488
	ds_write_b32 v226, v225 offset:12492
	v_mad_u32_u24 v232, v235, s35, v236
	s_waitcnt lgkmcnt(0)
	s_barrier
	ds_read2_b32 v[210:211], v227 offset1:65
	ds_read2_b32 v[212:213], v227 offset0:130 offset1:195
	ds_read2_b32 v[214:215], v228 offset0:4 offset1:69
	ds_read2_b32 v[216:217], v228 offset0:134 offset1:199
	ds_read2_b32 v[218:219], v229 offset1:65
	ds_read2_b32 v[220:221], v229 offset0:130 offset1:195
	ds_read2_b32 v[222:223], v230 offset0:4 offset1:69
	ds_read2_b32 v[224:225], v230 offset0:134 offset1:199
	s_add_u32 s26, s20, s32
	s_addc_u32 s27, s21, 0
	s_waitcnt lgkmcnt(0)
	s_barrier
	v_cvt_pk_bf16_f32 v210, v210, v211
	v_cvt_pk_bf16_f32 v211, v212, v213
	v_cvt_pk_bf16_f32 v212, v214, v215
	v_cvt_pk_bf16_f32 v213, v216, v217
	v_cvt_pk_bf16_f32 v218, v218, v219
	v_cvt_pk_bf16_f32 v219, v220, v221
	v_cvt_pk_bf16_f32 v220, v222, v223
	v_cvt_pk_bf16_f32 v221, v224, v225
	global_store_dwordx4 v232, v[210:213], s[20:21]
	global_store_dwordx4 v232, v[218:221], s[26:27]
	v_readlane_b32 s20, v237, 8
	v_readlane_b32 s21, v237, 9
	v_readlane_b32 s32, v237, 10
	v_readlane_b32 s35, v237, 11
	ds_write_b32 v226, v146 offset:0
	ds_write_b32 v226, v147 offset:4
	ds_write_b32 v226, v148 offset:8
	ds_write_b32 v226, v149 offset:12
	ds_write_b32 v226, v150 offset:4160
	ds_write_b32 v226, v151 offset:4164
	ds_write_b32 v226, v152 offset:4168
	ds_write_b32 v226, v153 offset:4172
	ds_write_b32 v226, v154 offset:8320
	ds_write_b32 v226, v155 offset:8324
	ds_write_b32 v226, v156 offset:8328
	ds_write_b32 v226, v157 offset:8332
	ds_write_b32 v226, v158 offset:12480
	ds_write_b32 v226, v159 offset:12484
	ds_write_b32 v226, v160 offset:12488
	ds_write_b32 v226, v161 offset:12492
	v_mad_u32_u24 v232, v235, s35, v236
	s_waitcnt lgkmcnt(0)
	s_barrier
	ds_read2_b32 v[146:147], v227 offset1:65
	ds_read2_b32 v[148:149], v227 offset0:130 offset1:195
	ds_read2_b32 v[150:151], v228 offset0:4 offset1:69
	ds_read2_b32 v[152:153], v228 offset0:134 offset1:199
	ds_read2_b32 v[154:155], v229 offset1:65
	ds_read2_b32 v[156:157], v229 offset0:130 offset1:195
	ds_read2_b32 v[158:159], v230 offset0:4 offset1:69
	ds_read2_b32 v[160:161], v230 offset0:134 offset1:199
	s_add_u32 s26, s20, s32
	s_addc_u32 s27, s21, 0
	s_waitcnt lgkmcnt(0)
	s_barrier
	v_cvt_pk_bf16_f32 v146, v146, v147
	v_cvt_pk_bf16_f32 v147, v148, v149
	v_cvt_pk_bf16_f32 v148, v150, v151
	v_cvt_pk_bf16_f32 v149, v152, v153
	v_cvt_pk_bf16_f32 v154, v154, v155
	v_cvt_pk_bf16_f32 v155, v156, v157
	v_cvt_pk_bf16_f32 v156, v158, v159
	v_cvt_pk_bf16_f32 v157, v160, v161
	global_store_dwordx4 v232, v[146:149], s[20:21]
	global_store_dwordx4 v232, v[154:157], s[26:27]
	s_branch .Lwcm0_done
.Lwcm0_tail2:
	s_waitcnt vmcnt(0)
	v_readlane_b32 s20, v237, 20
	v_readlane_b32 s21, v237, 21
	v_readlane_b32 s32, v237, 22
	v_readlane_b32 s35, v237, 23
	ds_write_b32 v226, v194 offset:0
	ds_write_b32 v226, v195 offset:4
	ds_write_b32 v226, v196 offset:8
	ds_write_b32 v226, v197 offset:12
	ds_write_b32 v226, v198 offset:4160
	ds_write_b32 v226, v199 offset:4164
	ds_write_b32 v226, v200 offset:4168
	ds_write_b32 v226, v201 offset:4172
	ds_write_b32 v226, v202 offset:8320
	ds_write_b32 v226, v203 offset:8324
	ds_write_b32 v226, v204 offset:8328
	ds_write_b32 v226, v205 offset:8332
	ds_write_b32 v226, v206 offset:12480
	ds_write_b32 v226, v207 offset:12484
	ds_write_b32 v226, v208 offset:12488
	ds_write_b32 v226, v209 offset:12492
	v_mad_u32_u24 v232, v235, s35, v236
	s_waitcnt lgkmcnt(0)
	s_barrier
	ds_read2_b32 v[194:195], v227 offset1:65
	ds_read2_b32 v[196:197], v227 offset0:130 offset1:195
	ds_read2_b32 v[198:199], v228 offset0:4 offset1:69
	ds_read2_b32 v[200:201], v228 offset0:134 offset1:199
	ds_read2_b32 v[202:203], v229 offset1:65
	ds_read2_b32 v[204:205], v229 offset0:130 offset1:195
	ds_read2_b32 v[206:207], v230 offset0:4 offset1:69
	ds_read2_b32 v[208:209], v230 offset0:134 offset1:199
	s_add_u32 s26, s20, s32
	s_addc_u32 s27, s21, 0
	s_waitcnt lgkmcnt(0)
	s_barrier
	v_cvt_pk_bf16_f32 v194, v194, v195
	v_cvt_pk_bf16_f32 v195, v196, v197
	v_cvt_pk_bf16_f32 v196, v198, v199
	v_cvt_pk_bf16_f32 v197, v200, v201
	v_cvt_pk_bf16_f32 v202, v202, v203
	v_cvt_pk_bf16_f32 v203, v204, v205
	v_cvt_pk_bf16_f32 v204, v206, v207
	v_cvt_pk_bf16_f32 v205, v208, v209
	global_store_dwordx4 v232, v[194:197], s[20:21]
	global_store_dwordx4 v232, v[202:205], s[26:27]
	v_readlane_b32 s20, v237, 24
	v_readlane_b32 s21, v237, 25
	v_readlane_b32 s32, v237, 26
	v_readlane_b32 s35, v237, 27
	ds_write_b32 v226, v210 offset:0
	ds_write_b32 v226, v211 offset:4
	ds_write_b32 v226, v212 offset:8
	ds_write_b32 v226, v213 offset:12
	ds_write_b32 v226, v214 offset:4160
	ds_write_b32 v226, v215 offset:4164
	ds_write_b32 v226, v216 offset:4168
	ds_write_b32 v226, v217 offset:4172
	ds_write_b32 v226, v218 offset:8320
	ds_write_b32 v226, v219 offset:8324
	ds_write_b32 v226, v220 offset:8328
	ds_write_b32 v226, v221 offset:8332
	ds_write_b32 v226, v222 offset:12480
	ds_write_b32 v226, v223 offset:12484
	ds_write_b32 v226, v224 offset:12488
	ds_write_b32 v226, v225 offset:12492
	v_mad_u32_u24 v232, v235, s35, v236
	s_waitcnt lgkmcnt(0)
	s_barrier
	ds_read2_b32 v[210:211], v227 offset1:65
	ds_read2_b32 v[212:213], v227 offset0:130 offset1:195
	ds_read2_b32 v[214:215], v228 offset0:4 offset1:69
	ds_read2_b32 v[216:217], v228 offset0:134 offset1:199
	ds_read2_b32 v[218:219], v229 offset1:65
	ds_read2_b32 v[220:221], v229 offset0:130 offset1:195
	ds_read2_b32 v[222:223], v230 offset0:4 offset1:69
	ds_read2_b32 v[224:225], v230 offset0:134 offset1:199
	s_add_u32 s26, s20, s32
	s_addc_u32 s27, s21, 0
	s_waitcnt lgkmcnt(0)
	s_barrier
	v_cvt_pk_bf16_f32 v210, v210, v211
	v_cvt_pk_bf16_f32 v211, v212, v213
	v_cvt_pk_bf16_f32 v212, v214, v215
	v_cvt_pk_bf16_f32 v213, v216, v217
	v_cvt_pk_bf16_f32 v218, v218, v219
	v_cvt_pk_bf16_f32 v219, v220, v221
	v_cvt_pk_bf16_f32 v220, v222, v223
	v_cvt_pk_bf16_f32 v221, v224, v225
	global_store_dwordx4 v232, v[210:213], s[20:21]
	global_store_dwordx4 v232, v[218:221], s[26:27]
	v_readlane_b32 s20, v237, 8
	v_readlane_b32 s21, v237, 9
	v_readlane_b32 s32, v237, 10
	v_readlane_b32 s35, v237, 11
	ds_write_b32 v226, v146 offset:0
	ds_write_b32 v226, v147 offset:4
	ds_write_b32 v226, v148 offset:8
	ds_write_b32 v226, v149 offset:12
	ds_write_b32 v226, v150 offset:4160
	ds_write_b32 v226, v151 offset:4164
	ds_write_b32 v226, v152 offset:4168
	ds_write_b32 v226, v153 offset:4172
	ds_write_b32 v226, v154 offset:8320
	ds_write_b32 v226, v155 offset:8324
	ds_write_b32 v226, v156 offset:8328
	ds_write_b32 v226, v157 offset:8332
	ds_write_b32 v226, v158 offset:12480
	ds_write_b32 v226, v159 offset:12484
	ds_write_b32 v226, v160 offset:12488
	ds_write_b32 v226, v161 offset:12492
	v_mad_u32_u24 v232, v235, s35, v236
	s_waitcnt lgkmcnt(0)
	s_barrier
	ds_read2_b32 v[146:147], v227 offset1:65
	ds_read2_b32 v[148:149], v227 offset0:130 offset1:195
	ds_read2_b32 v[150:151], v228 offset0:4 offset1:69
	ds_read2_b32 v[152:153], v228 offset0:134 offset1:199
	ds_read2_b32 v[154:155], v229 offset1:65
	ds_read2_b32 v[156:157], v229 offset0:130 offset1:195
	ds_read2_b32 v[158:159], v230 offset0:4 offset1:69
	ds_read2_b32 v[160:161], v230 offset0:134 offset1:199
	s_add_u32 s26, s20, s32
	s_addc_u32 s27, s21, 0
	s_waitcnt lgkmcnt(0)
	s_barrier
	v_cvt_pk_bf16_f32 v146, v146, v147
	v_cvt_pk_bf16_f32 v147, v148, v149
	v_cvt_pk_bf16_f32 v148, v150, v151
	v_cvt_pk_bf16_f32 v149, v152, v153
	v_cvt_pk_bf16_f32 v154, v154, v155
	v_cvt_pk_bf16_f32 v155, v156, v157
	v_cvt_pk_bf16_f32 v156, v158, v159
	v_cvt_pk_bf16_f32 v157, v160, v161
	global_store_dwordx4 v232, v[146:149], s[20:21]
	global_store_dwordx4 v232, v[154:157], s[26:27]
	v_readlane_b32 s20, v237, 12
	v_readlane_b32 s21, v237, 13
	v_readlane_b32 s32, v237, 14
	v_readlane_b32 s35, v237, 15
	ds_write_b32 v226, v162 offset:0
	ds_write_b32 v226, v163 offset:4
	ds_write_b32 v226, v164 offset:8
	ds_write_b32 v226, v165 offset:12
	ds_write_b32 v226, v166 offset:4160
	ds_write_b32 v226, v167 offset:4164
	ds_write_b32 v226, v168 offset:4168
	ds_write_b32 v226, v169 offset:4172
	ds_write_b32 v226, v170 offset:8320
	ds_write_b32 v226, v171 offset:8324
	ds_write_b32 v226, v172 offset:8328
	ds_write_b32 v226, v173 offset:8332
	ds_write_b32 v226, v174 offset:12480
	ds_write_b32 v226, v175 offset:12484
	ds_write_b32 v226, v176 offset:12488
	ds_write_b32 v226, v177 offset:12492
	v_mad_u32_u24 v232, v235, s35, v236
	s_waitcnt lgkmcnt(0)
	s_barrier
	ds_read2_b32 v[162:163], v227 offset1:65
	ds_read2_b32 v[164:165], v227 offset0:130 offset1:195
	ds_read2_b32 v[166:167], v228 offset0:4 offset1:69
	ds_read2_b32 v[168:169], v228 offset0:134 offset1:199
	ds_read2_b32 v[170:171], v229 offset1:65
	ds_read2_b32 v[172:173], v229 offset0:130 offset1:195
	ds_read2_b32 v[174:175], v230 offset0:4 offset1:69
	ds_read2_b32 v[176:177], v230 offset0:134 offset1:199
	s_add_u32 s26, s20, s32
	s_addc_u32 s27, s21, 0
	s_waitcnt lgkmcnt(0)
	s_barrier
	v_cvt_pk_bf16_f32 v162, v162, v163
	v_cvt_pk_bf16_f32 v163, v164, v165
	v_cvt_pk_bf16_f32 v164, v166, v167
	v_cvt_pk_bf16_f32 v165, v168, v169
	v_cvt_pk_bf16_f32 v170, v170, v171
	v_cvt_pk_bf16_f32 v171, v172, v173
	v_cvt_pk_bf16_f32 v172, v174, v175
	v_cvt_pk_bf16_f32 v173, v176, v177
	global_store_dwordx4 v232, v[162:165], s[20:21]
	global_store_dwordx4 v232, v[170:173], s[26:27]
	s_branch .Lwcm0_done
.Lwcm0_tail3:
	s_waitcnt vmcnt(0)
	v_readlane_b32 s20, v237, 24
	v_readlane_b32 s21, v237, 25
	v_readlane_b32 s32, v237, 26
	v_readlane_b32 s35, v237, 27
	ds_write_b32 v226, v210 offset:0
	ds_write_b32 v226, v211 offset:4
	ds_write_b32 v226, v212 offset:8
	ds_write_b32 v226, v213 offset:12
	ds_write_b32 v226, v214 offset:4160
	ds_write_b32 v226, v215 offset:4164
	ds_write_b32 v226, v216 offset:4168
	ds_write_b32 v226, v217 offset:4172
	ds_write_b32 v226, v218 offset:8320
	ds_write_b32 v226, v219 offset:8324
	ds_write_b32 v226, v220 offset:8328
	ds_write_b32 v226, v221 offset:8332
	ds_write_b32 v226, v222 offset:12480
	ds_write_b32 v226, v223 offset:12484
	ds_write_b32 v226, v224 offset:12488
	ds_write_b32 v226, v225 offset:12492
	v_mad_u32_u24 v232, v235, s35, v236
	s_waitcnt lgkmcnt(0)
	s_barrier
	ds_read2_b32 v[210:211], v227 offset1:65
	ds_read2_b32 v[212:213], v227 offset0:130 offset1:195
	ds_read2_b32 v[214:215], v228 offset0:4 offset1:69
	ds_read2_b32 v[216:217], v228 offset0:134 offset1:199
	ds_read2_b32 v[218:219], v229 offset1:65
	ds_read2_b32 v[220:221], v229 offset0:130 offset1:195
	ds_read2_b32 v[222:223], v230 offset0:4 offset1:69
	ds_read2_b32 v[224:225], v230 offset0:134 offset1:199
	s_add_u32 s26, s20, s32
	s_addc_u32 s27, s21, 0
	s_waitcnt lgkmcnt(0)
	s_barrier
	v_cvt_pk_bf16_f32 v210, v210, v211
	v_cvt_pk_bf16_f32 v211, v212, v213
	v_cvt_pk_bf16_f32 v212, v214, v215
	v_cvt_pk_bf16_f32 v213, v216, v217
	v_cvt_pk_bf16_f32 v218, v218, v219
	v_cvt_pk_bf16_f32 v219, v220, v221
	v_cvt_pk_bf16_f32 v220, v222, v223
	v_cvt_pk_bf16_f32 v221, v224, v225
	global_store_dwordx4 v232, v[210:213], s[20:21]
	global_store_dwordx4 v232, v[218:221], s[26:27]
	v_readlane_b32 s20, v237, 8
	v_readlane_b32 s21, v237, 9
	v_readlane_b32 s32, v237, 10
	v_readlane_b32 s35, v237, 11
	ds_write_b32 v226, v146 offset:0
	ds_write_b32 v226, v147 offset:4
	ds_write_b32 v226, v148 offset:8
	ds_write_b32 v226, v149 offset:12
	ds_write_b32 v226, v150 offset:4160
	ds_write_b32 v226, v151 offset:4164
	ds_write_b32 v226, v152 offset:4168
	ds_write_b32 v226, v153 offset:4172
	ds_write_b32 v226, v154 offset:8320
	ds_write_b32 v226, v155 offset:8324
	ds_write_b32 v226, v156 offset:8328
	ds_write_b32 v226, v157 offset:8332
	ds_write_b32 v226, v158 offset:12480
	ds_write_b32 v226, v159 offset:12484
	ds_write_b32 v226, v160 offset:12488
	ds_write_b32 v226, v161 offset:12492
	v_mad_u32_u24 v232, v235, s35, v236
	s_waitcnt lgkmcnt(0)
	s_barrier
	ds_read2_b32 v[146:147], v227 offset1:65
	ds_read2_b32 v[148:149], v227 offset0:130 offset1:195
	ds_read2_b32 v[150:151], v228 offset0:4 offset1:69
	ds_read2_b32 v[152:153], v228 offset0:134 offset1:199
	ds_read2_b32 v[154:155], v229 offset1:65
	ds_read2_b32 v[156:157], v229 offset0:130 offset1:195
	ds_read2_b32 v[158:159], v230 offset0:4 offset1:69
	ds_read2_b32 v[160:161], v230 offset0:134 offset1:199
	s_add_u32 s26, s20, s32
	s_addc_u32 s27, s21, 0
	s_waitcnt lgkmcnt(0)
	s_barrier
	v_cvt_pk_bf16_f32 v146, v146, v147
	v_cvt_pk_bf16_f32 v147, v148, v149
	v_cvt_pk_bf16_f32 v148, v150, v151
	v_cvt_pk_bf16_f32 v149, v152, v153
	v_cvt_pk_bf16_f32 v154, v154, v155
	v_cvt_pk_bf16_f32 v155, v156, v157
	v_cvt_pk_bf16_f32 v156, v158, v159
	v_cvt_pk_bf16_f32 v157, v160, v161
	global_store_dwordx4 v232, v[146:149], s[20:21]
	global_store_dwordx4 v232, v[154:157], s[26:27]
	v_readlane_b32 s20, v237, 12
	v_readlane_b32 s21, v237, 13
	v_readlane_b32 s32, v237, 14
	v_readlane_b32 s35, v237, 15
	ds_write_b32 v226, v162 offset:0
	ds_write_b32 v226, v163 offset:4
	ds_write_b32 v226, v164 offset:8
	ds_write_b32 v226, v165 offset:12
	ds_write_b32 v226, v166 offset:4160
	ds_write_b32 v226, v167 offset:4164
	ds_write_b32 v226, v168 offset:4168
	ds_write_b32 v226, v169 offset:4172
	ds_write_b32 v226, v170 offset:8320
	ds_write_b32 v226, v171 offset:8324
	ds_write_b32 v226, v172 offset:8328
	ds_write_b32 v226, v173 offset:8332
	ds_write_b32 v226, v174 offset:12480
	ds_write_b32 v226, v175 offset:12484
	ds_write_b32 v226, v176 offset:12488
	ds_write_b32 v226, v177 offset:12492
	v_mad_u32_u24 v232, v235, s35, v236
	s_waitcnt lgkmcnt(0)
	s_barrier
	ds_read2_b32 v[162:163], v227 offset1:65
	ds_read2_b32 v[164:165], v227 offset0:130 offset1:195
	ds_read2_b32 v[166:167], v228 offset0:4 offset1:69
	ds_read2_b32 v[168:169], v228 offset0:134 offset1:199
	ds_read2_b32 v[170:171], v229 offset1:65
	ds_read2_b32 v[172:173], v229 offset0:130 offset1:195
	ds_read2_b32 v[174:175], v230 offset0:4 offset1:69
	ds_read2_b32 v[176:177], v230 offset0:134 offset1:199
	s_add_u32 s26, s20, s32
	s_addc_u32 s27, s21, 0
	s_waitcnt lgkmcnt(0)
	s_barrier
	v_cvt_pk_bf16_f32 v162, v162, v163
	v_cvt_pk_bf16_f32 v163, v164, v165
	v_cvt_pk_bf16_f32 v164, v166, v167
	v_cvt_pk_bf16_f32 v165, v168, v169
	v_cvt_pk_bf16_f32 v170, v170, v171
	v_cvt_pk_bf16_f32 v171, v172, v173
	v_cvt_pk_bf16_f32 v172, v174, v175
	v_cvt_pk_bf16_f32 v173, v176, v177
	global_store_dwordx4 v232, v[162:165], s[20:21]
	global_store_dwordx4 v232, v[170:173], s[26:27]
	v_readlane_b32 s20, v237, 16
	v_readlane_b32 s21, v237, 17
	v_readlane_b32 s32, v237, 18
	v_readlane_b32 s35, v237, 19
	ds_write_b32 v226, v178 offset:0
	ds_write_b32 v226, v179 offset:4
	ds_write_b32 v226, v180 offset:8
	ds_write_b32 v226, v181 offset:12
	ds_write_b32 v226, v182 offset:4160
	ds_write_b32 v226, v183 offset:4164
	ds_write_b32 v226, v184 offset:4168
	ds_write_b32 v226, v185 offset:4172
	ds_write_b32 v226, v186 offset:8320
	ds_write_b32 v226, v187 offset:8324
	ds_write_b32 v226, v188 offset:8328
	ds_write_b32 v226, v189 offset:8332
	ds_write_b32 v226, v190 offset:12480
	ds_write_b32 v226, v191 offset:12484
	ds_write_b32 v226, v192 offset:12488
	ds_write_b32 v226, v193 offset:12492
	v_mad_u32_u24 v232, v235, s35, v236
	s_waitcnt lgkmcnt(0)
	s_barrier
	ds_read2_b32 v[178:179], v227 offset1:65
	ds_read2_b32 v[180:181], v227 offset0:130 offset1:195
	ds_read2_b32 v[182:183], v228 offset0:4 offset1:69
	ds_read2_b32 v[184:185], v228 offset0:134 offset1:199
	ds_read2_b32 v[186:187], v229 offset1:65
	ds_read2_b32 v[188:189], v229 offset0:130 offset1:195
	ds_read2_b32 v[190:191], v230 offset0:4 offset1:69
	ds_read2_b32 v[192:193], v230 offset0:134 offset1:199
	s_add_u32 s26, s20, s32
	s_addc_u32 s27, s21, 0
	s_waitcnt lgkmcnt(0)
	s_barrier
	v_cvt_pk_bf16_f32 v178, v178, v179
	v_cvt_pk_bf16_f32 v179, v180, v181
	v_cvt_pk_bf16_f32 v180, v182, v183
	v_cvt_pk_bf16_f32 v181, v184, v185
	v_cvt_pk_bf16_f32 v186, v186, v187
	v_cvt_pk_bf16_f32 v187, v188, v189
	v_cvt_pk_bf16_f32 v188, v190, v191
	v_cvt_pk_bf16_f32 v189, v192, v193
	global_store_dwordx4 v232, v[178:181], s[20:21]
	global_store_dwordx4 v232, v[186:189], s[26:27]
	s_branch .Lwcm0_done
.Lwcm0_tail4:
	s_waitcnt vmcnt(0)
	v_readlane_b32 s20, v237, 8
	v_readlane_b32 s21, v237, 9
	v_readlane_b32 s32, v237, 10
	v_readlane_b32 s35, v237, 11
	ds_write_b32 v226, v146 offset:0
	ds_write_b32 v226, v147 offset:4
	ds_write_b32 v226, v148 offset:8
	ds_write_b32 v226, v149 offset:12
	ds_write_b32 v226, v150 offset:4160
	ds_write_b32 v226, v151 offset:4164
	ds_write_b32 v226, v152 offset:4168
	ds_write_b32 v226, v153 offset:4172
	ds_write_b32 v226, v154 offset:8320
	ds_write_b32 v226, v155 offset:8324
	ds_write_b32 v226, v156 offset:8328
	ds_write_b32 v226, v157 offset:8332
	ds_write_b32 v226, v158 offset:12480
	ds_write_b32 v226, v159 offset:12484
	ds_write_b32 v226, v160 offset:12488
	ds_write_b32 v226, v161 offset:12492
	v_mad_u32_u24 v232, v235, s35, v236
	s_waitcnt lgkmcnt(0)
	s_barrier
	ds_read2_b32 v[146:147], v227 offset1:65
	ds_read2_b32 v[148:149], v227 offset0:130 offset1:195
	ds_read2_b32 v[150:151], v228 offset0:4 offset1:69
	ds_read2_b32 v[152:153], v228 offset0:134 offset1:199
	ds_read2_b32 v[154:155], v229 offset1:65
	ds_read2_b32 v[156:157], v229 offset0:130 offset1:195
	ds_read2_b32 v[158:159], v230 offset0:4 offset1:69
	ds_read2_b32 v[160:161], v230 offset0:134 offset1:199
	s_add_u32 s26, s20, s32
	s_addc_u32 s27, s21, 0
	s_waitcnt lgkmcnt(0)
	s_barrier
	v_cvt_pk_bf16_f32 v146, v146, v147
	v_cvt_pk_bf16_f32 v147, v148, v149
	v_cvt_pk_bf16_f32 v148, v150, v151
	v_cvt_pk_bf16_f32 v149, v152, v153
	v_cvt_pk_bf16_f32 v154, v154, v155
	v_cvt_pk_bf16_f32 v155, v156, v157
	v_cvt_pk_bf16_f32 v156, v158, v159
	v_cvt_pk_bf16_f32 v157, v160, v161
	global_store_dwordx4 v232, v[146:149], s[20:21]
	global_store_dwordx4 v232, v[154:157], s[26:27]
	v_readlane_b32 s20, v237, 12
	v_readlane_b32 s21, v237, 13
	v_readlane_b32 s32, v237, 14
	v_readlane_b32 s35, v237, 15
	ds_write_b32 v226, v162 offset:0
	ds_write_b32 v226, v163 offset:4
	ds_write_b32 v226, v164 offset:8
	ds_write_b32 v226, v165 offset:12
	ds_write_b32 v226, v166 offset:4160
	ds_write_b32 v226, v167 offset:4164
	ds_write_b32 v226, v168 offset:4168
	ds_write_b32 v226, v169 offset:4172
	ds_write_b32 v226, v170 offset:8320
	ds_write_b32 v226, v171 offset:8324
	ds_write_b32 v226, v172 offset:8328
	ds_write_b32 v226, v173 offset:8332
	ds_write_b32 v226, v174 offset:12480
	ds_write_b32 v226, v175 offset:12484
	ds_write_b32 v226, v176 offset:12488
	ds_write_b32 v226, v177 offset:12492
	v_mad_u32_u24 v232, v235, s35, v236
	s_waitcnt lgkmcnt(0)
	s_barrier
	ds_read2_b32 v[162:163], v227 offset1:65
	ds_read2_b32 v[164:165], v227 offset0:130 offset1:195
	ds_read2_b32 v[166:167], v228 offset0:4 offset1:69
	ds_read2_b32 v[168:169], v228 offset0:134 offset1:199
	ds_read2_b32 v[170:171], v229 offset1:65
	ds_read2_b32 v[172:173], v229 offset0:130 offset1:195
	ds_read2_b32 v[174:175], v230 offset0:4 offset1:69
	ds_read2_b32 v[176:177], v230 offset0:134 offset1:199
	s_add_u32 s26, s20, s32
	s_addc_u32 s27, s21, 0
	s_waitcnt lgkmcnt(0)
	s_barrier
	v_cvt_pk_bf16_f32 v162, v162, v163
	v_cvt_pk_bf16_f32 v163, v164, v165
	v_cvt_pk_bf16_f32 v164, v166, v167
	v_cvt_pk_bf16_f32 v165, v168, v169
	v_cvt_pk_bf16_f32 v170, v170, v171
	v_cvt_pk_bf16_f32 v171, v172, v173
	v_cvt_pk_bf16_f32 v172, v174, v175
	v_cvt_pk_bf16_f32 v173, v176, v177
	global_store_dwordx4 v232, v[162:165], s[20:21]
	global_store_dwordx4 v232, v[170:173], s[26:27]
	v_readlane_b32 s20, v237, 16
	v_readlane_b32 s21, v237, 17
	v_readlane_b32 s32, v237, 18
	v_readlane_b32 s35, v237, 19
	ds_write_b32 v226, v178 offset:0
	ds_write_b32 v226, v179 offset:4
	ds_write_b32 v226, v180 offset:8
	ds_write_b32 v226, v181 offset:12
	ds_write_b32 v226, v182 offset:4160
	ds_write_b32 v226, v183 offset:4164
	ds_write_b32 v226, v184 offset:4168
	ds_write_b32 v226, v185 offset:4172
	ds_write_b32 v226, v186 offset:8320
	ds_write_b32 v226, v187 offset:8324
	ds_write_b32 v226, v188 offset:8328
	ds_write_b32 v226, v189 offset:8332
	ds_write_b32 v226, v190 offset:12480
	ds_write_b32 v226, v191 offset:12484
	ds_write_b32 v226, v192 offset:12488
	ds_write_b32 v226, v193 offset:12492
	v_mad_u32_u24 v232, v235, s35, v236
	s_waitcnt lgkmcnt(0)
	s_barrier
	ds_read2_b32 v[178:179], v227 offset1:65
	ds_read2_b32 v[180:181], v227 offset0:130 offset1:195
	ds_read2_b32 v[182:183], v228 offset0:4 offset1:69
	ds_read2_b32 v[184:185], v228 offset0:134 offset1:199
	ds_read2_b32 v[186:187], v229 offset1:65
	ds_read2_b32 v[188:189], v229 offset0:130 offset1:195
	ds_read2_b32 v[190:191], v230 offset0:4 offset1:69
	ds_read2_b32 v[192:193], v230 offset0:134 offset1:199
	s_add_u32 s26, s20, s32
	s_addc_u32 s27, s21, 0
	s_waitcnt lgkmcnt(0)
	s_barrier
	v_cvt_pk_bf16_f32 v178, v178, v179
	v_cvt_pk_bf16_f32 v179, v180, v181
	v_cvt_pk_bf16_f32 v180, v182, v183
	v_cvt_pk_bf16_f32 v181, v184, v185
	v_cvt_pk_bf16_f32 v186, v186, v187
	v_cvt_pk_bf16_f32 v187, v188, v189
	v_cvt_pk_bf16_f32 v188, v190, v191
	v_cvt_pk_bf16_f32 v189, v192, v193
	global_store_dwordx4 v232, v[178:181], s[20:21]
	global_store_dwordx4 v232, v[186:189], s[26:27]
	v_readlane_b32 s20, v237, 20
	v_readlane_b32 s21, v237, 21
	v_readlane_b32 s32, v237, 22
	v_readlane_b32 s35, v237, 23
	ds_write_b32 v226, v194 offset:0
	ds_write_b32 v226, v195 offset:4
	ds_write_b32 v226, v196 offset:8
	ds_write_b32 v226, v197 offset:12
	ds_write_b32 v226, v198 offset:4160
	ds_write_b32 v226, v199 offset:4164
	ds_write_b32 v226, v200 offset:4168
	ds_write_b32 v226, v201 offset:4172
	ds_write_b32 v226, v202 offset:8320
	ds_write_b32 v226, v203 offset:8324
	ds_write_b32 v226, v204 offset:8328
	ds_write_b32 v226, v205 offset:8332
	ds_write_b32 v226, v206 offset:12480
	ds_write_b32 v226, v207 offset:12484
	ds_write_b32 v226, v208 offset:12488
	ds_write_b32 v226, v209 offset:12492
	v_mad_u32_u24 v232, v235, s35, v236
	s_waitcnt lgkmcnt(0)
	s_barrier
	ds_read2_b32 v[194:195], v227 offset1:65
	ds_read2_b32 v[196:197], v227 offset0:130 offset1:195
	ds_read2_b32 v[198:199], v228 offset0:4 offset1:69
	ds_read2_b32 v[200:201], v228 offset0:134 offset1:199
	ds_read2_b32 v[202:203], v229 offset1:65
	ds_read2_b32 v[204:205], v229 offset0:130 offset1:195
	ds_read2_b32 v[206:207], v230 offset0:4 offset1:69
	ds_read2_b32 v[208:209], v230 offset0:134 offset1:199
	s_add_u32 s26, s20, s32
	s_addc_u32 s27, s21, 0
	s_waitcnt lgkmcnt(0)
	s_barrier
	v_cvt_pk_bf16_f32 v194, v194, v195
	v_cvt_pk_bf16_f32 v195, v196, v197
	v_cvt_pk_bf16_f32 v196, v198, v199
	v_cvt_pk_bf16_f32 v197, v200, v201
	v_cvt_pk_bf16_f32 v202, v202, v203
	v_cvt_pk_bf16_f32 v203, v204, v205
	v_cvt_pk_bf16_f32 v204, v206, v207
	v_cvt_pk_bf16_f32 v205, v208, v209
	global_store_dwordx4 v232, v[194:197], s[20:21]
	global_store_dwordx4 v232, v[202:205], s[26:27]
	s_branch .Lwcm0_done

.Lwcm0_p3:
	s_waitcnt vmcnt(0)
	v_readlane_b32 s20, v237, 8
	v_readlane_b32 s21, v237, 9
	v_readlane_b32 s32, v237, 10
	v_readlane_b32 s35, v237, 11
	ds_write_b32 v226, v146 offset:0
	ds_write_b32 v226, v147 offset:4
	ds_write_b32 v226, v148 offset:8
	ds_write_b32 v226, v149 offset:12
	ds_write_b32 v226, v150 offset:4160
	ds_write_b32 v226, v151 offset:4164
	ds_write_b32 v226, v152 offset:4168
	ds_write_b32 v226, v153 offset:4172
	ds_write_b32 v226, v154 offset:8320
	ds_write_b32 v226, v155 offset:8324
	ds_write_b32 v226, v156 offset:8328
	ds_write_b32 v226, v157 offset:8332
	ds_write_b32 v226, v158 offset:12480
	ds_write_b32 v226, v159 offset:12484
	ds_write_b32 v226, v160 offset:12488
	ds_write_b32 v226, v161 offset:12492
	v_mad_u32_u24 v232, v235, s35, v236
	s_waitcnt lgkmcnt(0)
	s_barrier
	ds_read2_b32 v[146:147], v227 offset1:65
	ds_read2_b32 v[148:149], v227 offset0:130 offset1:195
	ds_read2_b32 v[150:151], v228 offset0:4 offset1:69
	ds_read2_b32 v[152:153], v228 offset0:134 offset1:199
	ds_read2_b32 v[154:155], v229 offset1:65
	ds_read2_b32 v[156:157], v229 offset0:130 offset1:195
	ds_read2_b32 v[158:159], v230 offset0:4 offset1:69
	ds_read2_b32 v[160:161], v230 offset0:134 offset1:199
	s_add_u32 s26, s20, s32
	s_addc_u32 s27, s21, 0
	s_waitcnt lgkmcnt(0)
	s_barrier
	v_cvt_pk_bf16_f32 v146, v146, v147
	v_cvt_pk_bf16_f32 v147, v148, v149
	v_cvt_pk_bf16_f32 v148, v150, v151
	v_cvt_pk_bf16_f32 v149, v152, v153
	v_cvt_pk_bf16_f32 v154, v154, v155
	v_cvt_pk_bf16_f32 v155, v156, v157
	v_cvt_pk_bf16_f32 v156, v158, v159
	v_cvt_pk_bf16_f32 v157, v160, v161
	global_store_dwordx4 v232, v[146:149], s[20:21]
	global_store_dwordx4 v232, v[154:157], s[26:27]
	v_readlane_b32 s20, v237, 12
	v_readlane_b32 s21, v237, 13
	v_readlane_b32 s32, v237, 14
	v_readlane_b32 s35, v237, 15
	ds_write_b32 v226, v162 offset:0
	ds_write_b32 v226, v163 offset:4
	ds_write_b32 v226, v164 offset:8
	ds_write_b32 v226, v165 offset:12
	ds_write_b32 v226, v166 offset:4160
	ds_write_b32 v226, v167 offset:4164
	ds_write_b32 v226, v168 offset:4168
	ds_write_b32 v226, v169 offset:4172
	ds_write_b32 v226, v170 offset:8320
	ds_write_b32 v226, v171 offset:8324
	ds_write_b32 v226, v172 offset:8328
	ds_write_b32 v226, v173 offset:8332
	ds_write_b32 v226, v174 offset:12480
	ds_write_b32 v226, v175 offset:12484
	ds_write_b32 v226, v176 offset:12488
	ds_write_b32 v226, v177 offset:12492
	v_mad_u32_u24 v232, v235, s35, v236
	s_waitcnt lgkmcnt(0)
	s_barrier
	ds_read2_b32 v[162:163], v227 offset1:65
	ds_read2_b32 v[164:165], v227 offset0:130 offset1:195
	ds_read2_b32 v[166:167], v228 offset0:4 offset1:69
	ds_read2_b32 v[168:169], v228 offset0:134 offset1:199
	ds_read2_b32 v[170:171], v229 offset1:65
	ds_read2_b32 v[172:173], v229 offset0:130 offset1:195
	ds_read2_b32 v[174:175], v230 offset0:4 offset1:69
	ds_read2_b32 v[176:177], v230 offset0:134 offset1:199
	s_add_u32 s26, s20, s32
	s_addc_u32 s27, s21, 0
	s_waitcnt lgkmcnt(0)
	s_barrier
	v_cvt_pk_bf16_f32 v162, v162, v163
	v_cvt_pk_bf16_f32 v163, v164, v165
	v_cvt_pk_bf16_f32 v164, v166, v167
	v_cvt_pk_bf16_f32 v165, v168, v169
	v_cvt_pk_bf16_f32 v170, v170, v171
	v_cvt_pk_bf16_f32 v171, v172, v173
	v_cvt_pk_bf16_f32 v172, v174, v175
	v_cvt_pk_bf16_f32 v173, v176, v177
	global_store_dwordx4 v232, v[162:165], s[20:21]
	global_store_dwordx4 v232, v[170:173], s[26:27]
	v_readlane_b32 s20, v237, 16
	v_readlane_b32 s21, v237, 17
	v_readlane_b32 s32, v237, 18
	v_readlane_b32 s35, v237, 19
	ds_write_b32 v226, v178 offset:0
	ds_write_b32 v226, v179 offset:4
	ds_write_b32 v226, v180 offset:8
	ds_write_b32 v226, v181 offset:12
	ds_write_b32 v226, v182 offset:4160
	ds_write_b32 v226, v183 offset:4164
	ds_write_b32 v226, v184 offset:4168
	ds_write_b32 v226, v185 offset:4172
	ds_write_b32 v226, v186 offset:8320
	ds_write_b32 v226, v187 offset:8324
	ds_write_b32 v226, v188 offset:8328
	ds_write_b32 v226, v189 offset:8332
	ds_write_b32 v226, v190 offset:12480
	ds_write_b32 v226, v191 offset:12484
	ds_write_b32 v226, v192 offset:12488
	ds_write_b32 v226, v193 offset:12492
	v_mad_u32_u24 v232, v235, s35, v236
	s_waitcnt lgkmcnt(0)
	s_barrier
	ds_read2_b32 v[178:179], v227 offset1:65
	ds_read2_b32 v[180:181], v227 offset0:130 offset1:195
	ds_read2_b32 v[182:183], v228 offset0:4 offset1:69
	ds_read2_b32 v[184:185], v228 offset0:134 offset1:199
	ds_read2_b32 v[186:187], v229 offset1:65
	ds_read2_b32 v[188:189], v229 offset0:130 offset1:195
	ds_read2_b32 v[190:191], v230 offset0:4 offset1:69
	ds_read2_b32 v[192:193], v230 offset0:134 offset1:199
	s_add_u32 s26, s20, s32
	s_addc_u32 s27, s21, 0
	s_waitcnt lgkmcnt(0)
	s_barrier
	v_cvt_pk_bf16_f32 v178, v178, v179
	v_cvt_pk_bf16_f32 v179, v180, v181
	v_cvt_pk_bf16_f32 v180, v182, v183
	v_cvt_pk_bf16_f32 v181, v184, v185
	v_cvt_pk_bf16_f32 v186, v186, v187
	v_cvt_pk_bf16_f32 v187, v188, v189
	v_cvt_pk_bf16_f32 v188, v190, v191
	v_cvt_pk_bf16_f32 v189, v192, v193
	global_store_dwordx4 v232, v[178:181], s[20:21]
	global_store_dwordx4 v232, v[186:189], s[26:27]
	s_branch .Lwcm0_done
.Lwcm0_p2:
	s_waitcnt vmcnt(0)
	v_readlane_b32 s20, v237, 8
	v_readlane_b32 s21, v237, 9
	v_readlane_b32 s32, v237, 10
	v_readlane_b32 s35, v237, 11
	ds_write_b32 v226, v146 offset:0
	ds_write_b32 v226, v147 offset:4
	ds_write_b32 v226, v148 offset:8
	ds_write_b32 v226, v149 offset:12
	ds_write_b32 v226, v150 offset:4160
	ds_write_b32 v226, v151 offset:4164
	ds_write_b32 v226, v152 offset:4168
	ds_write_b32 v226, v153 offset:4172
	ds_write_b32 v226, v154 offset:8320
	ds_write_b32 v226, v155 offset:8324
	ds_write_b32 v226, v156 offset:8328
	ds_write_b32 v226, v157 offset:8332
	ds_write_b32 v226, v158 offset:12480
	ds_write_b32 v226, v159 offset:12484
	ds_write_b32 v226, v160 offset:12488
	ds_write_b32 v226, v161 offset:12492
	v_mad_u32_u24 v232, v235, s35, v236
	s_waitcnt lgkmcnt(0)
	s_barrier
	ds_read2_b32 v[146:147], v227 offset1:65
	ds_read2_b32 v[148:149], v227 offset0:130 offset1:195
	ds_read2_b32 v[150:151], v228 offset0:4 offset1:69
	ds_read2_b32 v[152:153], v228 offset0:134 offset1:199
	ds_read2_b32 v[154:155], v229 offset1:65
	ds_read2_b32 v[156:157], v229 offset0:130 offset1:195
	ds_read2_b32 v[158:159], v230 offset0:4 offset1:69
	ds_read2_b32 v[160:161], v230 offset0:134 offset1:199
	s_add_u32 s26, s20, s32
	s_addc_u32 s27, s21, 0
	s_waitcnt lgkmcnt(0)
	s_barrier
	v_cvt_pk_bf16_f32 v146, v146, v147
	v_cvt_pk_bf16_f32 v147, v148, v149
	v_cvt_pk_bf16_f32 v148, v150, v151
	v_cvt_pk_bf16_f32 v149, v152, v153
	v_cvt_pk_bf16_f32 v154, v154, v155
	v_cvt_pk_bf16_f32 v155, v156, v157
	v_cvt_pk_bf16_f32 v156, v158, v159
	v_cvt_pk_bf16_f32 v157, v160, v161
	global_store_dwordx4 v232, v[146:149], s[20:21]
	global_store_dwordx4 v232, v[154:157], s[26:27]
	v_readlane_b32 s20, v237, 12
	v_readlane_b32 s21, v237, 13
	v_readlane_b32 s32, v237, 14
	v_readlane_b32 s35, v237, 15
	ds_write_b32 v226, v162 offset:0
	ds_write_b32 v226, v163 offset:4
	ds_write_b32 v226, v164 offset:8
	ds_write_b32 v226, v165 offset:12
	ds_write_b32 v226, v166 offset:4160
	ds_write_b32 v226, v167 offset:4164
	ds_write_b32 v226, v168 offset:4168
	ds_write_b32 v226, v169 offset:4172
	ds_write_b32 v226, v170 offset:8320
	ds_write_b32 v226, v171 offset:8324
	ds_write_b32 v226, v172 offset:8328
	ds_write_b32 v226, v173 offset:8332
	ds_write_b32 v226, v174 offset:12480
	ds_write_b32 v226, v175 offset:12484
	ds_write_b32 v226, v176 offset:12488
	ds_write_b32 v226, v177 offset:12492
	v_mad_u32_u24 v232, v235, s35, v236
	s_waitcnt lgkmcnt(0)
	s_barrier
	ds_read2_b32 v[162:163], v227 offset1:65
	ds_read2_b32 v[164:165], v227 offset0:130 offset1:195
	ds_read2_b32 v[166:167], v228 offset0:4 offset1:69
	ds_read2_b32 v[168:169], v228 offset0:134 offset1:199
	ds_read2_b32 v[170:171], v229 offset1:65
	ds_read2_b32 v[172:173], v229 offset0:130 offset1:195
	ds_read2_b32 v[174:175], v230 offset0:4 offset1:69
	ds_read2_b32 v[176:177], v230 offset0:134 offset1:199
	s_add_u32 s26, s20, s32
	s_addc_u32 s27, s21, 0
	s_waitcnt lgkmcnt(0)
	s_barrier
	v_cvt_pk_bf16_f32 v162, v162, v163
	v_cvt_pk_bf16_f32 v163, v164, v165
	v_cvt_pk_bf16_f32 v164, v166, v167
	v_cvt_pk_bf16_f32 v165, v168, v169
	v_cvt_pk_bf16_f32 v170, v170, v171
	v_cvt_pk_bf16_f32 v171, v172, v173
	v_cvt_pk_bf16_f32 v172, v174, v175
	v_cvt_pk_bf16_f32 v173, v176, v177
	global_store_dwordx4 v232, v[162:165], s[20:21]
	global_store_dwordx4 v232, v[170:173], s[26:27]
	s_branch .Lwcm0_done
.Lwcm0_p1:
	s_waitcnt vmcnt(0)
	v_readlane_b32 s20, v237, 8
	v_readlane_b32 s21, v237, 9
	v_readlane_b32 s32, v237, 10
	v_readlane_b32 s35, v237, 11
	ds_write_b32 v226, v146 offset:0
	ds_write_b32 v226, v147 offset:4
	ds_write_b32 v226, v148 offset:8
	ds_write_b32 v226, v149 offset:12
	ds_write_b32 v226, v150 offset:4160
	ds_write_b32 v226, v151 offset:4164
	ds_write_b32 v226, v152 offset:4168
	ds_write_b32 v226, v153 offset:4172
	ds_write_b32 v226, v154 offset:8320
	ds_write_b32 v226, v155 offset:8324
	ds_write_b32 v226, v156 offset:8328
	ds_write_b32 v226, v157 offset:8332
	ds_write_b32 v226, v158 offset:12480
	ds_write_b32 v226, v159 offset:12484
	ds_write_b32 v226, v160 offset:12488
	ds_write_b32 v226, v161 offset:12492
	v_mad_u32_u24 v232, v235, s35, v236
	s_waitcnt lgkmcnt(0)
	s_barrier
	ds_read2_b32 v[146:147], v227 offset1:65
	ds_read2_b32 v[148:149], v227 offset0:130 offset1:195
	ds_read2_b32 v[150:151], v228 offset0:4 offset1:69
	ds_read2_b32 v[152:153], v228 offset0:134 offset1:199
	ds_read2_b32 v[154:155], v229 offset1:65
	ds_read2_b32 v[156:157], v229 offset0:130 offset1:195
	ds_read2_b32 v[158:159], v230 offset0:4 offset1:69
	ds_read2_b32 v[160:161], v230 offset0:134 offset1:199
	s_add_u32 s26, s20, s32
	s_addc_u32 s27, s21, 0
	s_waitcnt lgkmcnt(0)
	s_barrier
	v_cvt_pk_bf16_f32 v146, v146, v147
	v_cvt_pk_bf16_f32 v147, v148, v149
	v_cvt_pk_bf16_f32 v148, v150, v151
	v_cvt_pk_bf16_f32 v149, v152, v153
	v_cvt_pk_bf16_f32 v154, v154, v155
	v_cvt_pk_bf16_f32 v155, v156, v157
	v_cvt_pk_bf16_f32 v156, v158, v159
	v_cvt_pk_bf16_f32 v157, v160, v161
	global_store_dwordx4 v232, v[146:149], s[20:21]
	global_store_dwordx4 v232, v[154:157], s[26:27]
.Lwcm0_done:
	s_waitcnt vmcnt(0) lgkmcnt(0)
	s_barrier
	v_readlane_b32 s99, v242, 0
	s_nop 0
	s_sub_u32 s100, s99, 0x100
	s_movk_i32 s23, 96
	s_movk_i32 s22, 0xbc0
	s_waitcnt vmcnt(0) lgkmcnt(0)
	s_barrier
	v_readlane_b32 s0, v242, 42
	v_readlane_b32 s1, v242, 43
	v_readlane_b32 s12, v242, 3
	v_readlane_b32 s13, v242, 4
	v_lshrrev_b32_e32 v233, 4, v137
	v_and_b32_e32 v234, 15, v137
	v_lshlrev_b32_e32 v234, 2, v234
	s_sub_u32 s0, s0, 0x118
	s_subb_u32 s1, s1, 0
	v_lshrrev_b32_e32 v235, 3, v137
	v_and_b32_e32 v236, 7, v137
	v_mul_u32_u24_e32 v226, 65, v233
	v_mul_u32_u24_e32 v227, 0x208, v236
	v_add_u32_e32 v226, v226, v234
	v_add_u32_e32 v227, v227, v235
	v_lshlrev_b32_e32 v226, 2, v226
	v_lshlrev_b32_e32 v227, 2, v227
	v_lshlrev_b32_e32 v234, 2, v234
	v_lshlrev_b32_e32 v236, 4, v236
	v_add_u32_e32 v228, 0x400, v227
	v_add_u32_e32 v229, 0x80, v227
	v_add_u32_e32 v230, 0x480, v227
	s_cmp_ge_u32 s100, s22
	s_cbranch_scc1 .Lwcm1_done
	s_cmpk_ge_u32 s100, 0x900
	s_cbranch_scc1 .Lwcm1_t3_1
	s_cmpk_ge_u32 s100, 0x380
	s_cbranch_scc1 .Lwcm1_t2_1
	s_cmpk_ge_u32 s100, 0x280
	s_cbranch_scc1 .Lwcm1_t1_1
	s_movk_i32 s14, 0x78
	s_sub_u32 s99, s100, 0
	s_mul_i32 s44, s99, 0x66667
	s_lshr_b32 s44, s44, 24
	s_mul_i32 s36, s44, 40
	s_sub_u32 s99, s99, s36
	s_mul_i32 s38, s44, 0xa0000
	s_lshl_b32 s36, s99, 8
	s_add_u32 s38, s38, s36
	s_add_u32 s38, s38, 0xa00000
	s_lshl_b32 s36, s99, 6
	s_mov_b32 s32, 0x10000
	s_mul_i32 s36, s36, 0x800
	s_lshl_b32 s44, s44, 7
	s_add_u32 s36, s36, s44
	s_add_u32 s36, s36, 0x500000
	s_mov_b32 s37, 0x28000
	s_movk_i32 s44, 0x800
	s_mov_b32 s99, 0x2800
	s_branch .Lwcm1_tj_1
.Lwcm1_t1_1:
	s_movk_i32 s14, 0x80
	s_sub_u32 s99, s100, 640
	s_mul_i32 s44, s99, 0x100000
	s_lshr_b32 s44, s44, 24
	s_mul_i32 s36, s44, 16
	s_sub_u32 s99, s99, s36
	s_mul_i32 s38, s44, 0x40000
	s_lshl_b32 s36, s99, 8
	s_add_u32 s38, s38, s36
	s_add_u32 s38, s38, 0x400000
	s_lshl_b32 s36, s99, 6
	s_mov_b32 s32, 0x10000
	s_mul_i32 s36, s36, 0x800
	s_lshl_b32 s44, s44, 7
	s_add_u32 s36, s36, s44
	s_add_u32 s36, s36, 0xc00000
	s_mov_b32 s37, 0x10000
	s_movk_i32 s44, 0x800
	s_mov_b32 s99, 0x1000
	s_branch .Lwcm1_tj_1
.Lwcm1_t2_1:
	s_movk_i32 s14, 0xf0
	s_sub_u32 s99, s100, 896
	s_mul_i32 s44, s99, 0x2e8bb
	s_lshr_b32 s44, s44, 24
	s_mul_i32 s36, s44, 88
	s_sub_u32 s99, s99, s36
	s_mul_i32 s38, s44, 0x160000
	s_lshl_b32 s36, s99, 8
	s_add_u32 s38, s38, s36
	s_add_u32 s38, s38, 0x1600000
	s_cmpk_ge_u32 s99, 44
	s_cselect_b32 s36, 44, 0
	s_cselect_b32 s37, 32, 0
	s_sub_u32 s36, s99, s36
	s_lshl_b32 s36, s36, 7
	s_add_u32 s36, s36, s37
	s_mov_b32 s32, 0x20000
	s_mul_i32 s36, s36, 0x800
	s_lshl_b32 s44, s44, 7
	s_add_u32 s36, s36, s44
	s_add_u32 s36, s36, 0x1900000
	s_mov_b32 s37, 0x58000
	s_movk_i32 s44, 0x800
	s_mov_b32 s99, 0x5800
	s_branch .Lwcm1_tj_1
.Lwcm1_t3_1:
	s_movk_i32 s14, 0xf8
	s_sub_u32 s99, s100, 2304
	s_mul_i32 s44, s99, 0x100000
	s_lshr_b32 s44, s44, 24
	s_mul_i32 s36, s44, 16
	s_sub_u32 s99, s99, s36
	s_mul_i32 s38, s44, 0x40000
	s_lshl_b32 s36, s99, 8
	s_add_u32 s38, s38, s36
	s_add_u32 s38, s38, 0xb00000
	s_lshl_b32 s36, s99, 6
	s_mov_b32 s32, 0x2c000
	s_mul_i32 s36, s36, 0x1600
	s_lshl_b32 s44, s44, 7
	s_add_u32 s36, s36, s44
	s_add_u32 s36, s36, 0x2980000
	s_mov_b32 s37, 0x10000
	s_movk_i32 s44, 0x1600
	s_mov_b32 s99, 0x1000
.Lwcm1_tj_1:
	s_load_dwordx2 s[8:9], s[0:1], s14
	s_add_u32 s20, s12, s36
	s_addc_u32 s21, s13, 0
	v_mad_u32_u24 v231, v233, s99, v234
	v_writelane_b32 v237, s20, 8
	v_writelane_b32 v237, s21, 9
	v_writelane_b32 v237, s32, 10
	v_writelane_b32 v237, s44, 11
	s_add_u32 s100, s100, s23
	s_waitcnt lgkmcnt(0)
	s_add_u32 s38, s8, s38
	s_addc_u32 s39, s9, 0
	global_load_dwordx4 v[146:149], v231, s[38:39]
	s_add_u32 s38, s38, s37
	s_addc_u32 s39, s39, 0
	global_load_dwordx4 v[150:153], v231, s[38:39]
	s_add_u32 s38, s38, s37
	s_addc_u32 s39, s39, 0
	global_load_dwordx4 v[154:157], v231, s[38:39]
	s_add_u32 s38, s38, s37
	s_addc_u32 s39, s39, 0
	global_load_dwordx4 v[158:161], v231, s[38:39]
	s_cmp_ge_u32 s100, s22
	s_cbranch_scc1 .Lwcm1_p1
	s_cmpk_ge_u32 s100, 0x900
	s_cbranch_scc1 .Lwcm1_t3_2
	s_cmpk_ge_u32 s100, 0x380
	s_cbranch_scc1 .Lwcm1_t2_2
	s_cmpk_ge_u32 s100, 0x280
	s_cbranch_scc1 .Lwcm1_t1_2
	s_movk_i32 s14, 0x78
	s_sub_u32 s99, s100, 0
	s_mul_i32 s44, s99, 0x66667
	s_lshr_b32 s44, s44, 24
	s_mul_i32 s36, s44, 40
	s_sub_u32 s99, s99, s36
	s_mul_i32 s38, s44, 0xa0000
	s_lshl_b32 s36, s99, 8
	s_add_u32 s38, s38, s36
	s_add_u32 s38, s38, 0xa00000
	s_lshl_b32 s36, s99, 6
	s_mov_b32 s32, 0x10000
	s_mul_i32 s36, s36, 0x800
	s_lshl_b32 s44, s44, 7
	s_add_u32 s36, s36, s44
	s_add_u32 s36, s36, 0x500000
	s_mov_b32 s37, 0x28000
	s_movk_i32 s44, 0x800
	s_mov_b32 s99, 0x2800
	s_branch .Lwcm1_tj_2

.Lwcm1_tj_2:
	s_load_dwordx2 s[8:9], s[0:1], s14
	s_add_u32 s20, s12, s36
	s_addc_u32 s21, s13, 0
	v_mad_u32_u24 v231, v233, s99, v234
	v_writelane_b32 v237, s20, 12
	v_writelane_b32 v237, s21, 13
	v_writelane_b32 v237, s32, 14
	v_writelane_b32 v237, s44, 15
	s_add_u32 s100, s100, s23
	s_waitcnt lgkmcnt(0)
	s_add_u32 s38, s8, s38
	s_addc_u32 s39, s9, 0
	global_load_dwordx4 v[162:165], v231, s[38:39]
	s_add_u32 s38, s38, s37
	s_addc_u32 s39, s39, 0
	global_load_dwordx4 v[166:169], v231, s[38:39]
	s_add_u32 s38, s38, s37
	s_addc_u32 s39, s39, 0
	global_load_dwordx4 v[170:173], v231, s[38:39]
	s_add_u32 s38, s38, s37
	s_addc_u32 s39, s39, 0
	global_load_dwordx4 v[174:177], v231, s[38:39]
	s_cmp_ge_u32 s100, s22
	s_cbranch_scc1 .Lwcm1_p2
	s_cmpk_ge_u32 s100, 0x900
	s_cbranch_scc1 .Lwcm1_t3_3
	s_cmpk_ge_u32 s100, 0x380
	s_cbranch_scc1 .Lwcm1_t2_3
	s_cmpk_ge_u32 s100, 0x280
	s_cbranch_scc1 .Lwcm1_t1_3
	s_movk_i32 s14, 0x78
	s_sub_u32 s99, s100, 0
	s_mul_i32 s44, s99, 0x66667
	s_lshr_b32 s44, s44, 24
	s_mul_i32 s36, s44, 40
	s_sub_u32 s99, s99, s36
	s_mul_i32 s38, s44, 0xa0000
	s_lshl_b32 s36, s99, 8
	s_add_u32 s38, s38, s36
	s_add_u32 s38, s38, 0xa00000
	s_lshl_b32 s36, s99, 6
	s_mov_b32 s32, 0x10000
	s_mul_i32 s36, s36, 0x800
	s_lshl_b32 s44, s44, 7
	s_add_u32 s36, s36, s44
	s_add_u32 s36, s36, 0x500000
	s_mov_b32 s37, 0x28000
	s_movk_i32 s44, 0x800
	s_mov_b32 s99, 0x2800
	s_branch .Lwcm1_tj_3

.Lwcm1_tj_3:
	s_load_dwordx2 s[8:9], s[0:1], s14
	s_add_u32 s20, s12, s36
	s_addc_u32 s21, s13, 0
	v_mad_u32_u24 v231, v233, s99, v234
	v_writelane_b32 v237, s20, 16
	v_writelane_b32 v237, s21, 17
	v_writelane_b32 v237, s32, 18
	v_writelane_b32 v237, s44, 19
	s_add_u32 s100, s100, s23
	s_waitcnt lgkmcnt(0)
	s_add_u32 s38, s8, s38
	s_addc_u32 s39, s9, 0
	global_load_dwordx4 v[178:181], v231, s[38:39]
	s_add_u32 s38, s38, s37
	s_addc_u32 s39, s39, 0
	global_load_dwordx4 v[182:185], v231, s[38:39]
	s_add_u32 s38, s38, s37
	s_addc_u32 s39, s39, 0
	global_load_dwordx4 v[186:189], v231, s[38:39]
	s_add_u32 s38, s38, s37
	s_addc_u32 s39, s39, 0
	global_load_dwordx4 v[190:193], v231, s[38:39]
	s_cmp_ge_u32 s100, s22
	s_cbranch_scc1 .Lwcm1_p3
	s_cmpk_ge_u32 s100, 0x900
	s_cbranch_scc1 .Lwcm1_t3_4
	s_cmpk_ge_u32 s100, 0x380
	s_cbranch_scc1 .Lwcm1_t2_4
	s_cmpk_ge_u32 s100, 0x280
	s_cbranch_scc1 .Lwcm1_t1_4
	s_movk_i32 s14, 0x78
	s_sub_u32 s99, s100, 0
	s_mul_i32 s44, s99, 0x66667
	s_lshr_b32 s44, s44, 24
	s_mul_i32 s36, s44, 40
	s_sub_u32 s99, s99, s36
	s_mul_i32 s38, s44, 0xa0000
	s_lshl_b32 s36, s99, 8
	s_add_u32 s38, s38, s36
	s_add_u32 s38, s38, 0xa00000
	s_lshl_b32 s36, s99, 6
	s_mov_b32 s32, 0x10000
	s_mul_i32 s36, s36, 0x800
	s_lshl_b32 s44, s44, 7
	s_add_u32 s36, s36, s44
	s_add_u32 s36, s36, 0x500000
	s_mov_b32 s37, 0x28000
	s_movk_i32 s44, 0x800
	s_mov_b32 s99, 0x2800
	s_branch .Lwcm1_tj_4

.Lwcm1_tj_4:
	s_load_dwordx2 s[8:9], s[0:1], s14
	s_add_u32 s20, s12, s36
	s_addc_u32 s21, s13, 0
	v_mad_u32_u24 v231, v233, s99, v234
	v_writelane_b32 v237, s20, 20
	v_writelane_b32 v237, s21, 21
	v_writelane_b32 v237, s32, 22
	v_writelane_b32 v237, s44, 23
	s_add_u32 s100, s100, s23
	s_waitcnt lgkmcnt(0)
	s_add_u32 s38, s8, s38
	s_addc_u32 s39, s9, 0
	global_load_dwordx4 v[194:197], v231, s[38:39]
	s_add_u32 s38, s38, s37
	s_addc_u32 s39, s39, 0
	global_load_dwordx4 v[198:201], v231, s[38:39]
	s_add_u32 s38, s38, s37
	s_addc_u32 s39, s39, 0
	global_load_dwordx4 v[202:205], v231, s[38:39]
	s_add_u32 s38, s38, s37
	s_addc_u32 s39, s39, 0
	global_load_dwordx4 v[206:209], v231, s[38:39]
	s_cmp_ge_u32 s100, s22
	s_cbranch_scc1 .Lwcm1_p4
	s_cmpk_ge_u32 s100, 0x900
	s_cbranch_scc1 .Lwcm1_t3_5
	s_cmpk_ge_u32 s100, 0x380
	s_cbranch_scc1 .Lwcm1_t2_5
	s_cmpk_ge_u32 s100, 0x280
	s_cbranch_scc1 .Lwcm1_t1_5
	s_movk_i32 s14, 0x78
	s_sub_u32 s99, s100, 0
	s_mul_i32 s44, s99, 0x66667
	s_lshr_b32 s44, s44, 24
	s_mul_i32 s36, s44, 40
	s_sub_u32 s99, s99, s36
	s_mul_i32 s38, s44, 0xa0000
	s_lshl_b32 s36, s99, 8
	s_add_u32 s38, s38, s36
	s_add_u32 s38, s38, 0xa00000
	s_lshl_b32 s36, s99, 6
	s_mov_b32 s32, 0x10000
	s_mul_i32 s36, s36, 0x800
	s_lshl_b32 s44, s44, 7
	s_add_u32 s36, s36, s44
	s_add_u32 s36, s36, 0x500000
	s_mov_b32 s37, 0x28000
	s_movk_i32 s44, 0x800
	s_mov_b32 s99, 0x2800
	s_branch .Lwcm1_tj_5

.Lwcm1_loop:
	s_waitcnt vmcnt(16)
	v_readlane_b32 s20, v237, 8
	v_readlane_b32 s21, v237, 9
	v_readlane_b32 s32, v237, 10
	v_readlane_b32 s35, v237, 11
	ds_write_b32 v226, v146 offset:0
	ds_write_b32 v226, v147 offset:4
	ds_write_b32 v226, v148 offset:8
	ds_write_b32 v226, v149 offset:12
	ds_write_b32 v226, v150 offset:4160
	ds_write_b32 v226, v151 offset:4164
	ds_write_b32 v226, v152 offset:4168
	ds_write_b32 v226, v153 offset:4172
	ds_write_b32 v226, v154 offset:8320
	ds_write_b32 v226, v155 offset:8324
	ds_write_b32 v226, v156 offset:8328
	ds_write_b32 v226, v157 offset:8332
	ds_write_b32 v226, v158 offset:12480
	ds_write_b32 v226, v159 offset:12484
	ds_write_b32 v226, v160 offset:12488
	ds_write_b32 v226, v161 offset:12492
	v_mad_u32_u24 v232, v235, s35, v236
	s_waitcnt lgkmcnt(0)
	s_barrier
	ds_read2_b32 v[146:147], v227 offset1:65
	ds_read2_b32 v[148:149], v227 offset0:130 offset1:195
	ds_read2_b32 v[150:151], v228 offset0:4 offset1:69
	ds_read2_b32 v[152:153], v228 offset0:134 offset1:199
	ds_read2_b32 v[154:155], v229 offset1:65
	ds_read2_b32 v[156:157], v229 offset0:130 offset1:195
	ds_read2_b32 v[158:159], v230 offset0:4 offset1:69
	ds_read2_b32 v[160:161], v230 offset0:134 offset1:199
	s_add_u32 s26, s20, s32
	s_addc_u32 s27, s21, 0
	s_waitcnt lgkmcnt(0)
	s_barrier
	v_cvt_pk_bf16_f32 v146, v146, v147
	v_cvt_pk_bf16_f32 v147, v148, v149
	v_cvt_pk_bf16_f32 v148, v150, v151
	v_cvt_pk_bf16_f32 v149, v152, v153
	v_cvt_pk_bf16_f32 v154, v154, v155
	v_cvt_pk_bf16_f32 v155, v156, v157
	v_cvt_pk_bf16_f32 v156, v158, v159
	v_cvt_pk_bf16_f32 v157, v160, v161
	global_store_dwordx4 v232, v[146:149], s[20:21]
	global_store_dwordx4 v232, v[154:157], s[26:27]
	s_cmp_ge_u32 s100, s22
	s_cbranch_scc1 .Lwcm1_tail0
	s_cmpk_ge_u32 s100, 0x900
	s_cbranch_scc1 .Lwcm1_t3_6
	s_cmpk_ge_u32 s100, 0x380
	s_cbranch_scc1 .Lwcm1_t2_6
	s_cmpk_ge_u32 s100, 0x280
	s_cbranch_scc1 .Lwcm1_t1_6
	s_movk_i32 s14, 0x78
	s_sub_u32 s99, s100, 0
	s_mul_i32 s44, s99, 0x66667
	s_lshr_b32 s44, s44, 24
	s_mul_i32 s36, s44, 40
	s_sub_u32 s99, s99, s36
	s_mul_i32 s38, s44, 0xa0000
	s_lshl_b32 s36, s99, 8
	s_add_u32 s38, s38, s36
	s_add_u32 s38, s38, 0xa00000
	s_lshl_b32 s36, s99, 6
	s_mov_b32 s32, 0x10000
	s_mul_i32 s36, s36, 0x800
	s_lshl_b32 s44, s44, 7
	s_add_u32 s36, s36, s44
	s_add_u32 s36, s36, 0x500000
	s_mov_b32 s37, 0x28000
	s_movk_i32 s44, 0x800
	s_mov_b32 s99, 0x2800
	s_branch .Lwcm1_tj_6

.Lwcm1_tj_6:
	s_load_dwordx2 s[8:9], s[0:1], s14
	s_add_u32 s20, s12, s36
	s_addc_u32 s21, s13, 0
	v_mad_u32_u24 v231, v233, s99, v234
	v_writelane_b32 v237, s20, 8
	v_writelane_b32 v237, s21, 9
	v_writelane_b32 v237, s32, 10
	v_writelane_b32 v237, s44, 11
	s_add_u32 s100, s100, s23
	s_waitcnt lgkmcnt(0)
	s_add_u32 s38, s8, s38
	s_addc_u32 s39, s9, 0
	global_load_dwordx4 v[146:149], v231, s[38:39]
	s_add_u32 s38, s38, s37
	s_addc_u32 s39, s39, 0
	global_load_dwordx4 v[150:153], v231, s[38:39]
	s_add_u32 s38, s38, s37
	s_addc_u32 s39, s39, 0
	global_load_dwordx4 v[154:157], v231, s[38:39]
	s_add_u32 s38, s38, s37
	s_addc_u32 s39, s39, 0
	global_load_dwordx4 v[158:161], v231, s[38:39]
	s_waitcnt vmcnt(16)
	v_readlane_b32 s20, v237, 12
	v_readlane_b32 s21, v237, 13
	v_readlane_b32 s32, v237, 14
	v_readlane_b32 s35, v237, 15
	ds_write_b32 v226, v162 offset:0
	ds_write_b32 v226, v163 offset:4
	ds_write_b32 v226, v164 offset:8
	ds_write_b32 v226, v165 offset:12
	ds_write_b32 v226, v166 offset:4160
	ds_write_b32 v226, v167 offset:4164
	ds_write_b32 v226, v168 offset:4168
	ds_write_b32 v226, v169 offset:4172
	ds_write_b32 v226, v170 offset:8320
	ds_write_b32 v226, v171 offset:8324
	ds_write_b32 v226, v172 offset:8328
	ds_write_b32 v226, v173 offset:8332
	ds_write_b32 v226, v174 offset:12480
	ds_write_b32 v226, v175 offset:12484
	ds_write_b32 v226, v176 offset:12488
	ds_write_b32 v226, v177 offset:12492
	v_mad_u32_u24 v232, v235, s35, v236
	s_waitcnt lgkmcnt(0)
	s_barrier
	ds_read2_b32 v[162:163], v227 offset1:65
	ds_read2_b32 v[164:165], v227 offset0:130 offset1:195
	ds_read2_b32 v[166:167], v228 offset0:4 offset1:69
	ds_read2_b32 v[168:169], v228 offset0:134 offset1:199
	ds_read2_b32 v[170:171], v229 offset1:65
	ds_read2_b32 v[172:173], v229 offset0:130 offset1:195
	ds_read2_b32 v[174:175], v230 offset0:4 offset1:69
	ds_read2_b32 v[176:177], v230 offset0:134 offset1:199
	s_add_u32 s26, s20, s32
	s_addc_u32 s27, s21, 0
	s_waitcnt lgkmcnt(0)
	s_barrier
	v_cvt_pk_bf16_f32 v162, v162, v163
	v_cvt_pk_bf16_f32 v163, v164, v165
	v_cvt_pk_bf16_f32 v164, v166, v167
	v_cvt_pk_bf16_f32 v165, v168, v169
	v_cvt_pk_bf16_f32 v170, v170, v171
	v_cvt_pk_bf16_f32 v171, v172, v173
	v_cvt_pk_bf16_f32 v172, v174, v175
	v_cvt_pk_bf16_f32 v173, v176, v177
	global_store_dwordx4 v232, v[162:165], s[20:21]
	global_store_dwordx4 v232, v[170:173], s[26:27]
	s_cmp_ge_u32 s100, s22
	s_cbranch_scc1 .Lwcm1_tail1
	s_cmpk_ge_u32 s100, 0x900
	s_cbranch_scc1 .Lwcm1_t3_7
	s_cmpk_ge_u32 s100, 0x380
	s_cbranch_scc1 .Lwcm1_t2_7
	s_cmpk_ge_u32 s100, 0x280
	s_cbranch_scc1 .Lwcm1_t1_7
	s_movk_i32 s14, 0x78
	s_sub_u32 s99, s100, 0
	s_mul_i32 s44, s99, 0x66667
	s_lshr_b32 s44, s44, 24
	s_mul_i32 s36, s44, 40
	s_sub_u32 s99, s99, s36
	s_mul_i32 s38, s44, 0xa0000
	s_lshl_b32 s36, s99, 8
	s_add_u32 s38, s38, s36
	s_add_u32 s38, s38, 0xa00000
	s_lshl_b32 s36, s99, 6
	s_mov_b32 s32, 0x10000
	s_mul_i32 s36, s36, 0x800
	s_lshl_b32 s44, s44, 7
	s_add_u32 s36, s36, s44
	s_add_u32 s36, s36, 0x500000
	s_mov_b32 s37, 0x28000
	s_movk_i32 s44, 0x800
	s_mov_b32 s99, 0x2800
	s_branch .Lwcm1_tj_7

.Lwcm1_tj_7:
	s_load_dwordx2 s[8:9], s[0:1], s14
	s_add_u32 s20, s12, s36
	s_addc_u32 s21, s13, 0
	v_mad_u32_u24 v231, v233, s99, v234
	v_writelane_b32 v237, s20, 12
	v_writelane_b32 v237, s21, 13
	v_writelane_b32 v237, s32, 14
	v_writelane_b32 v237, s44, 15
	s_add_u32 s100, s100, s23
	s_waitcnt lgkmcnt(0)
	s_add_u32 s38, s8, s38
	s_addc_u32 s39, s9, 0
	global_load_dwordx4 v[162:165], v231, s[38:39]
	s_add_u32 s38, s38, s37
	s_addc_u32 s39, s39, 0
	global_load_dwordx4 v[166:169], v231, s[38:39]
	s_add_u32 s38, s38, s37
	s_addc_u32 s39, s39, 0
	global_load_dwordx4 v[170:173], v231, s[38:39]
	s_add_u32 s38, s38, s37
	s_addc_u32 s39, s39, 0
	global_load_dwordx4 v[174:177], v231, s[38:39]
	s_waitcnt vmcnt(16)
	v_readlane_b32 s20, v237, 16
	v_readlane_b32 s21, v237, 17
	v_readlane_b32 s32, v237, 18
	v_readlane_b32 s35, v237, 19
	ds_write_b32 v226, v178 offset:0
	ds_write_b32 v226, v179 offset:4
	ds_write_b32 v226, v180 offset:8
	ds_write_b32 v226, v181 offset:12
	ds_write_b32 v226, v182 offset:4160
	ds_write_b32 v226, v183 offset:4164
	ds_write_b32 v226, v184 offset:4168
	ds_write_b32 v226, v185 offset:4172
	ds_write_b32 v226, v186 offset:8320
	ds_write_b32 v226, v187 offset:8324
	ds_write_b32 v226, v188 offset:8328
	ds_write_b32 v226, v189 offset:8332
	ds_write_b32 v226, v190 offset:12480
	ds_write_b32 v226, v191 offset:12484
	ds_write_b32 v226, v192 offset:12488
	ds_write_b32 v226, v193 offset:12492
	v_mad_u32_u24 v232, v235, s35, v236
	s_waitcnt lgkmcnt(0)
	s_barrier
	ds_read2_b32 v[178:179], v227 offset1:65
	ds_read2_b32 v[180:181], v227 offset0:130 offset1:195
	ds_read2_b32 v[182:183], v228 offset0:4 offset1:69
	ds_read2_b32 v[184:185], v228 offset0:134 offset1:199
	ds_read2_b32 v[186:187], v229 offset1:65
	ds_read2_b32 v[188:189], v229 offset0:130 offset1:195
	ds_read2_b32 v[190:191], v230 offset0:4 offset1:69
	ds_read2_b32 v[192:193], v230 offset0:134 offset1:199
	s_add_u32 s26, s20, s32
	s_addc_u32 s27, s21, 0
	s_waitcnt lgkmcnt(0)
	s_barrier
	v_cvt_pk_bf16_f32 v178, v178, v179
	v_cvt_pk_bf16_f32 v179, v180, v181
	v_cvt_pk_bf16_f32 v180, v182, v183
	v_cvt_pk_bf16_f32 v181, v184, v185
	v_cvt_pk_bf16_f32 v186, v186, v187
	v_cvt_pk_bf16_f32 v187, v188, v189
	v_cvt_pk_bf16_f32 v188, v190, v191
	v_cvt_pk_bf16_f32 v189, v192, v193
	global_store_dwordx4 v232, v[178:181], s[20:21]
	global_store_dwordx4 v232, v[186:189], s[26:27]
	s_cmp_ge_u32 s100, s22
	s_cbranch_scc1 .Lwcm1_tail2
	s_cmpk_ge_u32 s100, 0x900
	s_cbranch_scc1 .Lwcm1_t3_8
	s_cmpk_ge_u32 s100, 0x380
	s_cbranch_scc1 .Lwcm1_t2_8
	s_cmpk_ge_u32 s100, 0x280
	s_cbranch_scc1 .Lwcm1_t1_8
	s_movk_i32 s14, 0x78
	s_sub_u32 s99, s100, 0
	s_mul_i32 s44, s99, 0x66667
	s_lshr_b32 s44, s44, 24
	s_mul_i32 s36, s44, 40
	s_sub_u32 s99, s99, s36
	s_mul_i32 s38, s44, 0xa0000
	s_lshl_b32 s36, s99, 8
	s_add_u32 s38, s38, s36
	s_add_u32 s38, s38, 0xa00000
	s_lshl_b32 s36, s99, 6
	s_mov_b32 s32, 0x10000
	s_mul_i32 s36, s36, 0x800
	s_lshl_b32 s44, s44, 7
	s_add_u32 s36, s36, s44
	s_add_u32 s36, s36, 0x500000
	s_mov_b32 s37, 0x28000
	s_movk_i32 s44, 0x800
	s_mov_b32 s99, 0x2800
	s_branch .Lwcm1_tj_8

.Lwcm1_tj_8:
	s_load_dwordx2 s[8:9], s[0:1], s14
	s_add_u32 s20, s12, s36
	s_addc_u32 s21, s13, 0
	v_mad_u32_u24 v231, v233, s99, v234
	v_writelane_b32 v237, s20, 16
	v_writelane_b32 v237, s21, 17
	v_writelane_b32 v237, s32, 18
	v_writelane_b32 v237, s44, 19
	s_add_u32 s100, s100, s23
	s_waitcnt lgkmcnt(0)
	s_add_u32 s38, s8, s38
	s_addc_u32 s39, s9, 0
	global_load_dwordx4 v[178:181], v231, s[38:39]
	s_add_u32 s38, s38, s37
	s_addc_u32 s39, s39, 0
	global_load_dwordx4 v[182:185], v231, s[38:39]
	s_add_u32 s38, s38, s37
	s_addc_u32 s39, s39, 0
	global_load_dwordx4 v[186:189], v231, s[38:39]
	s_add_u32 s38, s38, s37
	s_addc_u32 s39, s39, 0
	global_load_dwordx4 v[190:193], v231, s[38:39]
	s_waitcnt vmcnt(16)
	v_readlane_b32 s20, v237, 20
	v_readlane_b32 s21, v237, 21
	v_readlane_b32 s32, v237, 22
	v_readlane_b32 s35, v237, 23
	ds_write_b32 v226, v194 offset:0
	ds_write_b32 v226, v195 offset:4
	ds_write_b32 v226, v196 offset:8
	ds_write_b32 v226, v197 offset:12
	ds_write_b32 v226, v198 offset:4160
	ds_write_b32 v226, v199 offset:4164
	ds_write_b32 v226, v200 offset:4168
	ds_write_b32 v226, v201 offset:4172
	ds_write_b32 v226, v202 offset:8320
	ds_write_b32 v226, v203 offset:8324
	ds_write_b32 v226, v204 offset:8328
	ds_write_b32 v226, v205 offset:8332
	ds_write_b32 v226, v206 offset:12480
	ds_write_b32 v226, v207 offset:12484
	ds_write_b32 v226, v208 offset:12488
	ds_write_b32 v226, v209 offset:12492
	v_mad_u32_u24 v232, v235, s35, v236
	s_waitcnt lgkmcnt(0)
	s_barrier
	ds_read2_b32 v[194:195], v227 offset1:65
	ds_read2_b32 v[196:197], v227 offset0:130 offset1:195
	ds_read2_b32 v[198:199], v228 offset0:4 offset1:69
	ds_read2_b32 v[200:201], v228 offset0:134 offset1:199
	ds_read2_b32 v[202:203], v229 offset1:65
	ds_read2_b32 v[204:205], v229 offset0:130 offset1:195
	ds_read2_b32 v[206:207], v230 offset0:4 offset1:69
	ds_read2_b32 v[208:209], v230 offset0:134 offset1:199
	s_add_u32 s26, s20, s32
	s_addc_u32 s27, s21, 0
	s_waitcnt lgkmcnt(0)
	s_barrier
	v_cvt_pk_bf16_f32 v194, v194, v195
	v_cvt_pk_bf16_f32 v195, v196, v197
	v_cvt_pk_bf16_f32 v196, v198, v199
	v_cvt_pk_bf16_f32 v197, v200, v201
	v_cvt_pk_bf16_f32 v202, v202, v203
	v_cvt_pk_bf16_f32 v203, v204, v205
	v_cvt_pk_bf16_f32 v204, v206, v207
	v_cvt_pk_bf16_f32 v205, v208, v209
	global_store_dwordx4 v232, v[194:197], s[20:21]
	global_store_dwordx4 v232, v[202:205], s[26:27]
	s_cmp_ge_u32 s100, s22
	s_cbranch_scc1 .Lwcm1_tail3
	s_cmpk_ge_u32 s100, 0x900
	s_cbranch_scc1 .Lwcm1_t3_9
	s_cmpk_ge_u32 s100, 0x380
	s_cbranch_scc1 .Lwcm1_t2_9
	s_cmpk_ge_u32 s100, 0x280
	s_cbranch_scc1 .Lwcm1_t1_9
	s_movk_i32 s14, 0x78
	s_sub_u32 s99, s100, 0
	s_mul_i32 s44, s99, 0x66667
	s_lshr_b32 s44, s44, 24
	s_mul_i32 s36, s44, 40
	s_sub_u32 s99, s99, s36
	s_mul_i32 s38, s44, 0xa0000
	s_lshl_b32 s36, s99, 8
	s_add_u32 s38, s38, s36
	s_add_u32 s38, s38, 0xa00000
	s_lshl_b32 s36, s99, 6
	s_mov_b32 s32, 0x10000
	s_mul_i32 s36, s36, 0x800
	s_lshl_b32 s44, s44, 7
	s_add_u32 s36, s36, s44
	s_add_u32 s36, s36, 0x500000
	s_mov_b32 s37, 0x28000
	s_movk_i32 s44, 0x800
	s_mov_b32 s99, 0x2800
	s_branch .Lwcm1_tj_9

.Lwcm1_tj_9:
	s_load_dwordx2 s[8:9], s[0:1], s14
	s_add_u32 s20, s12, s36
	s_addc_u32 s21, s13, 0
	v_mad_u32_u24 v231, v233, s99, v234
	v_writelane_b32 v237, s20, 20
	v_writelane_b32 v237, s21, 21
	v_writelane_b32 v237, s32, 22
	v_writelane_b32 v237, s44, 23
	s_add_u32 s100, s100, s23
	s_waitcnt lgkmcnt(0)
	s_add_u32 s38, s8, s38
	s_addc_u32 s39, s9, 0
	global_load_dwordx4 v[194:197], v231, s[38:39]
	s_add_u32 s38, s38, s37
	s_addc_u32 s39, s39, 0
	global_load_dwordx4 v[198:201], v231, s[38:39]
	s_add_u32 s38, s38, s37
	s_addc_u32 s39, s39, 0
	global_load_dwordx4 v[202:205], v231, s[38:39]
	s_add_u32 s38, s38, s37
	s_addc_u32 s39, s39, 0
	global_load_dwordx4 v[206:209], v231, s[38:39]
	s_waitcnt vmcnt(16)
	v_readlane_b32 s20, v237, 24
	v_readlane_b32 s21, v237, 25
	v_readlane_b32 s32, v237, 26
	v_readlane_b32 s35, v237, 27
	ds_write_b32 v226, v210 offset:0
	ds_write_b32 v226, v211 offset:4
	ds_write_b32 v226, v212 offset:8
	ds_write_b32 v226, v213 offset:12
	ds_write_b32 v226, v214 offset:4160
	ds_write_b32 v226, v215 offset:4164
	ds_write_b32 v226, v216 offset:4168
	ds_write_b32 v226, v217 offset:4172
	ds_write_b32 v226, v218 offset:8320
	ds_write_b32 v226, v219 offset:8324
	ds_write_b32 v226, v220 offset:8328
	ds_write_b32 v226, v221 offset:8332
	ds_write_b32 v226, v222 offset:12480
	ds_write_b32 v226, v223 offset:12484
	ds_write_b32 v226, v224 offset:12488
	ds_write_b32 v226, v225 offset:12492
	v_mad_u32_u24 v232, v235, s35, v236
	s_waitcnt lgkmcnt(0)
	s_barrier
	ds_read2_b32 v[210:211], v227 offset1:65
	ds_read2_b32 v[212:213], v227 offset0:130 offset1:195
	ds_read2_b32 v[214:215], v228 offset0:4 offset1:69
	ds_read2_b32 v[216:217], v228 offset0:134 offset1:199
	ds_read2_b32 v[218:219], v229 offset1:65
	ds_read2_b32 v[220:221], v229 offset0:130 offset1:195
	ds_read2_b32 v[222:223], v230 offset0:4 offset1:69
	ds_read2_b32 v[224:225], v230 offset0:134 offset1:199
	s_add_u32 s26, s20, s32
	s_addc_u32 s27, s21, 0
	s_waitcnt lgkmcnt(0)
	s_barrier
	v_cvt_pk_bf16_f32 v210, v210, v211
	v_cvt_pk_bf16_f32 v211, v212, v213
	v_cvt_pk_bf16_f32 v212, v214, v215
	v_cvt_pk_bf16_f32 v213, v216, v217
	v_cvt_pk_bf16_f32 v218, v218, v219
	v_cvt_pk_bf16_f32 v219, v220, v221
	v_cvt_pk_bf16_f32 v220, v222, v223
	v_cvt_pk_bf16_f32 v221, v224, v225
	global_store_dwordx4 v232, v[210:213], s[20:21]
	global_store_dwordx4 v232, v[218:221], s[26:27]
	s_cmp_ge_u32 s100, s22
	s_cbranch_scc1 .Lwcm1_tail4
	s_cmpk_ge_u32 s100, 0x900
	s_cbranch_scc1 .Lwcm1_t3_10
	s_cmpk_ge_u32 s100, 0x380
	s_cbranch_scc1 .Lwcm1_t2_10
	s_cmpk_ge_u32 s100, 0x280
	s_cbranch_scc1 .Lwcm1_t1_10
	s_movk_i32 s14, 0x78
	s_sub_u32 s99, s100, 0
	s_mul_i32 s44, s99, 0x66667
	s_lshr_b32 s44, s44, 24
	s_mul_i32 s36, s44, 40
	s_sub_u32 s99, s99, s36
	s_mul_i32 s38, s44, 0xa0000
	s_lshl_b32 s36, s99, 8
	s_add_u32 s38, s38, s36
	s_add_u32 s38, s38, 0xa00000
	s_lshl_b32 s36, s99, 6
	s_mov_b32 s32, 0x10000
	s_mul_i32 s36, s36, 0x800
	s_lshl_b32 s44, s44, 7
	s_add_u32 s36, s36, s44
	s_add_u32 s36, s36, 0x500000
	s_mov_b32 s37, 0x28000
	s_movk_i32 s44, 0x800
	s_mov_b32 s99, 0x2800
	s_branch .Lwcm1_tj_10

.Lgvm_loop:
	s_waitcnt vmcnt(0) lgkmcnt(0)
	s_barrier
	v_readlane_b32 s0, v242, 42
	v_readlane_b32 s1, v242, 43
	v_readlane_b32 s12, v242, 3
	v_readlane_b32 s13, v242, 4
	s_sub_u32 s0, s0, 0x118
	s_subb_u32 s1, s1, 0
	s_load_dwordx4 s[20:23], s[0:1], 0x38
	s_load_dwordx4 s[24:27], s[0:1], 0x48
	v_lshlrev_b32_e32 v106, 2, v137
	v_add_u32_e32 v107, 0x1000, v106
	v_lshrrev_b32_e32 v113, 5, v137
	v_and_b32_e32 v114, 31, v137
	s_waitcnt lgkmcnt(0)
	global_load_dword v90, v106, s[22:23]
	global_load_dword v91, v106, s[22:23] offset:1024
	global_load_dword v92, v106, s[22:23] offset:2048
	global_load_dword v93, v106, s[22:23] offset:3072
	global_load_dword v94, v106, s[20:21]
	global_load_dword v95, v106, s[20:21] offset:1024
	global_load_dword v96, v106, s[20:21] offset:2048
	global_load_dword v97, v106, s[20:21] offset:3072
	global_load_dword v98, v107, s[20:21]
	global_load_dword v99, v107, s[20:21] offset:1024
	global_load_dword v100, v107, s[20:21] offset:2048
	global_load_dword v101, v107, s[20:21] offset:3072
	s_lshl_b32 s14, s100, 7
	s_add_u32 s24, s24, 0x1800000
	s_addc_u32 s25, s25, 0
	s_add_u32 s24, s24, s14
	s_addc_u32 s25, s25, 0
	v_mul_u32_u24_e32 v116, 0x300000, v113
	v_lshl_add_u32 v116, v114, 2, v116
	v_mov_b32_e32 v117, 0
	v_lshl_add_u64 v[116:117], s[24:25], 0, v[116:117]
	s_mov_b64 s[8:9], 0x6000
	v_lshlrev_b32_e32 v108, 9, v113
	s_waitcnt vmcnt(11)
	v_mul_f32_e32 v102, 0xbfb8aa3b, v90
	v_exp_f32_e32 v102, v102
	s_nop 0
	v_add_f32_e32 v102, 1.0, v102
	v_rcp_f32_e32 v102, v102
	s_nop 0
	v_mul_f32_e32 v102, v90, v102
	ds_write_b32 v106, v102
	s_waitcnt vmcnt(10)
	v_mul_f32_e32 v103, 0xbfb8aa3b, v91
	v_exp_f32_e32 v103, v103
	s_nop 0
	v_add_f32_e32 v103, 1.0, v103
	v_rcp_f32_e32 v103, v103
	s_nop 0
	v_mul_f32_e32 v103, v91, v103
	ds_write_b32 v106, v103 offset:1024
	s_waitcnt vmcnt(9)
	v_mul_f32_e32 v104, 0xbfb8aa3b, v92
	v_exp_f32_e32 v104, v104
	s_nop 0
	v_add_f32_e32 v104, 1.0, v104
	v_rcp_f32_e32 v104, v104
	s_nop 0
	v_mul_f32_e32 v104, v92, v104
	ds_write_b32 v106, v104 offset:2048
	s_waitcnt vmcnt(8)
	v_mul_f32_e32 v105, 0xbfb8aa3b, v93
	v_exp_f32_e32 v105, v105
	s_nop 0
	v_add_f32_e32 v105, 1.0, v105
	v_rcp_f32_e32 v105, v105
	s_nop 0
	v_mul_f32_e32 v105, v93, v105
	ds_write_b32 v106, v105 offset:3072
	s_waitcnt vmcnt(7)
	v_mul_f32_e32 v102, 0xbfb8aa3b, v94
	v_exp_f32_e32 v102, v102
	s_nop 0
	v_add_f32_e32 v102, 1.0, v102
	v_rcp_f32_e32 v102, v102
	s_nop 0
	v_mul_f32_e32 v102, v94, v102
	ds_write_b32 v106, v102 offset:4096
	s_waitcnt vmcnt(6)
	v_mul_f32_e32 v103, 0xbfb8aa3b, v95
	v_exp_f32_e32 v103, v103
	s_nop 0
	v_add_f32_e32 v103, 1.0, v103
	v_rcp_f32_e32 v103, v103
	s_nop 0
	v_mul_f32_e32 v103, v95, v103
	ds_write_b32 v106, v103 offset:5120
	s_waitcnt vmcnt(5)
	v_mul_f32_e32 v104, 0xbfb8aa3b, v96
	v_exp_f32_e32 v104, v104
	s_nop 0
	v_add_f32_e32 v104, 1.0, v104
	v_rcp_f32_e32 v104, v104
	s_nop 0
	v_mul_f32_e32 v104, v96, v104
	ds_write_b32 v106, v104 offset:6144
	s_waitcnt vmcnt(4)
	v_mul_f32_e32 v105, 0xbfb8aa3b, v97
	v_exp_f32_e32 v105, v105
	s_nop 0
	v_add_f32_e32 v105, 1.0, v105
	v_rcp_f32_e32 v105, v105
	s_nop 0
	v_mul_f32_e32 v105, v97, v105
	ds_write_b32 v106, v105 offset:7168
	s_waitcnt vmcnt(3)
	v_mul_f32_e32 v102, 0xbfb8aa3b, v98
	v_exp_f32_e32 v102, v102
	s_nop 0
	v_add_f32_e32 v102, 1.0, v102
	v_rcp_f32_e32 v102, v102
	s_nop 0
	v_mul_f32_e32 v102, v98, v102
	ds_write_b32 v106, v102 offset:8192
	s_waitcnt vmcnt(2)
	v_mul_f32_e32 v103, 0xbfb8aa3b, v99
	v_exp_f32_e32 v103, v103
	s_nop 0
	v_add_f32_e32 v103, 1.0, v103
	v_rcp_f32_e32 v103, v103
	s_nop 0
	v_mul_f32_e32 v103, v99, v103
	ds_write_b32 v106, v103 offset:9216
	s_waitcnt vmcnt(1)
	v_mul_f32_e32 v104, 0xbfb8aa3b, v100
	v_exp_f32_e32 v104, v104
	s_nop 0
	v_add_f32_e32 v104, 1.0, v104
	v_rcp_f32_e32 v104, v104
	s_nop 0
	v_mul_f32_e32 v104, v100, v104
	ds_write_b32 v106, v104 offset:10240
	s_waitcnt vmcnt(0)
	v_mul_f32_e32 v105, 0xbfb8aa3b, v101
	v_exp_f32_e32 v105, v105
	s_nop 0
	v_add_f32_e32 v105, 1.0, v105
	v_rcp_f32_e32 v105, v105
	s_nop 0
	v_mul_f32_e32 v105, v101, v105
	ds_write_b32 v106, v105 offset:11264
	global_load_dword v194, v[116:117], off nt
	v_lshl_add_u64 v[116:117], v[116:117], 0, s[8:9]
	global_load_dword v195, v[116:117], off nt
	v_lshl_add_u64 v[116:117], v[116:117], 0, s[8:9]
	global_load_dword v196, v[116:117], off nt
	v_lshl_add_u64 v[116:117], v[116:117], 0, s[8:9]
	global_load_dword v197, v[116:117], off nt
	v_lshl_add_u64 v[116:117], v[116:117], 0, s[8:9]
	global_load_dword v198, v[116:117], off nt
	v_lshl_add_u64 v[116:117], v[116:117], 0, s[8:9]
	global_load_dword v199, v[116:117], off nt
	v_lshl_add_u64 v[116:117], v[116:117], 0, s[8:9]
	global_load_dword v200, v[116:117], off nt
	v_lshl_add_u64 v[116:117], v[116:117], 0, s[8:9]
	global_load_dword v201, v[116:117], off nt
	v_lshl_add_u64 v[116:117], v[116:117], 0, s[8:9]
	global_load_dword v202, v[116:117], off nt
	v_lshl_add_u64 v[116:117], v[116:117], 0, s[8:9]
	global_load_dword v203, v[116:117], off nt
	v_lshl_add_u64 v[116:117], v[116:117], 0, s[8:9]
	global_load_dword v204, v[116:117], off nt
	v_lshl_add_u64 v[116:117], v[116:117], 0, s[8:9]
	global_load_dword v205, v[116:117], off nt
	v_lshl_add_u64 v[116:117], v[116:117], 0, s[8:9]
	global_load_dword v206, v[116:117], off nt
	v_lshl_add_u64 v[116:117], v[116:117], 0, s[8:9]
	global_load_dword v207, v[116:117], off nt
	v_lshl_add_u64 v[116:117], v[116:117], 0, s[8:9]
	global_load_dword v208, v[116:117], off nt
	v_lshl_add_u64 v[116:117], v[116:117], 0, s[8:9]
	global_load_dword v209, v[116:117], off nt
	v_lshl_add_u64 v[116:117], v[116:117], 0, s[8:9]
	global_load_dword v210, v[116:117], off nt
	v_lshl_add_u64 v[116:117], v[116:117], 0, s[8:9]
	global_load_dword v211, v[116:117], off nt
	v_lshl_add_u64 v[116:117], v[116:117], 0, s[8:9]
	global_load_dword v212, v[116:117], off nt
	v_lshl_add_u64 v[116:117], v[116:117], 0, s[8:9]
	global_load_dword v213, v[116:117], off nt
	v_lshl_add_u64 v[116:117], v[116:117], 0, s[8:9]
	global_load_dword v214, v[116:117], off nt
	v_lshl_add_u64 v[116:117], v[116:117], 0, s[8:9]
	global_load_dword v215, v[116:117], off nt
	v_lshl_add_u64 v[116:117], v[116:117], 0, s[8:9]
	global_load_dword v216, v[116:117], off nt
	v_lshl_add_u64 v[116:117], v[116:117], 0, s[8:9]
	global_load_dword v217, v[116:117], off nt
	v_lshl_add_u64 v[116:117], v[116:117], 0, s[8:9]
	global_load_dword v218, v[116:117], off nt
	v_lshl_add_u64 v[116:117], v[116:117], 0, s[8:9]
	global_load_dword v219, v[116:117], off nt
	v_lshl_add_u64 v[116:117], v[116:117], 0, s[8:9]
	global_load_dword v220, v[116:117], off nt
	v_lshl_add_u64 v[116:117], v[116:117], 0, s[8:9]
	global_load_dword v221, v[116:117], off nt
	v_lshl_add_u64 v[116:117], v[116:117], 0, s[8:9]
	global_load_dword v222, v[116:117], off nt
	v_lshl_add_u64 v[116:117], v[116:117], 0, s[8:9]
	global_load_dword v223, v[116:117], off nt
	v_lshl_add_u64 v[116:117], v[116:117], 0, s[8:9]
	global_load_dword v224, v[116:117], off nt
	v_lshl_add_u64 v[116:117], v[116:117], 0, s[8:9]
	global_load_dword v225, v[116:117], off nt
	v_lshl_add_u64 v[116:117], v[116:117], 0, s[8:9]
	v_mov_b32_e32 v110, 0
	v_mov_b32_e32 v111, 0
	v_mov_b32_e32 v112, 0
	s_waitcnt lgkmcnt(0)
	s_barrier
	ds_read_b128 v[146:149], v108 offset:0
	ds_read_b128 v[150:153], v108 offset:16
	ds_read_b128 v[154:157], v108 offset:32
	ds_read_b128 v[158:161], v108 offset:48
	ds_read_b128 v[162:165], v108 offset:4096
	ds_read_b128 v[166:169], v108 offset:4112
	ds_read_b128 v[170:173], v108 offset:4128
	ds_read_b128 v[174:177], v108 offset:4144
	ds_read_b128 v[178:181], v108 offset:8192
	ds_read_b128 v[182:185], v108 offset:8208
	ds_read_b128 v[186:189], v108 offset:8224
	ds_read_b128 v[190:193], v108 offset:8240
	s_waitcnt lgkmcnt(0)
	s_waitcnt vmcnt(31)
	v_fmac_f32_e32 v110, v194, v146
	v_fmac_f32_e32 v111, v194, v162
	v_fmac_f32_e32 v112, v194, v178
	global_load_dword v194, v[116:117], off nt
	v_lshl_add_u64 v[116:117], v[116:117], 0, s[8:9]
	s_waitcnt vmcnt(31)
	v_fmac_f32_e32 v110, v195, v147
	v_fmac_f32_e32 v111, v195, v163
	v_fmac_f32_e32 v112, v195, v179
	global_load_dword v195, v[116:117], off nt
	v_lshl_add_u64 v[116:117], v[116:117], 0, s[8:9]
	s_waitcnt vmcnt(31)
	v_fmac_f32_e32 v110, v196, v148
	v_fmac_f32_e32 v111, v196, v164
	v_fmac_f32_e32 v112, v196, v180
	global_load_dword v196, v[116:117], off nt
	v_lshl_add_u64 v[116:117], v[116:117], 0, s[8:9]
	s_waitcnt vmcnt(31)
	v_fmac_f32_e32 v110, v197, v149
	v_fmac_f32_e32 v111, v197, v165
	v_fmac_f32_e32 v112, v197, v181
	global_load_dword v197, v[116:117], off nt
	v_lshl_add_u64 v[116:117], v[116:117], 0, s[8:9]
	s_waitcnt vmcnt(31)
	v_fmac_f32_e32 v110, v198, v150
	v_fmac_f32_e32 v111, v198, v166
	v_fmac_f32_e32 v112, v198, v182
	global_load_dword v198, v[116:117], off nt
	v_lshl_add_u64 v[116:117], v[116:117], 0, s[8:9]
	s_waitcnt vmcnt(31)
	v_fmac_f32_e32 v110, v199, v151
	v_fmac_f32_e32 v111, v199, v167
	v_fmac_f32_e32 v112, v199, v183
	global_load_dword v199, v[116:117], off nt
	v_lshl_add_u64 v[116:117], v[116:117], 0, s[8:9]
	s_waitcnt vmcnt(31)
	v_fmac_f32_e32 v110, v200, v152
	v_fmac_f32_e32 v111, v200, v168
	v_fmac_f32_e32 v112, v200, v184
	global_load_dword v200, v[116:117], off nt
	v_lshl_add_u64 v[116:117], v[116:117], 0, s[8:9]
	s_waitcnt vmcnt(31)
	v_fmac_f32_e32 v110, v201, v153
	v_fmac_f32_e32 v111, v201, v169
	v_fmac_f32_e32 v112, v201, v185
	global_load_dword v201, v[116:117], off nt
	v_lshl_add_u64 v[116:117], v[116:117], 0, s[8:9]
	s_waitcnt vmcnt(31)
	v_fmac_f32_e32 v110, v202, v154
	v_fmac_f32_e32 v111, v202, v170
	v_fmac_f32_e32 v112, v202, v186
	global_load_dword v202, v[116:117], off nt
	v_lshl_add_u64 v[116:117], v[116:117], 0, s[8:9]
	s_waitcnt vmcnt(31)
	v_fmac_f32_e32 v110, v203, v155
	v_fmac_f32_e32 v111, v203, v171
	v_fmac_f32_e32 v112, v203, v187
	global_load_dword v203, v[116:117], off nt
	v_lshl_add_u64 v[116:117], v[116:117], 0, s[8:9]
	s_waitcnt vmcnt(31)
	v_fmac_f32_e32 v110, v204, v156
	v_fmac_f32_e32 v111, v204, v172
	v_fmac_f32_e32 v112, v204, v188
	global_load_dword v204, v[116:117], off nt
	v_lshl_add_u64 v[116:117], v[116:117], 0, s[8:9]
	s_waitcnt vmcnt(31)
	v_fmac_f32_e32 v110, v205, v157
	v_fmac_f32_e32 v111, v205, v173
	v_fmac_f32_e32 v112, v205, v189
	global_load_dword v205, v[116:117], off nt
	v_lshl_add_u64 v[116:117], v[116:117], 0, s[8:9]
	s_waitcnt vmcnt(31)
	v_fmac_f32_e32 v110, v206, v158
	v_fmac_f32_e32 v111, v206, v174
	v_fmac_f32_e32 v112, v206, v190
	global_load_dword v206, v[116:117], off nt
	v_lshl_add_u64 v[116:117], v[116:117], 0, s[8:9]
	s_waitcnt vmcnt(31)
	v_fmac_f32_e32 v110, v207, v159
	v_fmac_f32_e32 v111, v207, v175
	v_fmac_f32_e32 v112, v207, v191
	global_load_dword v207, v[116:117], off nt
	v_lshl_add_u64 v[116:117], v[116:117], 0, s[8:9]
	s_waitcnt vmcnt(31)
	v_fmac_f32_e32 v110, v208, v160
	v_fmac_f32_e32 v111, v208, v176
	v_fmac_f32_e32 v112, v208, v192
	global_load_dword v208, v[116:117], off nt
	v_lshl_add_u64 v[116:117], v[116:117], 0, s[8:9]
	s_waitcnt vmcnt(31)
	v_fmac_f32_e32 v110, v209, v161
	v_fmac_f32_e32 v111, v209, v177
	v_fmac_f32_e32 v112, v209, v193
	global_load_dword v209, v[116:117], off nt
	v_lshl_add_u64 v[116:117], v[116:117], 0, s[8:9]
	ds_read_b128 v[146:149], v108 offset:64
	ds_read_b128 v[150:153], v108 offset:80
	ds_read_b128 v[154:157], v108 offset:96
	ds_read_b128 v[158:161], v108 offset:112
	ds_read_b128 v[162:165], v108 offset:4160
	ds_read_b128 v[166:169], v108 offset:4176
	ds_read_b128 v[170:173], v108 offset:4192
	ds_read_b128 v[174:177], v108 offset:4208
	ds_read_b128 v[178:181], v108 offset:8256
	ds_read_b128 v[182:185], v108 offset:8272
	ds_read_b128 v[186:189], v108 offset:8288
	ds_read_b128 v[190:193], v108 offset:8304
	s_waitcnt lgkmcnt(0)
	s_waitcnt vmcnt(31)
	v_fmac_f32_e32 v110, v210, v146
	v_fmac_f32_e32 v111, v210, v162
	v_fmac_f32_e32 v112, v210, v178
	global_load_dword v210, v[116:117], off nt
	v_lshl_add_u64 v[116:117], v[116:117], 0, s[8:9]
	s_waitcnt vmcnt(31)
	v_fmac_f32_e32 v110, v211, v147
	v_fmac_f32_e32 v111, v211, v163
	v_fmac_f32_e32 v112, v211, v179
	global_load_dword v211, v[116:117], off nt
	v_lshl_add_u64 v[116:117], v[116:117], 0, s[8:9]
	s_waitcnt vmcnt(31)
	v_fmac_f32_e32 v110, v212, v148
	v_fmac_f32_e32 v111, v212, v164
	v_fmac_f32_e32 v112, v212, v180
	global_load_dword v212, v[116:117], off nt
	v_lshl_add_u64 v[116:117], v[116:117], 0, s[8:9]
	s_waitcnt vmcnt(31)
	v_fmac_f32_e32 v110, v213, v149
	v_fmac_f32_e32 v111, v213, v165
	v_fmac_f32_e32 v112, v213, v181
	global_load_dword v213, v[116:117], off nt
	v_lshl_add_u64 v[116:117], v[116:117], 0, s[8:9]
	s_waitcnt vmcnt(31)
	v_fmac_f32_e32 v110, v214, v150
	v_fmac_f32_e32 v111, v214, v166
	v_fmac_f32_e32 v112, v214, v182
	global_load_dword v214, v[116:117], off nt
	v_lshl_add_u64 v[116:117], v[116:117], 0, s[8:9]
	s_waitcnt vmcnt(31)
	v_fmac_f32_e32 v110, v215, v151
	v_fmac_f32_e32 v111, v215, v167
	v_fmac_f32_e32 v112, v215, v183
	global_load_dword v215, v[116:117], off nt
	v_lshl_add_u64 v[116:117], v[116:117], 0, s[8:9]
	s_waitcnt vmcnt(31)
	v_fmac_f32_e32 v110, v216, v152
	v_fmac_f32_e32 v111, v216, v168
	v_fmac_f32_e32 v112, v216, v184
	global_load_dword v216, v[116:117], off nt
	v_lshl_add_u64 v[116:117], v[116:117], 0, s[8:9]
	s_waitcnt vmcnt(31)
	v_fmac_f32_e32 v110, v217, v153
	v_fmac_f32_e32 v111, v217, v169
	v_fmac_f32_e32 v112, v217, v185
	global_load_dword v217, v[116:117], off nt
	v_lshl_add_u64 v[116:117], v[116:117], 0, s[8:9]
	s_waitcnt vmcnt(31)
	v_fmac_f32_e32 v110, v218, v154
	v_fmac_f32_e32 v111, v218, v170
	v_fmac_f32_e32 v112, v218, v186
	global_load_dword v218, v[116:117], off nt
	v_lshl_add_u64 v[116:117], v[116:117], 0, s[8:9]
	s_waitcnt vmcnt(31)
	v_fmac_f32_e32 v110, v219, v155
	v_fmac_f32_e32 v111, v219, v171
	v_fmac_f32_e32 v112, v219, v187
	global_load_dword v219, v[116:117], off nt
	v_lshl_add_u64 v[116:117], v[116:117], 0, s[8:9]
	s_waitcnt vmcnt(31)
	v_fmac_f32_e32 v110, v220, v156
	v_fmac_f32_e32 v111, v220, v172
	v_fmac_f32_e32 v112, v220, v188
	global_load_dword v220, v[116:117], off nt
	v_lshl_add_u64 v[116:117], v[116:117], 0, s[8:9]
	s_waitcnt vmcnt(31)
	v_fmac_f32_e32 v110, v221, v157
	v_fmac_f32_e32 v111, v221, v173
	v_fmac_f32_e32 v112, v221, v189
	global_load_dword v221, v[116:117], off nt
	v_lshl_add_u64 v[116:117], v[116:117], 0, s[8:9]
	s_waitcnt vmcnt(31)
	v_fmac_f32_e32 v110, v222, v158
	v_fmac_f32_e32 v111, v222, v174
	v_fmac_f32_e32 v112, v222, v190
	global_load_dword v222, v[116:117], off nt
	v_lshl_add_u64 v[116:117], v[116:117], 0, s[8:9]
	s_waitcnt vmcnt(31)
	v_fmac_f32_e32 v110, v223, v159
	v_fmac_f32_e32 v111, v223, v175
	v_fmac_f32_e32 v112, v223, v191
	global_load_dword v223, v[116:117], off nt
	v_lshl_add_u64 v[116:117], v[116:117], 0, s[8:9]
	s_waitcnt vmcnt(31)
	v_fmac_f32_e32 v110, v224, v160
	v_fmac_f32_e32 v111, v224, v176
	v_fmac_f32_e32 v112, v224, v192
	global_load_dword v224, v[116:117], off nt
	v_lshl_add_u64 v[116:117], v[116:117], 0, s[8:9]
	s_waitcnt vmcnt(31)
	v_fmac_f32_e32 v110, v225, v161
	v_fmac_f32_e32 v111, v225, v177
	v_fmac_f32_e32 v112, v225, v193
	global_load_dword v225, v[116:117], off nt
	v_lshl_add_u64 v[116:117], v[116:117], 0, s[8:9]
	ds_read_b128 v[146:149], v108 offset:128
	ds_read_b128 v[150:153], v108 offset:144
	ds_read_b128 v[154:157], v108 offset:160
	ds_read_b128 v[158:161], v108 offset:176
	ds_read_b128 v[162:165], v108 offset:4224
	ds_read_b128 v[166:169], v108 offset:4240
	ds_read_b128 v[170:173], v108 offset:4256
	ds_read_b128 v[174:177], v108 offset:4272
	ds_read_b128 v[178:181], v108 offset:8320
	ds_read_b128 v[182:185], v108 offset:8336
	ds_read_b128 v[186:189], v108 offset:8352
	ds_read_b128 v[190:193], v108 offset:8368
	s_waitcnt lgkmcnt(0)
	s_waitcnt vmcnt(31)
	v_fmac_f32_e32 v110, v194, v146
	v_fmac_f32_e32 v111, v194, v162
	v_fmac_f32_e32 v112, v194, v178
	global_load_dword v194, v[116:117], off nt
	v_lshl_add_u64 v[116:117], v[116:117], 0, s[8:9]
	s_waitcnt vmcnt(31)
	v_fmac_f32_e32 v110, v195, v147
	v_fmac_f32_e32 v111, v195, v163
	v_fmac_f32_e32 v112, v195, v179
	global_load_dword v195, v[116:117], off nt
	v_lshl_add_u64 v[116:117], v[116:117], 0, s[8:9]
	s_waitcnt vmcnt(31)
	v_fmac_f32_e32 v110, v196, v148
	v_fmac_f32_e32 v111, v196, v164
	v_fmac_f32_e32 v112, v196, v180
	global_load_dword v196, v[116:117], off nt
	v_lshl_add_u64 v[116:117], v[116:117], 0, s[8:9]
	s_waitcnt vmcnt(31)
	v_fmac_f32_e32 v110, v197, v149
	v_fmac_f32_e32 v111, v197, v165
	v_fmac_f32_e32 v112, v197, v181
	global_load_dword v197, v[116:117], off nt
	v_lshl_add_u64 v[116:117], v[116:117], 0, s[8:9]
	s_waitcnt vmcnt(31)
	v_fmac_f32_e32 v110, v198, v150
	v_fmac_f32_e32 v111, v198, v166
	v_fmac_f32_e32 v112, v198, v182
	global_load_dword v198, v[116:117], off nt
	v_lshl_add_u64 v[116:117], v[116:117], 0, s[8:9]
	s_waitcnt vmcnt(31)
	v_fmac_f32_e32 v110, v199, v151
	v_fmac_f32_e32 v111, v199, v167
	v_fmac_f32_e32 v112, v199, v183
	global_load_dword v199, v[116:117], off nt
	v_lshl_add_u64 v[116:117], v[116:117], 0, s[8:9]
	s_waitcnt vmcnt(31)
	v_fmac_f32_e32 v110, v200, v152
	v_fmac_f32_e32 v111, v200, v168
	v_fmac_f32_e32 v112, v200, v184
	global_load_dword v200, v[116:117], off nt
	v_lshl_add_u64 v[116:117], v[116:117], 0, s[8:9]
	s_waitcnt vmcnt(31)
	v_fmac_f32_e32 v110, v201, v153
	v_fmac_f32_e32 v111, v201, v169
	v_fmac_f32_e32 v112, v201, v185
	global_load_dword v201, v[116:117], off nt
	v_lshl_add_u64 v[116:117], v[116:117], 0, s[8:9]
	s_waitcnt vmcnt(31)
	v_fmac_f32_e32 v110, v202, v154
	v_fmac_f32_e32 v111, v202, v170
	v_fmac_f32_e32 v112, v202, v186
	global_load_dword v202, v[116:117], off nt
	v_lshl_add_u64 v[116:117], v[116:117], 0, s[8:9]
	s_waitcnt vmcnt(31)
	v_fmac_f32_e32 v110, v203, v155
	v_fmac_f32_e32 v111, v203, v171
	v_fmac_f32_e32 v112, v203, v187
	global_load_dword v203, v[116:117], off nt
	v_lshl_add_u64 v[116:117], v[116:117], 0, s[8:9]
	s_waitcnt vmcnt(31)
	v_fmac_f32_e32 v110, v204, v156
	v_fmac_f32_e32 v111, v204, v172
	v_fmac_f32_e32 v112, v204, v188
	global_load_dword v204, v[116:117], off nt
	v_lshl_add_u64 v[116:117], v[116:117], 0, s[8:9]
	s_waitcnt vmcnt(31)
	v_fmac_f32_e32 v110, v205, v157
	v_fmac_f32_e32 v111, v205, v173
	v_fmac_f32_e32 v112, v205, v189
	global_load_dword v205, v[116:117], off nt
	v_lshl_add_u64 v[116:117], v[116:117], 0, s[8:9]
	s_waitcnt vmcnt(31)
	v_fmac_f32_e32 v110, v206, v158
	v_fmac_f32_e32 v111, v206, v174
	v_fmac_f32_e32 v112, v206, v190
	global_load_dword v206, v[116:117], off nt
	v_lshl_add_u64 v[116:117], v[116:117], 0, s[8:9]
	s_waitcnt vmcnt(31)
	v_fmac_f32_e32 v110, v207, v159
	v_fmac_f32_e32 v111, v207, v175
	v_fmac_f32_e32 v112, v207, v191
	global_load_dword v207, v[116:117], off nt
	v_lshl_add_u64 v[116:117], v[116:117], 0, s[8:9]
	s_waitcnt vmcnt(31)
	v_fmac_f32_e32 v110, v208, v160
	v_fmac_f32_e32 v111, v208, v176
	v_fmac_f32_e32 v112, v208, v192
	global_load_dword v208, v[116:117], off nt
	v_lshl_add_u64 v[116:117], v[116:117], 0, s[8:9]
	s_waitcnt vmcnt(31)
	v_fmac_f32_e32 v110, v209, v161
	v_fmac_f32_e32 v111, v209, v177
	v_fmac_f32_e32 v112, v209, v193
	global_load_dword v209, v[116:117], off nt
	v_lshl_add_u64 v[116:117], v[116:117], 0, s[8:9]
	ds_read_b128 v[146:149], v108 offset:192
	ds_read_b128 v[150:153], v108 offset:208
	ds_read_b128 v[154:157], v108 offset:224
	ds_read_b128 v[158:161], v108 offset:240
	ds_read_b128 v[162:165], v108 offset:4288
	ds_read_b128 v[166:169], v108 offset:4304
	ds_read_b128 v[170:173], v108 offset:4320
	ds_read_b128 v[174:177], v108 offset:4336
	ds_read_b128 v[178:181], v108 offset:8384
	ds_read_b128 v[182:185], v108 offset:8400
	ds_read_b128 v[186:189], v108 offset:8416
	ds_read_b128 v[190:193], v108 offset:8432
	s_waitcnt lgkmcnt(0)
	s_waitcnt vmcnt(31)
	v_fmac_f32_e32 v110, v210, v146
	v_fmac_f32_e32 v111, v210, v162
	v_fmac_f32_e32 v112, v210, v178
	global_load_dword v210, v[116:117], off nt
	v_lshl_add_u64 v[116:117], v[116:117], 0, s[8:9]
	s_waitcnt vmcnt(31)
	v_fmac_f32_e32 v110, v211, v147
	v_fmac_f32_e32 v111, v211, v163
	v_fmac_f32_e32 v112, v211, v179
	global_load_dword v211, v[116:117], off nt
	v_lshl_add_u64 v[116:117], v[116:117], 0, s[8:9]
	s_waitcnt vmcnt(31)
	v_fmac_f32_e32 v110, v212, v148
	v_fmac_f32_e32 v111, v212, v164
	v_fmac_f32_e32 v112, v212, v180
	global_load_dword v212, v[116:117], off nt
	v_lshl_add_u64 v[116:117], v[116:117], 0, s[8:9]
	s_waitcnt vmcnt(31)
	v_fmac_f32_e32 v110, v213, v149
	v_fmac_f32_e32 v111, v213, v165
	v_fmac_f32_e32 v112, v213, v181
	global_load_dword v213, v[116:117], off nt
	v_lshl_add_u64 v[116:117], v[116:117], 0, s[8:9]
	s_waitcnt vmcnt(31)
	v_fmac_f32_e32 v110, v214, v150
	v_fmac_f32_e32 v111, v214, v166
	v_fmac_f32_e32 v112, v214, v182
	global_load_dword v214, v[116:117], off nt
	v_lshl_add_u64 v[116:117], v[116:117], 0, s[8:9]
	s_waitcnt vmcnt(31)
	v_fmac_f32_e32 v110, v215, v151
	v_fmac_f32_e32 v111, v215, v167
	v_fmac_f32_e32 v112, v215, v183
	global_load_dword v215, v[116:117], off nt
	v_lshl_add_u64 v[116:117], v[116:117], 0, s[8:9]
	s_waitcnt vmcnt(31)
	v_fmac_f32_e32 v110, v216, v152
	v_fmac_f32_e32 v111, v216, v168
	v_fmac_f32_e32 v112, v216, v184
	global_load_dword v216, v[116:117], off nt
	v_lshl_add_u64 v[116:117], v[116:117], 0, s[8:9]
	s_waitcnt vmcnt(31)
	v_fmac_f32_e32 v110, v217, v153
	v_fmac_f32_e32 v111, v217, v169
	v_fmac_f32_e32 v112, v217, v185
	global_load_dword v217, v[116:117], off nt
	v_lshl_add_u64 v[116:117], v[116:117], 0, s[8:9]
	s_waitcnt vmcnt(31)
	v_fmac_f32_e32 v110, v218, v154
	v_fmac_f32_e32 v111, v218, v170
	v_fmac_f32_e32 v112, v218, v186
	global_load_dword v218, v[116:117], off nt
	v_lshl_add_u64 v[116:117], v[116:117], 0, s[8:9]
	s_waitcnt vmcnt(31)
	v_fmac_f32_e32 v110, v219, v155
	v_fmac_f32_e32 v111, v219, v171
	v_fmac_f32_e32 v112, v219, v187
	global_load_dword v219, v[116:117], off nt
	v_lshl_add_u64 v[116:117], v[116:117], 0, s[8:9]
	s_waitcnt vmcnt(31)
	v_fmac_f32_e32 v110, v220, v156
	v_fmac_f32_e32 v111, v220, v172
	v_fmac_f32_e32 v112, v220, v188
	global_load_dword v220, v[116:117], off nt
	v_lshl_add_u64 v[116:117], v[116:117], 0, s[8:9]
	s_waitcnt vmcnt(31)
	v_fmac_f32_e32 v110, v221, v157
	v_fmac_f32_e32 v111, v221, v173
	v_fmac_f32_e32 v112, v221, v189
	global_load_dword v221, v[116:117], off nt
	v_lshl_add_u64 v[116:117], v[116:117], 0, s[8:9]
	s_waitcnt vmcnt(31)
	v_fmac_f32_e32 v110, v222, v158
	v_fmac_f32_e32 v111, v222, v174
	v_fmac_f32_e32 v112, v222, v190
	global_load_dword v222, v[116:117], off nt
	v_lshl_add_u64 v[116:117], v[116:117], 0, s[8:9]
	s_waitcnt vmcnt(31)
	v_fmac_f32_e32 v110, v223, v159
	v_fmac_f32_e32 v111, v223, v175
	v_fmac_f32_e32 v112, v223, v191
	global_load_dword v223, v[116:117], off nt
	v_lshl_add_u64 v[116:117], v[116:117], 0, s[8:9]
	s_waitcnt vmcnt(31)
	v_fmac_f32_e32 v110, v224, v160
	v_fmac_f32_e32 v111, v224, v176
	v_fmac_f32_e32 v112, v224, v192
	global_load_dword v224, v[116:117], off nt
	v_lshl_add_u64 v[116:117], v[116:117], 0, s[8:9]
	s_waitcnt vmcnt(31)
	v_fmac_f32_e32 v110, v225, v161
	v_fmac_f32_e32 v111, v225, v177
	v_fmac_f32_e32 v112, v225, v193
	global_load_dword v225, v[116:117], off nt
	v_lshl_add_u64 v[116:117], v[116:117], 0, s[8:9]
	ds_read_b128 v[146:149], v108 offset:256
	ds_read_b128 v[150:153], v108 offset:272
	ds_read_b128 v[154:157], v108 offset:288
	ds_read_b128 v[158:161], v108 offset:304
	ds_read_b128 v[162:165], v108 offset:4352
	ds_read_b128 v[166:169], v108 offset:4368
	ds_read_b128 v[170:173], v108 offset:4384
	ds_read_b128 v[174:177], v108 offset:4400
	ds_read_b128 v[178:181], v108 offset:8448
	ds_read_b128 v[182:185], v108 offset:8464
	ds_read_b128 v[186:189], v108 offset:8480
	ds_read_b128 v[190:193], v108 offset:8496
	s_waitcnt lgkmcnt(0)
	s_waitcnt vmcnt(31)
	v_fmac_f32_e32 v110, v194, v146
	v_fmac_f32_e32 v111, v194, v162
	v_fmac_f32_e32 v112, v194, v178
	global_load_dword v194, v[116:117], off nt
	v_lshl_add_u64 v[116:117], v[116:117], 0, s[8:9]
	s_waitcnt vmcnt(31)
	v_fmac_f32_e32 v110, v195, v147
	v_fmac_f32_e32 v111, v195, v163
	v_fmac_f32_e32 v112, v195, v179
	global_load_dword v195, v[116:117], off nt
	v_lshl_add_u64 v[116:117], v[116:117], 0, s[8:9]
	s_waitcnt vmcnt(31)
	v_fmac_f32_e32 v110, v196, v148
	v_fmac_f32_e32 v111, v196, v164
	v_fmac_f32_e32 v112, v196, v180
	global_load_dword v196, v[116:117], off nt
	v_lshl_add_u64 v[116:117], v[116:117], 0, s[8:9]
	s_waitcnt vmcnt(31)
	v_fmac_f32_e32 v110, v197, v149
	v_fmac_f32_e32 v111, v197, v165
	v_fmac_f32_e32 v112, v197, v181
	global_load_dword v197, v[116:117], off nt
	v_lshl_add_u64 v[116:117], v[116:117], 0, s[8:9]
	s_waitcnt vmcnt(31)
	v_fmac_f32_e32 v110, v198, v150
	v_fmac_f32_e32 v111, v198, v166
	v_fmac_f32_e32 v112, v198, v182
	global_load_dword v198, v[116:117], off nt
	v_lshl_add_u64 v[116:117], v[116:117], 0, s[8:9]
	s_waitcnt vmcnt(31)
	v_fmac_f32_e32 v110, v199, v151
	v_fmac_f32_e32 v111, v199, v167
	v_fmac_f32_e32 v112, v199, v183
	global_load_dword v199, v[116:117], off nt
	v_lshl_add_u64 v[116:117], v[116:117], 0, s[8:9]
	s_waitcnt vmcnt(31)
	v_fmac_f32_e32 v110, v200, v152
	v_fmac_f32_e32 v111, v200, v168
	v_fmac_f32_e32 v112, v200, v184
	global_load_dword v200, v[116:117], off nt
	v_lshl_add_u64 v[116:117], v[116:117], 0, s[8:9]
	s_waitcnt vmcnt(31)
	v_fmac_f32_e32 v110, v201, v153
	v_fmac_f32_e32 v111, v201, v169
	v_fmac_f32_e32 v112, v201, v185
	global_load_dword v201, v[116:117], off nt
	v_lshl_add_u64 v[116:117], v[116:117], 0, s[8:9]
	s_waitcnt vmcnt(31)
	v_fmac_f32_e32 v110, v202, v154
	v_fmac_f32_e32 v111, v202, v170
	v_fmac_f32_e32 v112, v202, v186
	global_load_dword v202, v[116:117], off nt
	v_lshl_add_u64 v[116:117], v[116:117], 0, s[8:9]
	s_waitcnt vmcnt(31)
	v_fmac_f32_e32 v110, v203, v155
	v_fmac_f32_e32 v111, v203, v171
	v_fmac_f32_e32 v112, v203, v187
	global_load_dword v203, v[116:117], off nt
	v_lshl_add_u64 v[116:117], v[116:117], 0, s[8:9]
	s_waitcnt vmcnt(31)
	v_fmac_f32_e32 v110, v204, v156
	v_fmac_f32_e32 v111, v204, v172
	v_fmac_f32_e32 v112, v204, v188
	global_load_dword v204, v[116:117], off nt
	v_lshl_add_u64 v[116:117], v[116:117], 0, s[8:9]
	s_waitcnt vmcnt(31)
	v_fmac_f32_e32 v110, v205, v157
	v_fmac_f32_e32 v111, v205, v173
	v_fmac_f32_e32 v112, v205, v189
	global_load_dword v205, v[116:117], off nt
	v_lshl_add_u64 v[116:117], v[116:117], 0, s[8:9]
	s_waitcnt vmcnt(31)
	v_fmac_f32_e32 v110, v206, v158
	v_fmac_f32_e32 v111, v206, v174
	v_fmac_f32_e32 v112, v206, v190
	global_load_dword v206, v[116:117], off nt
	v_lshl_add_u64 v[116:117], v[116:117], 0, s[8:9]
	s_waitcnt vmcnt(31)
	v_fmac_f32_e32 v110, v207, v159
	v_fmac_f32_e32 v111, v207, v175
	v_fmac_f32_e32 v112, v207, v191
	global_load_dword v207, v[116:117], off nt
	v_lshl_add_u64 v[116:117], v[116:117], 0, s[8:9]
	s_waitcnt vmcnt(31)
	v_fmac_f32_e32 v110, v208, v160
	v_fmac_f32_e32 v111, v208, v176
	v_fmac_f32_e32 v112, v208, v192
	global_load_dword v208, v[116:117], off nt
	v_lshl_add_u64 v[116:117], v[116:117], 0, s[8:9]
	s_waitcnt vmcnt(31)
	v_fmac_f32_e32 v110, v209, v161
	v_fmac_f32_e32 v111, v209, v177
	v_fmac_f32_e32 v112, v209, v193
	global_load_dword v209, v[116:117], off nt
	v_lshl_add_u64 v[116:117], v[116:117], 0, s[8:9]
	ds_read_b128 v[146:149], v108 offset:320
	ds_read_b128 v[150:153], v108 offset:336
	ds_read_b128 v[154:157], v108 offset:352
	ds_read_b128 v[158:161], v108 offset:368
	ds_read_b128 v[162:165], v108 offset:4416
	ds_read_b128 v[166:169], v108 offset:4432
	ds_read_b128 v[170:173], v108 offset:4448
	ds_read_b128 v[174:177], v108 offset:4464
	ds_read_b128 v[178:181], v108 offset:8512
	ds_read_b128 v[182:185], v108 offset:8528
	ds_read_b128 v[186:189], v108 offset:8544
	ds_read_b128 v[190:193], v108 offset:8560
	s_waitcnt lgkmcnt(0)
	s_waitcnt vmcnt(31)
	v_fmac_f32_e32 v110, v210, v146
	v_fmac_f32_e32 v111, v210, v162
	v_fmac_f32_e32 v112, v210, v178
	global_load_dword v210, v[116:117], off nt
	v_lshl_add_u64 v[116:117], v[116:117], 0, s[8:9]
	s_waitcnt vmcnt(31)
	v_fmac_f32_e32 v110, v211, v147
	v_fmac_f32_e32 v111, v211, v163
	v_fmac_f32_e32 v112, v211, v179
	global_load_dword v211, v[116:117], off nt
	v_lshl_add_u64 v[116:117], v[116:117], 0, s[8:9]
	s_waitcnt vmcnt(31)
	v_fmac_f32_e32 v110, v212, v148
	v_fmac_f32_e32 v111, v212, v164
	v_fmac_f32_e32 v112, v212, v180
	global_load_dword v212, v[116:117], off nt
	v_lshl_add_u64 v[116:117], v[116:117], 0, s[8:9]
	s_waitcnt vmcnt(31)
	v_fmac_f32_e32 v110, v213, v149
	v_fmac_f32_e32 v111, v213, v165
	v_fmac_f32_e32 v112, v213, v181
	global_load_dword v213, v[116:117], off nt
	v_lshl_add_u64 v[116:117], v[116:117], 0, s[8:9]
	s_waitcnt vmcnt(31)
	v_fmac_f32_e32 v110, v214, v150
	v_fmac_f32_e32 v111, v214, v166
	v_fmac_f32_e32 v112, v214, v182
	global_load_dword v214, v[116:117], off nt
	v_lshl_add_u64 v[116:117], v[116:117], 0, s[8:9]
	s_waitcnt vmcnt(31)
	v_fmac_f32_e32 v110, v215, v151
	v_fmac_f32_e32 v111, v215, v167
	v_fmac_f32_e32 v112, v215, v183
	global_load_dword v215, v[116:117], off nt
	v_lshl_add_u64 v[116:117], v[116:117], 0, s[8:9]
	s_waitcnt vmcnt(31)
	v_fmac_f32_e32 v110, v216, v152
	v_fmac_f32_e32 v111, v216, v168
	v_fmac_f32_e32 v112, v216, v184
	global_load_dword v216, v[116:117], off nt
	v_lshl_add_u64 v[116:117], v[116:117], 0, s[8:9]
	s_waitcnt vmcnt(31)
	v_fmac_f32_e32 v110, v217, v153
	v_fmac_f32_e32 v111, v217, v169
	v_fmac_f32_e32 v112, v217, v185
	global_load_dword v217, v[116:117], off nt
	v_lshl_add_u64 v[116:117], v[116:117], 0, s[8:9]
	s_waitcnt vmcnt(31)
	v_fmac_f32_e32 v110, v218, v154
	v_fmac_f32_e32 v111, v218, v170
	v_fmac_f32_e32 v112, v218, v186
	global_load_dword v218, v[116:117], off nt
	v_lshl_add_u64 v[116:117], v[116:117], 0, s[8:9]
	s_waitcnt vmcnt(31)
	v_fmac_f32_e32 v110, v219, v155
	v_fmac_f32_e32 v111, v219, v171
	v_fmac_f32_e32 v112, v219, v187
	global_load_dword v219, v[116:117], off nt
	v_lshl_add_u64 v[116:117], v[116:117], 0, s[8:9]
	s_waitcnt vmcnt(31)
	v_fmac_f32_e32 v110, v220, v156
	v_fmac_f32_e32 v111, v220, v172
	v_fmac_f32_e32 v112, v220, v188
	global_load_dword v220, v[116:117], off nt
	v_lshl_add_u64 v[116:117], v[116:117], 0, s[8:9]
	s_waitcnt vmcnt(31)
	v_fmac_f32_e32 v110, v221, v157
	v_fmac_f32_e32 v111, v221, v173
	v_fmac_f32_e32 v112, v221, v189
	global_load_dword v221, v[116:117], off nt
	v_lshl_add_u64 v[116:117], v[116:117], 0, s[8:9]
	s_waitcnt vmcnt(31)
	v_fmac_f32_e32 v110, v222, v158
	v_fmac_f32_e32 v111, v222, v174
	v_fmac_f32_e32 v112, v222, v190
	global_load_dword v222, v[116:117], off nt
	v_lshl_add_u64 v[116:117], v[116:117], 0, s[8:9]
	s_waitcnt vmcnt(31)
	v_fmac_f32_e32 v110, v223, v159
	v_fmac_f32_e32 v111, v223, v175
	v_fmac_f32_e32 v112, v223, v191
	global_load_dword v223, v[116:117], off nt
	v_lshl_add_u64 v[116:117], v[116:117], 0, s[8:9]
	s_waitcnt vmcnt(31)
	v_fmac_f32_e32 v110, v224, v160
	v_fmac_f32_e32 v111, v224, v176
	v_fmac_f32_e32 v112, v224, v192
	global_load_dword v224, v[116:117], off nt
	v_lshl_add_u64 v[116:117], v[116:117], 0, s[8:9]
	s_waitcnt vmcnt(31)
	v_fmac_f32_e32 v110, v225, v161
	v_fmac_f32_e32 v111, v225, v177
	v_fmac_f32_e32 v112, v225, v193
	global_load_dword v225, v[116:117], off nt
	v_lshl_add_u64 v[116:117], v[116:117], 0, s[8:9]
	ds_read_b128 v[146:149], v108 offset:384
	ds_read_b128 v[150:153], v108 offset:400
	ds_read_b128 v[154:157], v108 offset:416
	ds_read_b128 v[158:161], v108 offset:432
	ds_read_b128 v[162:165], v108 offset:4480
	ds_read_b128 v[166:169], v108 offset:4496
	ds_read_b128 v[170:173], v108 offset:4512
	ds_read_b128 v[174:177], v108 offset:4528
	ds_read_b128 v[178:181], v108 offset:8576
	ds_read_b128 v[182:185], v108 offset:8592
	ds_read_b128 v[186:189], v108 offset:8608
	ds_read_b128 v[190:193], v108 offset:8624
	s_waitcnt lgkmcnt(0)
	s_waitcnt vmcnt(31)
	v_fmac_f32_e32 v110, v194, v146
	v_fmac_f32_e32 v111, v194, v162
	v_fmac_f32_e32 v112, v194, v178
	s_waitcnt vmcnt(30)
	v_fmac_f32_e32 v110, v195, v147
	v_fmac_f32_e32 v111, v195, v163
	v_fmac_f32_e32 v112, v195, v179
	s_waitcnt vmcnt(29)
	v_fmac_f32_e32 v110, v196, v148
	v_fmac_f32_e32 v111, v196, v164
	v_fmac_f32_e32 v112, v196, v180
	s_waitcnt vmcnt(28)
	v_fmac_f32_e32 v110, v197, v149
	v_fmac_f32_e32 v111, v197, v165
	v_fmac_f32_e32 v112, v197, v181
	s_waitcnt vmcnt(27)
	v_fmac_f32_e32 v110, v198, v150
	v_fmac_f32_e32 v111, v198, v166
	v_fmac_f32_e32 v112, v198, v182
	s_waitcnt vmcnt(26)
	v_fmac_f32_e32 v110, v199, v151
	v_fmac_f32_e32 v111, v199, v167
	v_fmac_f32_e32 v112, v199, v183
	s_waitcnt vmcnt(25)
	v_fmac_f32_e32 v110, v200, v152
	v_fmac_f32_e32 v111, v200, v168
	v_fmac_f32_e32 v112, v200, v184
	s_waitcnt vmcnt(24)
	v_fmac_f32_e32 v110, v201, v153
	v_fmac_f32_e32 v111, v201, v169
	v_fmac_f32_e32 v112, v201, v185
	s_waitcnt vmcnt(23)
	v_fmac_f32_e32 v110, v202, v154
	v_fmac_f32_e32 v111, v202, v170
	v_fmac_f32_e32 v112, v202, v186
	s_waitcnt vmcnt(22)
	v_fmac_f32_e32 v110, v203, v155
	v_fmac_f32_e32 v111, v203, v171
	v_fmac_f32_e32 v112, v203, v187
	s_waitcnt vmcnt(21)
	v_fmac_f32_e32 v110, v204, v156
	v_fmac_f32_e32 v111, v204, v172
	v_fmac_f32_e32 v112, v204, v188
	s_waitcnt vmcnt(20)
	v_fmac_f32_e32 v110, v205, v157
	v_fmac_f32_e32 v111, v205, v173
	v_fmac_f32_e32 v112, v205, v189
	s_waitcnt vmcnt(19)
	v_fmac_f32_e32 v110, v206, v158
	v_fmac_f32_e32 v111, v206, v174
	v_fmac_f32_e32 v112, v206, v190
	s_waitcnt vmcnt(18)
	v_fmac_f32_e32 v110, v207, v159
	v_fmac_f32_e32 v111, v207, v175
	v_fmac_f32_e32 v112, v207, v191
	s_waitcnt vmcnt(17)
	v_fmac_f32_e32 v110, v208, v160
	v_fmac_f32_e32 v111, v208, v176
	v_fmac_f32_e32 v112, v208, v192
	s_waitcnt vmcnt(16)
	v_fmac_f32_e32 v110, v209, v161
	v_fmac_f32_e32 v111, v209, v177
	v_fmac_f32_e32 v112, v209, v193
	ds_read_b128 v[146:149], v108 offset:448
	ds_read_b128 v[150:153], v108 offset:464
	ds_read_b128 v[154:157], v108 offset:480
	ds_read_b128 v[158:161], v108 offset:496
	ds_read_b128 v[162:165], v108 offset:4544
	ds_read_b128 v[166:169], v108 offset:4560
	ds_read_b128 v[170:173], v108 offset:4576
	ds_read_b128 v[174:177], v108 offset:4592
	ds_read_b128 v[178:181], v108 offset:8640
	ds_read_b128 v[182:185], v108 offset:8656
	ds_read_b128 v[186:189], v108 offset:8672
	ds_read_b128 v[190:193], v108 offset:8688
	s_waitcnt lgkmcnt(0)
	s_waitcnt vmcnt(15)
	v_fmac_f32_e32 v110, v210, v146
	v_fmac_f32_e32 v111, v210, v162
	v_fmac_f32_e32 v112, v210, v178
	s_waitcnt vmcnt(14)
	v_fmac_f32_e32 v110, v211, v147
	v_fmac_f32_e32 v111, v211, v163
	v_fmac_f32_e32 v112, v211, v179
	s_waitcnt vmcnt(13)
	v_fmac_f32_e32 v110, v212, v148
	v_fmac_f32_e32 v111, v212, v164
	v_fmac_f32_e32 v112, v212, v180
	s_waitcnt vmcnt(12)
	v_fmac_f32_e32 v110, v213, v149
	v_fmac_f32_e32 v111, v213, v165
	v_fmac_f32_e32 v112, v213, v181
	s_waitcnt vmcnt(11)
	v_fmac_f32_e32 v110, v214, v150
	v_fmac_f32_e32 v111, v214, v166
	v_fmac_f32_e32 v112, v214, v182
	s_waitcnt vmcnt(10)
	v_fmac_f32_e32 v110, v215, v151
	v_fmac_f32_e32 v111, v215, v167
	v_fmac_f32_e32 v112, v215, v183
	s_waitcnt vmcnt(9)
	v_fmac_f32_e32 v110, v216, v152
	v_fmac_f32_e32 v111, v216, v168
	v_fmac_f32_e32 v112, v216, v184
	s_waitcnt vmcnt(8)
	v_fmac_f32_e32 v110, v217, v153
	v_fmac_f32_e32 v111, v217, v169
	v_fmac_f32_e32 v112, v217, v185
	s_waitcnt vmcnt(7)
	v_fmac_f32_e32 v110, v218, v154
	v_fmac_f32_e32 v111, v218, v170
	v_fmac_f32_e32 v112, v218, v186
	s_waitcnt vmcnt(6)
	v_fmac_f32_e32 v110, v219, v155
	v_fmac_f32_e32 v111, v219, v171
	v_fmac_f32_e32 v112, v219, v187
	s_waitcnt vmcnt(5)
	v_fmac_f32_e32 v110, v220, v156
	v_fmac_f32_e32 v111, v220, v172
	v_fmac_f32_e32 v112, v220, v188
	s_waitcnt vmcnt(4)
	v_fmac_f32_e32 v110, v221, v157
	v_fmac_f32_e32 v111, v221, v173
	v_fmac_f32_e32 v112, v221, v189
	s_waitcnt vmcnt(3)
	v_fmac_f32_e32 v110, v222, v158
	v_fmac_f32_e32 v111, v222, v174
	v_fmac_f32_e32 v112, v222, v190
	s_waitcnt vmcnt(2)
	v_fmac_f32_e32 v110, v223, v159
	v_fmac_f32_e32 v111, v223, v175
	v_fmac_f32_e32 v112, v223, v191
	s_waitcnt vmcnt(1)
	v_fmac_f32_e32 v110, v224, v160
	v_fmac_f32_e32 v111, v224, v176
	v_fmac_f32_e32 v112, v224, v192
	s_waitcnt vmcnt(0)
	v_fmac_f32_e32 v110, v225, v161
	v_fmac_f32_e32 v111, v225, v177
	v_fmac_f32_e32 v112, v225, v193
	v_mul_u32_u24_e32 v109, 0x180, v113
	v_lshl_add_u32 v109, v114, 2, v109
	ds_write_b32 v109, v110 offset:12288
	ds_write_b32 v109, v111 offset:12416
	ds_write_b32 v109, v112 offset:12544
	s_waitcnt lgkmcnt(0)
	s_barrier
	v_cmp_gt_u32_e32 vcc, 0x60, v137
	s_and_saveexec_b64 s[14:15], vcc
	s_cbranch_execz .Lgvm0_skip
	s_lshl_b32 s16, s100, 7
	s_add_u32 s16, s16, 0x6000
	v_lshl_add_u32 v102, v114, 2, s16
	global_load_dword v103, v102, s[26:27]
	v_lshlrev_b32_e32 v104, 7, v113
	v_lshl_add_u32 v104, v114, 2, v104
	ds_read_b32 v146, v104 offset:12288
	ds_read_b32 v147, v104 offset:12672
	ds_read_b32 v148, v104 offset:13056
	ds_read_b32 v149, v104 offset:13440
	ds_read_b32 v150, v104 offset:13824
	ds_read_b32 v151, v104 offset:14208
	ds_read_b32 v152, v104 offset:14592
	ds_read_b32 v153, v104 offset:14976
	v_mul_u32_u24_e32 v105, 0x6000, v113
	v_add_u32_e32 v105, v105, v102
	s_add_u32 s12, s12, 0x2f9c000
	s_addc_u32 s13, s13, 0
	s_waitcnt vmcnt(0) lgkmcnt(0)
	v_add_f32_e32 v103, v103, v146
	v_add_f32_e32 v103, v103, v147
	v_add_f32_e32 v103, v103, v148
	v_add_f32_e32 v103, v103, v149
	v_add_f32_e32 v103, v103, v150
	v_add_f32_e32 v103, v103, v151
	v_add_f32_e32 v103, v103, v152
	v_add_f32_e32 v103, v103, v153
	global_store_dword v105, v103, s[12:13]
.Lgvm0_skip:
	s_or_b64 exec, exec, s[14:15]
	s_waitcnt vmcnt(0) lgkmcnt(0)
	s_barrier
	s_add_u32 s100, s100, 96
	s_cmpk_lt_u32 s100, 0xc0
	s_cbranch_scc1 .Lgvm_loop
